# GEMM K-loops: last 8 MFMAs of each 32-MFMA compute segment sunk below the trailing s_barrier (early barrier arrival); main MFMAs prio 2, tail prio 3; mid-segment setprio flip removed
# baseline (speedup 1.0000x reference)
; #define PG8_STAGE(bufoff, gbase, voff) do { _Pragma("unroll") for (int _i = 0; _i < 2; ++_i) \
;         __builtin_amdgcn_global_load_lds((const unsigned*)((const char*)(gbase) + (voff)[_i]), (PG8_LAS unsigned*)(lds + (bufoff) + ldsw + _i * 8192), 16, 0, 0); } while (0)
; #define PG8_LDA(dst, b, h) do { _Pragma("unroll") for (int m = 0; m < 4; ++m) _Pragma("unroll") for (int k = 0; k < 2; ++k) dst[m][k] = *(const PG8_LAS bf16x8*)(lds + PG8_SA(b, h) + aoff + m * 2048 + k * 1024); } while (0)
; #define PG8_LDB(dst, b, h) do { _Pragma("unroll") for (int n = 0; n < 2; ++n) _Pragma("unroll") for (int k = 0; k < 2; ++k) dst[n][k] = *(const PG8_LAS bf16x8*)(lds + PG8_SB(b, h) + boff + n * 2048 + k * 1024); } while (0)
; #define PG8_MMA(ai, bj, At, Bt) do { __builtin_amdgcn_s_setprio(3); _Pragma("unroll") for (int m = 0; m < 4; ++m) _Pragma("unroll") for (int n = 0; n < 2; ++n) _Pragma("unroll") for (int k = 0; k < 2; ++k) \
;         acc[ai][bj][m][n] = __builtin_amdgcn_mfma_f32_16x16x32_bf16(Bt[n][k], At[m][k], acc[ai][bj][m][n], 0, 0, 0); __builtin_amdgcn_s_setprio(0); } while (0)
; #define PG8_WAIT_V(n) asm volatile("s_waitcnt vmcnt(" #n ")" ::: "memory")
; template <class Epi, class Sched, bool ALIGN_EPI = false, bool SP2 = false>
; __device__ __forceinline__ void gemm_phase(PG8_LAS unsigned char* lds, const Gemm g, const Sched& S, const Epi& E) {
;     ...
;             PG8_LDB(B0, 0, 0); PG8_LDB(B1, 0, 1); PG8_SCHED; PG8_LDA(At, 0, 0); PG8_STAGE(PG8_SA(1, 1), a1 + hstepA, voffA);
;             PG8_WAIT_V(8); PG8_WAIT_L(0); PG8_BAR; PG8_MMA(0, 0, At, B0); PG8_MMA(0, 1, At, B1); PG8_BAR; PG8_SCHED;
;             PG8_LDA(At, 0, 1); PG8_STAGE(PG8_SB(0, 0), b2, voffB); PG8_STAGE(PG8_SB(0, 1), b2 + hstepB, voffB); PG8_STAGE(PG8_SA(0, 0), a2, voffA);
;             PG8_WAIT_V(8); PG8_WAIT_L(0); PG8_BAR; PG8_MMA(1, 0, At, B0); PG8_MMA(1, 1, At, B1); PG8_BAR; PG8_SCHED;
;             PG8_LDB(B0, 1, 0); PG8_LDB(B1, 1, 1); PG8_SCHED; PG8_LDA(At, 1, 0); PG8_STAGE(PG8_SA(0, 1), a2 + hstepA, voffA);
;             PG8_WAIT_V(8); PG8_WAIT_L(0); PG8_BAR; PG8_MMA(0, 0, At, B0); PG8_MMA(0, 1, At, B1); PG8_BAR; PG8_SCHED;
;             PG8_LDA(At, 1, 1); PG8_STAGE(PG8_SB(1, 0), b3, voffB); PG8_STAGE(PG8_SB(1, 1), b3 + hstepB, voffB); PG8_STAGE(PG8_SA(1, 0), a3, voffA);
;             PG8_WAIT_V(8); PG8_WAIT_L(0); PG8_BAR; PG8_MMA(1, 0, At, B0); PG8_MMA(1, 1, At, B1); PG8_BAR; PG8_SCHED;
.LBB0_143:
	ds_read_b128 v[130:133], v167
	ds_read_b128 v[134:137], v167 offset:1024
	ds_read_b128 v[156:159], v167 offset:2048
	ds_read_b128 v[172:175], v167 offset:3072
	ds_read_b128 v[176:179], v168
	ds_read_b128 v[180:183], v168 offset:1024
	ds_read_b128 v[184:187], v168 offset:2048
	ds_read_b128 v[188:191], v168 offset:3072
	s_add_u32 s8, s6, 0xfff00080
	s_addc_u32 s9, s7, -1
	s_cmp_eq_u32 s45, 60
	s_cselect_b32 s37, s1, s9
	s_cselect_b32 s36, s14, s8
	s_cselect_b32 s9, s25, s44
	s_cselect_b32 s8, s27, s33
	v_lshl_add_u64 v[160:161], s[6:7], 0, v[148:149]
	s_add_i32 m0, s55, 0xc000
	ds_read_b128 v[192:195], v169
	ds_read_b128 v[196:199], v169 offset:1024
	ds_read_b128 v[200:203], v169 offset:2048
	ds_read_b128 v[204:207], v169 offset:3072
	ds_read_b128 v[208:211], v169 offset:4096
	ds_read_b128 v[212:215], v169 offset:5120
	ds_read_b128 v[216:219], v169 offset:6144
	ds_read_b128 v[220:223], v169 offset:7168
	global_load_lds_dwordx4 v[160:161], off
	v_lshl_add_u64 v[160:161], s[6:7], 0, v[150:151]
	s_add_i32 m0, s55, 0xe000
	s_nop 0
	global_load_lds_dwordx4 v[160:161], off
	s_waitcnt vmcnt(8)
	s_waitcnt lgkmcnt(0)
	s_barrier
	s_setprio 2
	s_waitcnt lgkmcnt(0)
	v_mfma_f32_16x16x32_bf16 v[126:129], v[130:133], v[192:195], v[126:129]
	v_mfma_f32_16x16x32_bf16 v[118:121], v[156:159], v[192:195], v[118:121]
	v_mfma_f32_16x16x32_bf16 v[110:113], v[130:133], v[200:203], v[110:113]
	v_mfma_f32_16x16x32_bf16 v[102:105], v[156:159], v[200:203], v[102:105]
	v_mfma_f32_16x16x32_bf16 v[94:97], v[130:133], v[208:211], v[94:97]
	v_mfma_f32_16x16x32_bf16 v[86:89], v[156:159], v[208:211], v[86:89]
	v_mfma_f32_16x16x32_bf16 v[78:81], v[130:133], v[216:219], v[78:81]
	v_mfma_f32_16x16x32_bf16 v[70:73], v[156:159], v[216:219], v[70:73]
	v_mfma_f32_16x16x32_bf16 v[126:129], v[134:137], v[196:199], v[126:129]
	v_mfma_f32_16x16x32_bf16 v[118:121], v[172:175], v[196:199], v[118:121]
	v_mfma_f32_16x16x32_bf16 v[110:113], v[134:137], v[204:207], v[110:113]
	v_mfma_f32_16x16x32_bf16 v[102:105], v[172:175], v[204:207], v[102:105]
	v_mfma_f32_16x16x32_bf16 v[94:97], v[134:137], v[212:215], v[94:97]
	v_mfma_f32_16x16x32_bf16 v[86:89], v[172:175], v[212:215], v[86:89]
	v_mfma_f32_16x16x32_bf16 v[78:81], v[134:137], v[220:223], v[78:81]
	v_mfma_f32_16x16x32_bf16 v[70:73], v[172:175], v[220:223], v[70:73]
	v_mfma_f32_16x16x32_bf16 v[122:125], v[176:179], v[192:195], v[122:125]
	v_mfma_f32_16x16x32_bf16 v[114:117], v[184:187], v[192:195], v[114:117]
	v_mfma_f32_16x16x32_bf16 v[106:109], v[176:179], v[200:203], v[106:109]
	v_mfma_f32_16x16x32_bf16 v[98:101], v[184:187], v[200:203], v[98:101]
	v_mfma_f32_16x16x32_bf16 v[90:93], v[176:179], v[208:211], v[90:93]
	v_mfma_f32_16x16x32_bf16 v[82:85], v[184:187], v[208:211], v[82:85]
	v_mfma_f32_16x16x32_bf16 v[74:77], v[176:179], v[216:219], v[74:77]
	v_mfma_f32_16x16x32_bf16 v[66:69], v[184:187], v[216:219], v[66:69]
	s_setprio 3
	s_barrier
	v_mfma_f32_16x16x32_bf16 v[122:125], v[180:183], v[196:199], v[122:125]
	v_mfma_f32_16x16x32_bf16 v[114:117], v[188:191], v[196:199], v[114:117]
	v_mfma_f32_16x16x32_bf16 v[106:109], v[180:183], v[204:207], v[106:109]
	v_mfma_f32_16x16x32_bf16 v[98:101], v[188:191], v[204:207], v[98:101]
	v_mfma_f32_16x16x32_bf16 v[90:93], v[180:183], v[212:215], v[90:93]
	v_mfma_f32_16x16x32_bf16 v[82:85], v[188:191], v[212:215], v[82:85]
	v_mfma_f32_16x16x32_bf16 v[74:77], v[180:183], v[220:223], v[74:77]
	v_mfma_f32_16x16x32_bf16 v[66:69], v[188:191], v[220:223], v[66:69]
	s_setprio 0
	s_add_i32 s56, s83, s66
	v_lshl_add_u64 v[160:161], s[8:9], 0, v[140:141]
	s_mov_b32 m0, s56
	ds_read_b128 v[192:195], v169 offset:16384
	ds_read_b128 v[196:199], v169 offset:17408
	ds_read_b128 v[200:203], v169 offset:18432
	ds_read_b128 v[204:207], v169 offset:19456
	ds_read_b128 v[208:211], v169 offset:20480
	ds_read_b128 v[212:215], v169 offset:21504
	ds_read_b128 v[216:219], v169 offset:22528
	ds_read_b128 v[220:223], v169 offset:23552
	global_load_lds_dwordx4 v[160:161], off
	s_add_i32 m0, s56, 0x2000
	s_add_u32 s56, s8, 0x100000
	v_lshl_add_u64 v[224:225], s[8:9], 0, v[144:145]
	s_addc_u32 s57, s9, 0
	s_add_i32 s58, s89, s66
	global_load_lds_dwordx4 v[224:225], off
	v_lshl_add_u64 v[226:227], s[56:57], 0, v[140:141]
	s_mov_b32 m0, s58
	v_lshl_add_u64 v[228:229], s[36:37], 0, v[142:143]
	global_load_lds_dwordx4 v[226:227], off
	v_lshl_add_u64 v[226:227], s[56:57], 0, v[144:145]
	s_add_i32 m0, s58, 0x2000
	s_nop 0
	global_load_lds_dwordx4 v[226:227], off
	v_lshl_add_u64 v[226:227], s[36:37], 0, v[138:139]
	s_mov_b32 m0, s55
	s_nop 0
	global_load_lds_dwordx4 v[226:227], off
	s_mov_b32 m0, s67
	s_nop 0
	global_load_lds_dwordx4 v[228:229], off
	s_waitcnt vmcnt(8)
	s_waitcnt lgkmcnt(0)
	s_barrier
	s_setprio 2
	s_waitcnt lgkmcnt(0)
	v_mfma_f32_16x16x32_bf16 v[62:65], v[130:133], v[192:195], v[62:65]
	v_mfma_f32_16x16x32_bf16 v[54:57], v[156:159], v[192:195], v[54:57]
	v_mfma_f32_16x16x32_bf16 v[46:49], v[130:133], v[200:203], v[46:49]
	v_mfma_f32_16x16x32_bf16 v[38:41], v[156:159], v[200:203], v[38:41]
	v_mfma_f32_16x16x32_bf16 v[30:33], v[130:133], v[208:211], v[30:33]
	v_mfma_f32_16x16x32_bf16 v[22:25], v[156:159], v[208:211], v[22:25]
	v_mfma_f32_16x16x32_bf16 v[14:17], v[130:133], v[216:219], v[14:17]
	v_mfma_f32_16x16x32_bf16 v[6:9], v[156:159], v[216:219], v[6:9]
	v_mfma_f32_16x16x32_bf16 v[62:65], v[134:137], v[196:199], v[62:65]
	v_mfma_f32_16x16x32_bf16 v[54:57], v[172:175], v[196:199], v[54:57]
	v_mfma_f32_16x16x32_bf16 v[46:49], v[134:137], v[204:207], v[46:49]
	v_mfma_f32_16x16x32_bf16 v[38:41], v[172:175], v[204:207], v[38:41]
	v_mfma_f32_16x16x32_bf16 v[30:33], v[134:137], v[212:215], v[30:33]
	v_mfma_f32_16x16x32_bf16 v[22:25], v[172:175], v[212:215], v[22:25]
	v_mfma_f32_16x16x32_bf16 v[14:17], v[134:137], v[220:223], v[14:17]
	v_mfma_f32_16x16x32_bf16 v[6:9], v[172:175], v[220:223], v[6:9]
	v_mfma_f32_16x16x32_bf16 v[58:61], v[176:179], v[192:195], v[58:61]
	v_mfma_f32_16x16x32_bf16 v[50:53], v[184:187], v[192:195], v[50:53]
	v_mfma_f32_16x16x32_bf16 v[42:45], v[176:179], v[200:203], v[42:45]
	v_mfma_f32_16x16x32_bf16 v[34:37], v[184:187], v[200:203], v[34:37]
	v_mfma_f32_16x16x32_bf16 v[26:29], v[176:179], v[208:211], v[26:29]
	v_mfma_f32_16x16x32_bf16 v[18:21], v[184:187], v[208:211], v[18:21]
	v_mfma_f32_16x16x32_bf16 v[10:13], v[176:179], v[216:219], v[10:13]
	v_mfma_f32_16x16x32_bf16 v[2:5], v[184:187], v[216:219], v[2:5]
	s_setprio 3
	s_barrier
; #define PG8_STAGE(bufoff, gbase, voff) do { _Pragma("unroll") for (int _i = 0; _i < 2; ++_i) \
;         __builtin_amdgcn_global_load_lds((const unsigned*)((const char*)(gbase) + (voff)[_i]), (PG8_LAS unsigned*)(lds + (bufoff) + ldsw + _i * 8192), 16, 0, 0); } while (0)
; #define PG8_LDA(dst, b, h) do { _Pragma("unroll") for (int m = 0; m < 4; ++m) _Pragma("unroll") for (int k = 0; k < 2; ++k) dst[m][k] = *(const PG8_LAS bf16x8*)(lds + PG8_SA(b, h) + aoff + m * 2048 + k * 1024); } while (0)
; #define PG8_LDB(dst, b, h) do { _Pragma("unroll") for (int n = 0; n < 2; ++n) _Pragma("unroll") for (int k = 0; k < 2; ++k) dst[n][k] = *(const PG8_LAS bf16x8*)(lds + PG8_SB(b, h) + boff + n * 2048 + k * 1024); } while (0)
; #define PG8_MMA(ai, bj, At, Bt) do { __builtin_amdgcn_s_setprio(3); _Pragma("unroll") for (int m = 0; m < 4; ++m) _Pragma("unroll") for (int n = 0; n < 2; ++n) _Pragma("unroll") for (int k = 0; k < 2; ++k) \
;         acc[ai][bj][m][n] = __builtin_amdgcn_mfma_f32_16x16x32_bf16(Bt[n][k], At[m][k], acc[ai][bj][m][n], 0, 0, 0); __builtin_amdgcn_s_setprio(0); } while (0)
; #define PG8_WAIT_V(n) asm volatile("s_waitcnt vmcnt(" #n ")" ::: "memory")
; template <class Epi, class Sched, bool ALIGN_EPI = false, bool SP2 = false>
; __device__ __forceinline__ void gemm_phase(PG8_LAS unsigned char* lds, const Gemm g, const Sched& S, const Epi& E) {
;     ...
;             PG8_LDB(B0, 0, 0); PG8_LDB(B1, 0, 1); PG8_SCHED; PG8_LDA(At, 0, 0); PG8_STAGE(PG8_SA(1, 1), a1 + hstepA, voffA);
;             PG8_WAIT_V(8); PG8_WAIT_L(0); PG8_BAR; PG8_MMA(0, 0, At, B0); PG8_MMA(0, 1, At, B1); PG8_BAR; PG8_SCHED;
;             PG8_LDA(At, 0, 1); PG8_STAGE(PG8_SB(0, 0), b2, voffB); PG8_STAGE(PG8_SB(0, 1), b2 + hstepB, voffB); PG8_STAGE(PG8_SA(0, 0), a2, voffA);
;             PG8_WAIT_V(8); PG8_WAIT_L(0); PG8_BAR; PG8_MMA(1, 0, At, B0); PG8_MMA(1, 1, At, B1); PG8_BAR; PG8_SCHED;
;             PG8_LDB(B0, 1, 0); PG8_LDB(B1, 1, 1); PG8_SCHED; PG8_LDA(At, 1, 0); PG8_STAGE(PG8_SA(0, 1), a2 + hstepA, voffA);
;             PG8_WAIT_V(8); PG8_WAIT_L(0); PG8_BAR; PG8_MMA(0, 0, At, B0); PG8_MMA(0, 1, At, B1); PG8_BAR; PG8_SCHED;
;             PG8_LDA(At, 1, 1); PG8_STAGE(PG8_SB(1, 0), b3, voffB); PG8_STAGE(PG8_SB(1, 1), b3 + hstepB, voffB); PG8_STAGE(PG8_SA(1, 0), a3, voffA);
;             PG8_WAIT_V(8); PG8_WAIT_L(0); PG8_BAR; PG8_MMA(1, 0, At, B0); PG8_MMA(1, 1, At, B1); PG8_BAR; PG8_SCHED;
	v_mfma_f32_16x16x32_bf16 v[58:61], v[180:183], v[196:199], v[58:61]
	v_mfma_f32_16x16x32_bf16 v[50:53], v[188:191], v[196:199], v[50:53]
	v_mfma_f32_16x16x32_bf16 v[42:45], v[180:183], v[204:207], v[42:45]
	v_mfma_f32_16x16x32_bf16 v[34:37], v[188:191], v[204:207], v[34:37]
	v_mfma_f32_16x16x32_bf16 v[26:29], v[180:183], v[212:215], v[26:29]
	v_mfma_f32_16x16x32_bf16 v[18:21], v[188:191], v[212:215], v[18:21]
	v_mfma_f32_16x16x32_bf16 v[10:13], v[180:183], v[220:223], v[10:13]
	v_mfma_f32_16x16x32_bf16 v[2:5], v[188:191], v[220:223], v[2:5]
	s_setprio 0
	s_add_i32 s56, 0, 0x18000
	v_add_u32_e32 v146, s56, v164
	s_add_i32 s57, 0, 0x1c000
	ds_read_b128 v[130:133], v146
	ds_read_b128 v[134:137], v146 offset:1024
	ds_read_b128 v[156:159], v146 offset:2048
	ds_read_b128 v[172:175], v146 offset:3072
	v_add_u32_e32 v146, s57, v164
	ds_read_b128 v[176:179], v146
	ds_read_b128 v[180:183], v146 offset:1024
	ds_read_b128 v[184:187], v146 offset:2048
	ds_read_b128 v[188:191], v146 offset:3072
	s_add_u32 s36, s36, 0x100000
	s_addc_u32 s37, s37, 0
	s_mov_b32 m0, s72
	v_lshl_add_u64 v[230:231], s[36:37], 0, v[138:139]
	ds_read_b128 v[192:195], v169 offset:32768
	ds_read_b128 v[196:199], v169 offset:33792
	ds_read_b128 v[200:203], v169 offset:34816
	ds_read_b128 v[204:207], v169 offset:35840
	ds_read_b128 v[208:211], v169 offset:36864
	ds_read_b128 v[212:215], v169 offset:37888
	ds_read_b128 v[216:219], v169 offset:38912
	ds_read_b128 v[220:223], v169 offset:39936
	global_load_lds_dwordx4 v[230:231], off
	v_lshl_add_u64 v[230:231], s[36:37], 0, v[142:143]
	s_mov_b32 m0, s73
	s_nop 0
	global_load_lds_dwordx4 v[230:231], off
	s_waitcnt vmcnt(8)
	s_waitcnt lgkmcnt(0)
	s_barrier
	s_setprio 2
	s_waitcnt lgkmcnt(0)
	v_mfma_f32_16x16x32_bf16 v[126:129], v[130:133], v[192:195], v[126:129]
	v_mfma_f32_16x16x32_bf16 v[118:121], v[156:159], v[192:195], v[118:121]
	v_mfma_f32_16x16x32_bf16 v[110:113], v[130:133], v[200:203], v[110:113]
	v_mfma_f32_16x16x32_bf16 v[102:105], v[156:159], v[200:203], v[102:105]
	v_mfma_f32_16x16x32_bf16 v[94:97], v[130:133], v[208:211], v[94:97]
	v_mfma_f32_16x16x32_bf16 v[86:89], v[156:159], v[208:211], v[86:89]
	v_mfma_f32_16x16x32_bf16 v[78:81], v[130:133], v[216:219], v[78:81]
	v_mfma_f32_16x16x32_bf16 v[70:73], v[156:159], v[216:219], v[70:73]
	v_mfma_f32_16x16x32_bf16 v[126:129], v[134:137], v[196:199], v[126:129]
	v_mfma_f32_16x16x32_bf16 v[118:121], v[172:175], v[196:199], v[118:121]
	v_mfma_f32_16x16x32_bf16 v[110:113], v[134:137], v[204:207], v[110:113]
	v_mfma_f32_16x16x32_bf16 v[102:105], v[172:175], v[204:207], v[102:105]
	v_mfma_f32_16x16x32_bf16 v[94:97], v[134:137], v[212:215], v[94:97]
	v_mfma_f32_16x16x32_bf16 v[86:89], v[172:175], v[212:215], v[86:89]
	v_mfma_f32_16x16x32_bf16 v[78:81], v[134:137], v[220:223], v[78:81]
	v_mfma_f32_16x16x32_bf16 v[70:73], v[172:175], v[220:223], v[70:73]
	v_mfma_f32_16x16x32_bf16 v[122:125], v[176:179], v[192:195], v[122:125]
	v_mfma_f32_16x16x32_bf16 v[114:117], v[184:187], v[192:195], v[114:117]
	v_mfma_f32_16x16x32_bf16 v[106:109], v[176:179], v[200:203], v[106:109]
	v_mfma_f32_16x16x32_bf16 v[98:101], v[184:187], v[200:203], v[98:101]
	v_mfma_f32_16x16x32_bf16 v[90:93], v[176:179], v[208:211], v[90:93]
	v_mfma_f32_16x16x32_bf16 v[82:85], v[184:187], v[208:211], v[82:85]
	v_mfma_f32_16x16x32_bf16 v[74:77], v[176:179], v[216:219], v[74:77]
	v_mfma_f32_16x16x32_bf16 v[66:69], v[184:187], v[216:219], v[66:69]
	s_setprio 3
	s_barrier
; #define PG8_STAGE(bufoff, gbase, voff) do { _Pragma("unroll") for (int _i = 0; _i < 2; ++_i) \
;         __builtin_amdgcn_global_load_lds((const unsigned*)((const char*)(gbase) + (voff)[_i]), (PG8_LAS unsigned*)(lds + (bufoff) + ldsw + _i * 8192), 16, 0, 0); } while (0)
; #define PG8_LDA(dst, b, h) do { _Pragma("unroll") for (int m = 0; m < 4; ++m) _Pragma("unroll") for (int k = 0; k < 2; ++k) dst[m][k] = *(const PG8_LAS bf16x8*)(lds + PG8_SA(b, h) + aoff + m * 2048 + k * 1024); } while (0)
; #define PG8_LDB(dst, b, h) do { _Pragma("unroll") for (int n = 0; n < 2; ++n) _Pragma("unroll") for (int k = 0; k < 2; ++k) dst[n][k] = *(const PG8_LAS bf16x8*)(lds + PG8_SB(b, h) + boff + n * 2048 + k * 1024); } while (0)
; #define PG8_MMA(ai, bj, At, Bt) do { __builtin_amdgcn_s_setprio(3); _Pragma("unroll") for (int m = 0; m < 4; ++m) _Pragma("unroll") for (int n = 0; n < 2; ++n) _Pragma("unroll") for (int k = 0; k < 2; ++k) \
;         acc[ai][bj][m][n] = __builtin_amdgcn_mfma_f32_16x16x32_bf16(Bt[n][k], At[m][k], acc[ai][bj][m][n], 0, 0, 0); __builtin_amdgcn_s_setprio(0); } while (0)
; #define PG8_WAIT_V(n) asm volatile("s_waitcnt vmcnt(" #n ")" ::: "memory")
; #define PG8_WAIT_L(n) asm volatile("s_waitcnt lgkmcnt(" #n ")" ::: "memory")
; #define PG8_BAR __builtin_amdgcn_s_barrier()
; #define PG8_SCHED __builtin_amdgcn_sched_barrier(0)
; template <class Epi, class Sched, bool ALIGN_EPI = false, bool SP2 = false>
; __device__ __forceinline__ void gemm_phase(PG8_LAS unsigned char* lds, const Gemm g, const Sched& S, const Epi& E) {
;     ...
;             PG8_LDB(B0, 1, 0); PG8_LDB(B1, 1, 1); PG8_SCHED; PG8_LDA(At, 1, 0); PG8_STAGE(PG8_SA(0, 1), a2 + hstepA, voffA);
;             PG8_WAIT_V(8); PG8_WAIT_L(0); PG8_BAR; PG8_MMA(0, 0, At, B0); PG8_MMA(0, 1, At, B1); PG8_BAR; PG8_SCHED;
;             PG8_LDA(At, 1, 1); PG8_STAGE(PG8_SB(1, 0), b3, voffB); PG8_STAGE(PG8_SB(1, 1), b3 + hstepB, voffB); PG8_STAGE(PG8_SA(1, 0), a3, voffA);
;             PG8_WAIT_V(8); PG8_WAIT_L(0); PG8_BAR; PG8_MMA(1, 0, At, B0); PG8_MMA(1, 1, At, B1); PG8_BAR; PG8_SCHED;
;     __device__ __forceinline__ void operator()(const f32x4 (&acc)[2][2][4][2], const Unit& u, int wr, int wc, int fr, int fq) const {
;         const int row0 = u.pm * BM + wr * 64 + fr; const int cls = u.pn >> 3;
;         if (u.pn >= 40) {
	v_mfma_f32_16x16x32_bf16 v[122:125], v[180:183], v[196:199], v[122:125]
	v_mfma_f32_16x16x32_bf16 v[114:117], v[188:191], v[196:199], v[114:117]
	v_mfma_f32_16x16x32_bf16 v[106:109], v[180:183], v[204:207], v[106:109]
	v_mfma_f32_16x16x32_bf16 v[98:101], v[188:191], v[204:207], v[98:101]
	v_mfma_f32_16x16x32_bf16 v[90:93], v[180:183], v[212:215], v[90:93]
	v_mfma_f32_16x16x32_bf16 v[82:85], v[188:191], v[212:215], v[82:85]
	v_mfma_f32_16x16x32_bf16 v[74:77], v[180:183], v[220:223], v[74:77]
	v_mfma_f32_16x16x32_bf16 v[66:69], v[188:191], v[220:223], v[66:69]
	s_setprio 0
	s_add_i32 s36, s56, s66
	v_lshl_add_u64 v[160:161], v[160:161], 0, s[18:19]
	s_mov_b32 m0, s36
	ds_read_b128 v[192:195], v169 offset:49152
	ds_read_b128 v[196:199], v169 offset:50176
	ds_read_b128 v[200:203], v169 offset:51200
	ds_read_b128 v[204:207], v169 offset:52224
	ds_read_b128 v[208:211], v169 offset:53248
	ds_read_b128 v[212:215], v169 offset:54272
	ds_read_b128 v[216:219], v169 offset:55296
	ds_read_b128 v[220:223], v169 offset:56320
	global_load_lds_dwordx4 v[160:161], off
	s_add_i32 m0, s36, 0x2000
	s_add_u32 s8, s8, 0x100080
	v_lshl_add_u64 v[160:161], v[224:225], 0, s[18:19]
	s_addc_u32 s9, s9, 0
	s_add_i32 s36, s57, s66
	global_load_lds_dwordx4 v[160:161], off
	v_lshl_add_u64 v[160:161], s[8:9], 0, v[140:141]
	s_mov_b32 m0, s36
	s_nop 0
	global_load_lds_dwordx4 v[160:161], off
	v_lshl_add_u64 v[160:161], s[8:9], 0, v[144:145]
	s_add_i32 m0, s36, 0x2000
	s_nop 0
	global_load_lds_dwordx4 v[160:161], off
	v_lshl_add_u64 v[160:161], v[226:227], 0, s[18:19]
	s_mov_b32 m0, s75
	s_nop 0
	global_load_lds_dwordx4 v[160:161], off
	v_lshl_add_u64 v[160:161], v[228:229], 0, s[18:19]
	s_mov_b32 m0, s76
	s_nop 0
	global_load_lds_dwordx4 v[160:161], off
	s_waitcnt vmcnt(8)
	s_waitcnt lgkmcnt(0)
	s_barrier
	s_setprio 2
	s_waitcnt lgkmcnt(0)
	v_mfma_f32_16x16x32_bf16 v[62:65], v[130:133], v[192:195], v[62:65]
	v_mfma_f32_16x16x32_bf16 v[54:57], v[156:159], v[192:195], v[54:57]
	v_mfma_f32_16x16x32_bf16 v[46:49], v[130:133], v[200:203], v[46:49]
	v_mfma_f32_16x16x32_bf16 v[38:41], v[156:159], v[200:203], v[38:41]
	v_mfma_f32_16x16x32_bf16 v[30:33], v[130:133], v[208:211], v[30:33]
	v_mfma_f32_16x16x32_bf16 v[22:25], v[156:159], v[208:211], v[22:25]
	v_mfma_f32_16x16x32_bf16 v[14:17], v[130:133], v[216:219], v[14:17]
	v_mfma_f32_16x16x32_bf16 v[6:9], v[156:159], v[216:219], v[6:9]
	v_mfma_f32_16x16x32_bf16 v[62:65], v[134:137], v[196:199], v[62:65]
	v_mfma_f32_16x16x32_bf16 v[54:57], v[172:175], v[196:199], v[54:57]
	v_mfma_f32_16x16x32_bf16 v[46:49], v[134:137], v[204:207], v[46:49]
	v_mfma_f32_16x16x32_bf16 v[38:41], v[172:175], v[204:207], v[38:41]
	v_mfma_f32_16x16x32_bf16 v[30:33], v[134:137], v[212:215], v[30:33]
	v_mfma_f32_16x16x32_bf16 v[22:25], v[172:175], v[212:215], v[22:25]
	v_mfma_f32_16x16x32_bf16 v[14:17], v[134:137], v[220:223], v[14:17]
	v_mfma_f32_16x16x32_bf16 v[6:9], v[172:175], v[220:223], v[6:9]
	v_mfma_f32_16x16x32_bf16 v[58:61], v[176:179], v[192:195], v[58:61]
	v_mfma_f32_16x16x32_bf16 v[50:53], v[184:187], v[192:195], v[50:53]
	v_mfma_f32_16x16x32_bf16 v[42:45], v[176:179], v[200:203], v[42:45]
	v_mfma_f32_16x16x32_bf16 v[34:37], v[184:187], v[200:203], v[34:37]
	v_mfma_f32_16x16x32_bf16 v[26:29], v[176:179], v[208:211], v[26:29]
	v_mfma_f32_16x16x32_bf16 v[18:21], v[184:187], v[208:211], v[18:21]
	v_mfma_f32_16x16x32_bf16 v[10:13], v[176:179], v[216:219], v[10:13]
	v_mfma_f32_16x16x32_bf16 v[2:5], v[184:187], v[216:219], v[2:5]
	s_setprio 3
	s_barrier
	v_mfma_f32_16x16x32_bf16 v[58:61], v[180:183], v[196:199], v[58:61]
	v_mfma_f32_16x16x32_bf16 v[50:53], v[188:191], v[196:199], v[50:53]
	v_mfma_f32_16x16x32_bf16 v[42:45], v[180:183], v[204:207], v[42:45]
	v_mfma_f32_16x16x32_bf16 v[34:37], v[188:191], v[204:207], v[34:37]
	v_mfma_f32_16x16x32_bf16 v[26:29], v[180:183], v[212:215], v[26:29]
	v_mfma_f32_16x16x32_bf16 v[18:21], v[188:191], v[212:215], v[18:21]
	v_mfma_f32_16x16x32_bf16 v[10:13], v[180:183], v[220:223], v[10:13]
	v_mfma_f32_16x16x32_bf16 v[2:5], v[188:191], v[220:223], v[2:5]
	s_setprio 0
	s_add_i32 s45, s45, 2
	s_add_u32 s6, s6, 0x100
	s_addc_u32 s7, s7, 0
	s_add_u32 s33, s33, 0x100
	s_addc_u32 s44, s44, 0
	s_cmp_gt_u32 s45, 61
	s_cbranch_scc0 .LBB0_143
	s_and_b64 vcc, exec, s[20:21]
	s_cbranch_vccz .LBB0_148
	s_barrier
	v_lshl_add_u32 v156, s0, 8, v163
	s_cmp_lt_i32 s54, 40
	s_mov_b64 s[0:1], -1
	s_cbranch_scc1 .LBB0_149

; #define PG8_STAGE(bufoff, gbase, voff) do { _Pragma("unroll") for (int _i = 0; _i < 2; ++_i) \
;         __builtin_amdgcn_global_load_lds((const unsigned*)((const char*)(gbase) + (voff)[_i]), (PG8_LAS unsigned*)(lds + (bufoff) + ldsw + _i * 8192), 16, 0, 0); } while (0)
; #define PG8_LDA(dst, b, h) do { _Pragma("unroll") for (int m = 0; m < 4; ++m) _Pragma("unroll") for (int k = 0; k < 2; ++k) dst[m][k] = *(const PG8_LAS bf16x8*)(lds + PG8_SA(b, h) + aoff + m * 2048 + k * 1024); } while (0)
; #define PG8_LDB(dst, b, h) do { _Pragma("unroll") for (int n = 0; n < 2; ++n) _Pragma("unroll") for (int k = 0; k < 2; ++k) dst[n][k] = *(const PG8_LAS bf16x8*)(lds + PG8_SB(b, h) + boff + n * 2048 + k * 1024); } while (0)
; #define PG8_MMA(ai, bj, At, Bt) do { __builtin_amdgcn_s_setprio(3); _Pragma("unroll") for (int m = 0; m < 4; ++m) _Pragma("unroll") for (int n = 0; n < 2; ++n) _Pragma("unroll") for (int k = 0; k < 2; ++k) \
;         acc[ai][bj][m][n] = __builtin_amdgcn_mfma_f32_16x16x32_bf16(Bt[n][k], At[m][k], acc[ai][bj][m][n], 0, 0, 0); __builtin_amdgcn_s_setprio(0); } while (0)
; #define PG8_WAIT_V(n) asm volatile("s_waitcnt vmcnt(" #n ")" ::: "memory")
; template <class Epi, class Sched, bool ALIGN_EPI = false, bool SP2 = false>
; __device__ __forceinline__ void gemm_phase(PG8_LAS unsigned char* lds, const Gemm g, const Sched& S, const Epi& E) {
;     ...
;             PG8_LDB(B0, 0, 0); PG8_LDB(B1, 0, 1); PG8_SCHED; PG8_LDA(At, 0, 0); PG8_STAGE(PG8_SA(1, 1), a1 + hstepA, voffA);
;             PG8_WAIT_V(8); PG8_WAIT_L(0); PG8_BAR; PG8_MMA(0, 0, At, B0); PG8_MMA(0, 1, At, B1); PG8_BAR; PG8_SCHED;
;             PG8_LDA(At, 0, 1); PG8_STAGE(PG8_SB(0, 0), b2, voffB); PG8_STAGE(PG8_SB(0, 1), b2 + hstepB, voffB); PG8_STAGE(PG8_SA(0, 0), a2, voffA);
;             PG8_WAIT_V(8); PG8_WAIT_L(0); PG8_BAR; PG8_MMA(1, 0, At, B0); PG8_MMA(1, 1, At, B1); PG8_BAR; PG8_SCHED;
;             PG8_LDB(B0, 1, 0); PG8_LDB(B1, 1, 1); PG8_SCHED; PG8_LDA(At, 1, 0); PG8_STAGE(PG8_SA(0, 1), a2 + hstepA, voffA);
;             PG8_WAIT_V(8); PG8_WAIT_L(0); PG8_BAR; PG8_MMA(0, 0, At, B0); PG8_MMA(0, 1, At, B1); PG8_BAR; PG8_SCHED;
;             PG8_LDA(At, 1, 1); PG8_STAGE(PG8_SB(1, 0), b3, voffB); PG8_STAGE(PG8_SB(1, 1), b3 + hstepB, voffB); PG8_STAGE(PG8_SA(1, 0), a3, voffA);
;             PG8_WAIT_V(8); PG8_WAIT_L(0); PG8_BAR; PG8_MMA(1, 0, At, B0); PG8_MMA(1, 1, At, B1); PG8_BAR; PG8_SCHED;
.LBB0_478:
	ds_read_b128 v[130:133], v170
	ds_read_b128 v[134:137], v170 offset:1024
	ds_read_b128 v[138:141], v170 offset:2048
	ds_read_b128 v[142:145], v170 offset:3072
	ds_read_b128 v[164:167], v171
	ds_read_b128 v[174:177], v171 offset:1024
	ds_read_b128 v[178:181], v171 offset:2048
	ds_read_b128 v[182:185], v171 offset:3072
	s_add_u32 s36, s6, 0xfff80080
	s_addc_u32 s37, s7, -1
	s_cmp_eq_u32 s79, 4
	s_cselect_b32 s59, s27, s37
	s_cselect_b32 s58, s26, s36
	s_cselect_b32 s37, s23, s78
	s_cselect_b32 s36, s25, s77
	v_lshl_add_u64 v[218:219], s[6:7], 0, v[154:155]
	s_add_i32 m0, s31, 0xc000
	ds_read_b128 v[186:189], v172
	ds_read_b128 v[190:193], v172 offset:1024
	ds_read_b128 v[194:197], v172 offset:2048
	ds_read_b128 v[198:201], v172 offset:3072
	ds_read_b128 v[202:205], v172 offset:4096
	ds_read_b128 v[206:209], v172 offset:5120
	ds_read_b128 v[210:213], v172 offset:6144
	ds_read_b128 v[214:217], v172 offset:7168
	global_load_lds_dwordx4 v[218:219], off
	v_lshl_add_u64 v[218:219], s[6:7], 0, v[156:157]
	s_add_i32 m0, s31, 0xe000
	s_nop 0
	global_load_lds_dwordx4 v[218:219], off
	s_waitcnt vmcnt(8)
	s_waitcnt lgkmcnt(0)
	s_barrier
	s_setprio 2
	s_waitcnt lgkmcnt(0)
	v_mfma_f32_16x16x32_bf16 v[126:129], v[130:133], v[186:189], v[126:129]
	v_mfma_f32_16x16x32_bf16 v[122:125], v[138:141], v[186:189], v[122:125]
	v_mfma_f32_16x16x32_bf16 v[118:121], v[130:133], v[194:197], v[118:121]
	v_mfma_f32_16x16x32_bf16 v[114:117], v[138:141], v[194:197], v[114:117]
	v_mfma_f32_16x16x32_bf16 v[110:113], v[130:133], v[202:205], v[110:113]
	v_mfma_f32_16x16x32_bf16 v[102:105], v[138:141], v[202:205], v[102:105]
	v_mfma_f32_16x16x32_bf16 v[78:81], v[130:133], v[210:213], v[78:81]
	v_mfma_f32_16x16x32_bf16 v[74:77], v[138:141], v[210:213], v[74:77]
	v_mfma_f32_16x16x32_bf16 v[126:129], v[134:137], v[190:193], v[126:129]
	v_mfma_f32_16x16x32_bf16 v[122:125], v[142:145], v[190:193], v[122:125]
	v_mfma_f32_16x16x32_bf16 v[118:121], v[134:137], v[198:201], v[118:121]
	v_mfma_f32_16x16x32_bf16 v[114:117], v[142:145], v[198:201], v[114:117]
	v_mfma_f32_16x16x32_bf16 v[110:113], v[134:137], v[206:209], v[110:113]
	v_mfma_f32_16x16x32_bf16 v[102:105], v[142:145], v[206:209], v[102:105]
	v_mfma_f32_16x16x32_bf16 v[78:81], v[134:137], v[214:217], v[78:81]
	v_mfma_f32_16x16x32_bf16 v[74:77], v[142:145], v[214:217], v[74:77]
	v_mfma_f32_16x16x32_bf16 v[106:109], v[164:167], v[186:189], v[106:109]
	v_mfma_f32_16x16x32_bf16 v[98:101], v[178:181], v[186:189], v[98:101]
	v_mfma_f32_16x16x32_bf16 v[94:97], v[164:167], v[194:197], v[94:97]
	v_mfma_f32_16x16x32_bf16 v[90:93], v[178:181], v[194:197], v[90:93]
	v_mfma_f32_16x16x32_bf16 v[86:89], v[164:167], v[202:205], v[86:89]
	v_mfma_f32_16x16x32_bf16 v[82:85], v[178:181], v[202:205], v[82:85]
	v_mfma_f32_16x16x32_bf16 v[70:73], v[164:167], v[210:213], v[70:73]
	v_mfma_f32_16x16x32_bf16 v[66:69], v[178:181], v[210:213], v[66:69]
	s_setprio 3
	s_barrier
	v_mfma_f32_16x16x32_bf16 v[106:109], v[174:177], v[190:193], v[106:109]
	v_mfma_f32_16x16x32_bf16 v[98:101], v[182:185], v[190:193], v[98:101]
	v_mfma_f32_16x16x32_bf16 v[94:97], v[174:177], v[198:201], v[94:97]
	v_mfma_f32_16x16x32_bf16 v[90:93], v[182:185], v[198:201], v[90:93]
	v_mfma_f32_16x16x32_bf16 v[86:89], v[174:177], v[206:209], v[86:89]
	v_mfma_f32_16x16x32_bf16 v[82:85], v[182:185], v[206:209], v[82:85]
	v_mfma_f32_16x16x32_bf16 v[70:73], v[174:177], v[214:217], v[70:73]
	v_mfma_f32_16x16x32_bf16 v[66:69], v[182:185], v[214:217], v[66:69]
	s_setprio 0
	s_add_i32 s83, s72, s44
	v_lshl_add_u64 v[218:219], s[36:37], 0, v[148:149]
	s_mov_b32 m0, s83
	ds_read_b128 v[186:189], v172 offset:16384
	ds_read_b128 v[190:193], v172 offset:17408
	ds_read_b128 v[194:197], v172 offset:18432
	ds_read_b128 v[198:201], v172 offset:19456
	ds_read_b128 v[202:205], v172 offset:20480
	ds_read_b128 v[206:209], v172 offset:21504
	ds_read_b128 v[210:213], v172 offset:22528
	ds_read_b128 v[214:217], v172 offset:23552
	global_load_lds_dwordx4 v[218:219], off
	s_add_i32 m0, s83, 0x2000
	s_add_u32 s84, s36, 0x20000
	v_lshl_add_u64 v[220:221], s[36:37], 0, v[152:153]
	s_addc_u32 s85, s37, 0
	s_add_i32 s83, s73, s44
	global_load_lds_dwordx4 v[220:221], off
	v_lshl_add_u64 v[222:223], s[84:85], 0, v[148:149]
	s_mov_b32 m0, s83
	v_lshl_add_u64 v[224:225], s[58:59], 0, v[150:151]
	global_load_lds_dwordx4 v[222:223], off
	v_lshl_add_u64 v[222:223], s[84:85], 0, v[152:153]
	s_add_i32 m0, s83, 0x2000
	s_nop 0
	global_load_lds_dwordx4 v[222:223], off
	v_lshl_add_u64 v[222:223], s[58:59], 0, v[146:147]
	s_mov_b32 m0, s31
	s_nop 0
	global_load_lds_dwordx4 v[222:223], off
	s_mov_b32 m0, s45
	s_nop 0
	global_load_lds_dwordx4 v[224:225], off
	s_waitcnt vmcnt(8)
	s_waitcnt lgkmcnt(0)
	s_barrier
	s_setprio 2
	s_waitcnt lgkmcnt(0)
	v_mfma_f32_16x16x32_bf16 v[62:65], v[130:133], v[186:189], v[62:65]
	v_mfma_f32_16x16x32_bf16 v[58:61], v[138:141], v[186:189], v[58:61]
	v_mfma_f32_16x16x32_bf16 v[54:57], v[130:133], v[194:197], v[54:57]
	v_mfma_f32_16x16x32_bf16 v[46:49], v[138:141], v[194:197], v[46:49]
	v_mfma_f32_16x16x32_bf16 v[38:41], v[130:133], v[202:205], v[38:41]
	v_mfma_f32_16x16x32_bf16 v[30:33], v[138:141], v[202:205], v[30:33]
	v_mfma_f32_16x16x32_bf16 v[22:25], v[130:133], v[210:213], v[22:25]
	v_mfma_f32_16x16x32_bf16 v[14:17], v[138:141], v[210:213], v[14:17]
	v_mfma_f32_16x16x32_bf16 v[62:65], v[134:137], v[190:193], v[62:65]
	v_mfma_f32_16x16x32_bf16 v[58:61], v[142:145], v[190:193], v[58:61]
	v_mfma_f32_16x16x32_bf16 v[54:57], v[134:137], v[198:201], v[54:57]
	v_mfma_f32_16x16x32_bf16 v[46:49], v[142:145], v[198:201], v[46:49]
	v_mfma_f32_16x16x32_bf16 v[38:41], v[134:137], v[206:209], v[38:41]
	v_mfma_f32_16x16x32_bf16 v[30:33], v[142:145], v[206:209], v[30:33]
	v_mfma_f32_16x16x32_bf16 v[22:25], v[134:137], v[214:217], v[22:25]
	v_mfma_f32_16x16x32_bf16 v[14:17], v[142:145], v[214:217], v[14:17]
	v_mfma_f32_16x16x32_bf16 v[50:53], v[164:167], v[186:189], v[50:53]
	v_mfma_f32_16x16x32_bf16 v[42:45], v[178:181], v[186:189], v[42:45]
	v_mfma_f32_16x16x32_bf16 v[34:37], v[164:167], v[194:197], v[34:37]
	v_mfma_f32_16x16x32_bf16 v[26:29], v[178:181], v[194:197], v[26:29]
	v_mfma_f32_16x16x32_bf16 v[18:21], v[164:167], v[202:205], v[18:21]
	v_mfma_f32_16x16x32_bf16 v[10:13], v[178:181], v[202:205], v[10:13]
	v_mfma_f32_16x16x32_bf16 v[6:9], v[164:167], v[210:213], v[6:9]
	v_mfma_f32_16x16x32_bf16 v[2:5], v[178:181], v[210:213], v[2:5]
	s_setprio 3
	s_barrier
; #define PG8_STAGE(bufoff, gbase, voff) do { _Pragma("unroll") for (int _i = 0; _i < 2; ++_i) \
;         __builtin_amdgcn_global_load_lds((const unsigned*)((const char*)(gbase) + (voff)[_i]), (PG8_LAS unsigned*)(lds + (bufoff) + ldsw + _i * 8192), 16, 0, 0); } while (0)
; #define PG8_LDA(dst, b, h) do { _Pragma("unroll") for (int m = 0; m < 4; ++m) _Pragma("unroll") for (int k = 0; k < 2; ++k) dst[m][k] = *(const PG8_LAS bf16x8*)(lds + PG8_SA(b, h) + aoff + m * 2048 + k * 1024); } while (0)
; #define PG8_LDB(dst, b, h) do { _Pragma("unroll") for (int n = 0; n < 2; ++n) _Pragma("unroll") for (int k = 0; k < 2; ++k) dst[n][k] = *(const PG8_LAS bf16x8*)(lds + PG8_SB(b, h) + boff + n * 2048 + k * 1024); } while (0)
; #define PG8_MMA(ai, bj, At, Bt) do { __builtin_amdgcn_s_setprio(3); _Pragma("unroll") for (int m = 0; m < 4; ++m) _Pragma("unroll") for (int n = 0; n < 2; ++n) _Pragma("unroll") for (int k = 0; k < 2; ++k) \
;         acc[ai][bj][m][n] = __builtin_amdgcn_mfma_f32_16x16x32_bf16(Bt[n][k], At[m][k], acc[ai][bj][m][n], 0, 0, 0); __builtin_amdgcn_s_setprio(0); } while (0)
; #define PG8_WAIT_V(n) asm volatile("s_waitcnt vmcnt(" #n ")" ::: "memory")
; template <class Epi, class Sched, bool ALIGN_EPI = false, bool SP2 = false>
; __device__ __forceinline__ void gemm_phase(PG8_LAS unsigned char* lds, const Gemm g, const Sched& S, const Epi& E) {
;     ...
;             PG8_LDB(B0, 0, 0); PG8_LDB(B1, 0, 1); PG8_SCHED; PG8_LDA(At, 0, 0); PG8_STAGE(PG8_SA(1, 1), a1 + hstepA, voffA);
;             PG8_WAIT_V(8); PG8_WAIT_L(0); PG8_BAR; PG8_MMA(0, 0, At, B0); PG8_MMA(0, 1, At, B1); PG8_BAR; PG8_SCHED;
;             PG8_LDA(At, 0, 1); PG8_STAGE(PG8_SB(0, 0), b2, voffB); PG8_STAGE(PG8_SB(0, 1), b2 + hstepB, voffB); PG8_STAGE(PG8_SA(0, 0), a2, voffA);
;             PG8_WAIT_V(8); PG8_WAIT_L(0); PG8_BAR; PG8_MMA(1, 0, At, B0); PG8_MMA(1, 1, At, B1); PG8_BAR; PG8_SCHED;
;             PG8_LDB(B0, 1, 0); PG8_LDB(B1, 1, 1); PG8_SCHED; PG8_LDA(At, 1, 0); PG8_STAGE(PG8_SA(0, 1), a2 + hstepA, voffA);
;             PG8_WAIT_V(8); PG8_WAIT_L(0); PG8_BAR; PG8_MMA(0, 0, At, B0); PG8_MMA(0, 1, At, B1); PG8_BAR; PG8_SCHED;
;             PG8_LDA(At, 1, 1); PG8_STAGE(PG8_SB(1, 0), b3, voffB); PG8_STAGE(PG8_SB(1, 1), b3 + hstepB, voffB); PG8_STAGE(PG8_SA(1, 0), a3, voffA);
;             PG8_WAIT_V(8); PG8_WAIT_L(0); PG8_BAR; PG8_MMA(1, 0, At, B0); PG8_MMA(1, 1, At, B1); PG8_BAR; PG8_SCHED;
	v_mfma_f32_16x16x32_bf16 v[50:53], v[174:177], v[190:193], v[50:53]
	v_mfma_f32_16x16x32_bf16 v[42:45], v[182:185], v[190:193], v[42:45]
	v_mfma_f32_16x16x32_bf16 v[34:37], v[174:177], v[198:201], v[34:37]
	v_mfma_f32_16x16x32_bf16 v[26:29], v[182:185], v[198:201], v[26:29]
	v_mfma_f32_16x16x32_bf16 v[18:21], v[174:177], v[206:209], v[18:21]
	v_mfma_f32_16x16x32_bf16 v[10:13], v[182:185], v[206:209], v[10:13]
	v_mfma_f32_16x16x32_bf16 v[6:9], v[174:177], v[214:217], v[6:9]
	v_mfma_f32_16x16x32_bf16 v[2:5], v[182:185], v[214:217], v[2:5]
	s_setprio 0
	s_add_i32 s83, 0, 0x18000
	s_add_i32 s84, 0, 0x1c000
	v_add_u32_e32 v142, s83, v168
	v_add_u32_e32 v173, s84, v168
	ds_read_b128 v[130:133], v142
	ds_read_b128 v[134:137], v142 offset:1024
	ds_read_b128 v[138:141], v142 offset:2048
	ds_read_b128 v[142:145], v142 offset:3072
	ds_read_b128 v[164:167], v173
	ds_read_b128 v[174:177], v173 offset:1024
	ds_read_b128 v[178:181], v173 offset:2048
	ds_read_b128 v[182:185], v173 offset:3072
	s_add_u32 s58, s58, 0x80000
	s_addc_u32 s59, s59, 0
	s_mov_b32 m0, s54
	v_lshl_add_u64 v[226:227], s[58:59], 0, v[146:147]
	ds_read_b128 v[186:189], v172 offset:32768
	ds_read_b128 v[190:193], v172 offset:33792
	ds_read_b128 v[194:197], v172 offset:34816
	ds_read_b128 v[198:201], v172 offset:35840
	ds_read_b128 v[202:205], v172 offset:36864
	ds_read_b128 v[206:209], v172 offset:37888
	ds_read_b128 v[210:213], v172 offset:38912
	ds_read_b128 v[214:217], v172 offset:39936
	global_load_lds_dwordx4 v[226:227], off
	v_lshl_add_u64 v[226:227], s[58:59], 0, v[150:151]
	s_mov_b32 m0, s55
	s_nop 0
	global_load_lds_dwordx4 v[226:227], off
	s_waitcnt vmcnt(8)
	s_waitcnt lgkmcnt(0)
	s_barrier
	s_setprio 2
	s_waitcnt lgkmcnt(0)
	v_mfma_f32_16x16x32_bf16 v[126:129], v[130:133], v[186:189], v[126:129]
	v_mfma_f32_16x16x32_bf16 v[122:125], v[138:141], v[186:189], v[122:125]
	v_mfma_f32_16x16x32_bf16 v[118:121], v[130:133], v[194:197], v[118:121]
	v_mfma_f32_16x16x32_bf16 v[114:117], v[138:141], v[194:197], v[114:117]
	v_mfma_f32_16x16x32_bf16 v[110:113], v[130:133], v[202:205], v[110:113]
	v_mfma_f32_16x16x32_bf16 v[102:105], v[138:141], v[202:205], v[102:105]
	v_mfma_f32_16x16x32_bf16 v[78:81], v[130:133], v[210:213], v[78:81]
	v_mfma_f32_16x16x32_bf16 v[74:77], v[138:141], v[210:213], v[74:77]
	v_mfma_f32_16x16x32_bf16 v[126:129], v[134:137], v[190:193], v[126:129]
	v_mfma_f32_16x16x32_bf16 v[122:125], v[142:145], v[190:193], v[122:125]
	v_mfma_f32_16x16x32_bf16 v[118:121], v[134:137], v[198:201], v[118:121]
	v_mfma_f32_16x16x32_bf16 v[114:117], v[142:145], v[198:201], v[114:117]
	v_mfma_f32_16x16x32_bf16 v[110:113], v[134:137], v[206:209], v[110:113]
	v_mfma_f32_16x16x32_bf16 v[102:105], v[142:145], v[206:209], v[102:105]
	v_mfma_f32_16x16x32_bf16 v[78:81], v[134:137], v[214:217], v[78:81]
	v_mfma_f32_16x16x32_bf16 v[74:77], v[142:145], v[214:217], v[74:77]
	v_mfma_f32_16x16x32_bf16 v[106:109], v[164:167], v[186:189], v[106:109]
	v_mfma_f32_16x16x32_bf16 v[98:101], v[178:181], v[186:189], v[98:101]
	v_mfma_f32_16x16x32_bf16 v[94:97], v[164:167], v[194:197], v[94:97]
	v_mfma_f32_16x16x32_bf16 v[90:93], v[178:181], v[194:197], v[90:93]
	v_mfma_f32_16x16x32_bf16 v[86:89], v[164:167], v[202:205], v[86:89]
	v_mfma_f32_16x16x32_bf16 v[82:85], v[178:181], v[202:205], v[82:85]
	v_mfma_f32_16x16x32_bf16 v[70:73], v[164:167], v[210:213], v[70:73]
	v_mfma_f32_16x16x32_bf16 v[66:69], v[178:181], v[210:213], v[66:69]
	s_setprio 3
	s_barrier
; #define PG8_STAGE(bufoff, gbase, voff) do { _Pragma("unroll") for (int _i = 0; _i < 2; ++_i) \
;         __builtin_amdgcn_global_load_lds((const unsigned*)((const char*)(gbase) + (voff)[_i]), (PG8_LAS unsigned*)(lds + (bufoff) + ldsw + _i * 8192), 16, 0, 0); } while (0)
; #define PG8_LDA(dst, b, h) do { _Pragma("unroll") for (int m = 0; m < 4; ++m) _Pragma("unroll") for (int k = 0; k < 2; ++k) dst[m][k] = *(const PG8_LAS bf16x8*)(lds + PG8_SA(b, h) + aoff + m * 2048 + k * 1024); } while (0)
; #define PG8_LDB(dst, b, h) do { _Pragma("unroll") for (int n = 0; n < 2; ++n) _Pragma("unroll") for (int k = 0; k < 2; ++k) dst[n][k] = *(const PG8_LAS bf16x8*)(lds + PG8_SB(b, h) + boff + n * 2048 + k * 1024); } while (0)
; #define PG8_MMA(ai, bj, At, Bt) do { __builtin_amdgcn_s_setprio(3); _Pragma("unroll") for (int m = 0; m < 4; ++m) _Pragma("unroll") for (int n = 0; n < 2; ++n) _Pragma("unroll") for (int k = 0; k < 2; ++k) \
;         acc[ai][bj][m][n] = __builtin_amdgcn_mfma_f32_16x16x32_bf16(Bt[n][k], At[m][k], acc[ai][bj][m][n], 0, 0, 0); __builtin_amdgcn_s_setprio(0); } while (0)
; #define PG8_WAIT_V(n) asm volatile("s_waitcnt vmcnt(" #n ")" ::: "memory")
; #define PG8_WAIT_L(n) asm volatile("s_waitcnt lgkmcnt(" #n ")" ::: "memory")
; #define PG8_BAR __builtin_amdgcn_s_barrier()
; #define PG8_SCHED __builtin_amdgcn_sched_barrier(0)
; template <class Epi, class Sched, bool ALIGN_EPI = false, bool SP2 = false>
; __device__ __forceinline__ void gemm_phase(PG8_LAS unsigned char* lds, const Gemm g, const Sched& S, const Epi& E) {
;     ...
;             PG8_LDB(B0, 1, 0); PG8_LDB(B1, 1, 1); PG8_SCHED; PG8_LDA(At, 1, 0); PG8_STAGE(PG8_SA(0, 1), a2 + hstepA, voffA);
;             PG8_WAIT_V(8); PG8_WAIT_L(0); PG8_BAR; PG8_MMA(0, 0, At, B0); PG8_MMA(0, 1, At, B1); PG8_BAR; PG8_SCHED;
;             PG8_LDA(At, 1, 1); PG8_STAGE(PG8_SB(1, 0), b3, voffB); PG8_STAGE(PG8_SB(1, 1), b3 + hstepB, voffB); PG8_STAGE(PG8_SA(1, 0), a3, voffA);
;             PG8_WAIT_V(8); PG8_WAIT_L(0); PG8_BAR; PG8_MMA(1, 0, At, B0); PG8_MMA(1, 1, At, B1); PG8_BAR; PG8_SCHED;
;     ...
;         if constexpr (ALIGN_EPI) { if (wr == 0) PG8_BAR; }
	v_mfma_f32_16x16x32_bf16 v[106:109], v[174:177], v[190:193], v[106:109]
	v_mfma_f32_16x16x32_bf16 v[98:101], v[182:185], v[190:193], v[98:101]
	v_mfma_f32_16x16x32_bf16 v[94:97], v[174:177], v[198:201], v[94:97]
	v_mfma_f32_16x16x32_bf16 v[90:93], v[182:185], v[198:201], v[90:93]
	v_mfma_f32_16x16x32_bf16 v[86:89], v[174:177], v[206:209], v[86:89]
	v_mfma_f32_16x16x32_bf16 v[82:85], v[182:185], v[206:209], v[82:85]
	v_mfma_f32_16x16x32_bf16 v[70:73], v[174:177], v[214:217], v[70:73]
	v_mfma_f32_16x16x32_bf16 v[66:69], v[182:185], v[214:217], v[66:69]
	s_setprio 0
	s_add_i32 s58, s83, s44
	v_lshl_add_u64 v[218:219], v[218:219], 0, s[18:19]
	s_mov_b32 m0, s58
	ds_read_b128 v[186:189], v172 offset:49152
	ds_read_b128 v[190:193], v172 offset:50176
	ds_read_b128 v[194:197], v172 offset:51200
	ds_read_b128 v[198:201], v172 offset:52224
	ds_read_b128 v[202:205], v172 offset:53248
	ds_read_b128 v[206:209], v172 offset:54272
	ds_read_b128 v[210:213], v172 offset:55296
	ds_read_b128 v[214:217], v172 offset:56320
	global_load_lds_dwordx4 v[218:219], off
	s_add_i32 m0, s58, 0x2000
	s_add_u32 s36, s36, 0x20080
	v_lshl_add_u64 v[218:219], v[220:221], 0, s[18:19]
	s_addc_u32 s37, s37, 0
	s_add_i32 s58, s84, s44
	global_load_lds_dwordx4 v[218:219], off
	v_lshl_add_u64 v[218:219], s[36:37], 0, v[148:149]
	s_mov_b32 m0, s58
	s_nop 0
	global_load_lds_dwordx4 v[218:219], off
	v_lshl_add_u64 v[218:219], s[36:37], 0, v[152:153]
	s_add_i32 m0, s58, 0x2000
	s_nop 0
	global_load_lds_dwordx4 v[218:219], off
	v_lshl_add_u64 v[218:219], v[222:223], 0, s[18:19]
	s_mov_b32 m0, s63
	s_nop 0
	global_load_lds_dwordx4 v[218:219], off
	v_lshl_add_u64 v[218:219], v[224:225], 0, s[18:19]
	s_mov_b32 m0, s66
	s_nop 0
	global_load_lds_dwordx4 v[218:219], off
	s_waitcnt vmcnt(8)
	s_waitcnt lgkmcnt(0)
	s_barrier
	s_setprio 2
	s_waitcnt lgkmcnt(0)
	v_mfma_f32_16x16x32_bf16 v[62:65], v[130:133], v[186:189], v[62:65]
	v_mfma_f32_16x16x32_bf16 v[58:61], v[138:141], v[186:189], v[58:61]
	v_mfma_f32_16x16x32_bf16 v[54:57], v[130:133], v[194:197], v[54:57]
	v_mfma_f32_16x16x32_bf16 v[46:49], v[138:141], v[194:197], v[46:49]
	v_mfma_f32_16x16x32_bf16 v[38:41], v[130:133], v[202:205], v[38:41]
	v_mfma_f32_16x16x32_bf16 v[30:33], v[138:141], v[202:205], v[30:33]
	v_mfma_f32_16x16x32_bf16 v[22:25], v[130:133], v[210:213], v[22:25]
	v_mfma_f32_16x16x32_bf16 v[14:17], v[138:141], v[210:213], v[14:17]
	v_mfma_f32_16x16x32_bf16 v[62:65], v[134:137], v[190:193], v[62:65]
	v_mfma_f32_16x16x32_bf16 v[58:61], v[142:145], v[190:193], v[58:61]
	v_mfma_f32_16x16x32_bf16 v[54:57], v[134:137], v[198:201], v[54:57]
	v_mfma_f32_16x16x32_bf16 v[46:49], v[142:145], v[198:201], v[46:49]
	v_mfma_f32_16x16x32_bf16 v[38:41], v[134:137], v[206:209], v[38:41]
	v_mfma_f32_16x16x32_bf16 v[30:33], v[142:145], v[206:209], v[30:33]
	v_mfma_f32_16x16x32_bf16 v[22:25], v[134:137], v[214:217], v[22:25]
	v_mfma_f32_16x16x32_bf16 v[14:17], v[142:145], v[214:217], v[14:17]
	v_mfma_f32_16x16x32_bf16 v[50:53], v[164:167], v[186:189], v[50:53]
	v_mfma_f32_16x16x32_bf16 v[42:45], v[178:181], v[186:189], v[42:45]
	v_mfma_f32_16x16x32_bf16 v[34:37], v[164:167], v[194:197], v[34:37]
	v_mfma_f32_16x16x32_bf16 v[26:29], v[178:181], v[194:197], v[26:29]
	v_mfma_f32_16x16x32_bf16 v[18:21], v[164:167], v[202:205], v[18:21]
	v_mfma_f32_16x16x32_bf16 v[10:13], v[178:181], v[202:205], v[10:13]
	v_mfma_f32_16x16x32_bf16 v[6:9], v[164:167], v[210:213], v[6:9]
	v_mfma_f32_16x16x32_bf16 v[2:5], v[178:181], v[210:213], v[2:5]
	s_setprio 3
	s_barrier
	v_mfma_f32_16x16x32_bf16 v[50:53], v[174:177], v[190:193], v[50:53]
	v_mfma_f32_16x16x32_bf16 v[42:45], v[182:185], v[190:193], v[42:45]
	v_mfma_f32_16x16x32_bf16 v[34:37], v[174:177], v[198:201], v[34:37]
	v_mfma_f32_16x16x32_bf16 v[26:29], v[182:185], v[198:201], v[26:29]
	v_mfma_f32_16x16x32_bf16 v[18:21], v[174:177], v[206:209], v[18:21]
	v_mfma_f32_16x16x32_bf16 v[10:13], v[182:185], v[206:209], v[10:13]
	v_mfma_f32_16x16x32_bf16 v[6:9], v[174:177], v[214:217], v[6:9]
	v_mfma_f32_16x16x32_bf16 v[2:5], v[182:185], v[214:217], v[2:5]
	s_setprio 0
	s_add_i32 s79, s79, 2
	s_add_u32 s6, s6, 0x100
	s_addc_u32 s7, s7, 0
	s_add_u32 s77, s77, 0x100
	s_addc_u32 s78, s78, 0
	s_cmp_gt_u32 s79, 5
	s_cbranch_scc0 .LBB0_478
	s_and_b64 vcc, exec, s[20:21]
	s_cbranch_vccz .LBB0_481
	s_barrier

; #define PG8_STAGE(bufoff, gbase, voff) do { _Pragma("unroll") for (int _i = 0; _i < 2; ++_i) \
;         __builtin_amdgcn_global_load_lds((const unsigned*)((const char*)(gbase) + (voff)[_i]), (PG8_LAS unsigned*)(lds + (bufoff) + ldsw + _i * 8192), 16, 0, 0); } while (0)
; #define PG8_LDA(dst, b, h) do { _Pragma("unroll") for (int m = 0; m < 4; ++m) _Pragma("unroll") for (int k = 0; k < 2; ++k) dst[m][k] = *(const PG8_LAS bf16x8*)(lds + PG8_SA(b, h) + aoff + m * 2048 + k * 1024); } while (0)
; #define PG8_LDB(dst, b, h) do { _Pragma("unroll") for (int n = 0; n < 2; ++n) _Pragma("unroll") for (int k = 0; k < 2; ++k) dst[n][k] = *(const PG8_LAS bf16x8*)(lds + PG8_SB(b, h) + boff + n * 2048 + k * 1024); } while (0)
; #define PG8_MMA(ai, bj, At, Bt) do { __builtin_amdgcn_s_setprio(3); _Pragma("unroll") for (int m = 0; m < 4; ++m) _Pragma("unroll") for (int n = 0; n < 2; ++n) _Pragma("unroll") for (int k = 0; k < 2; ++k) \
;         acc[ai][bj][m][n] = __builtin_amdgcn_mfma_f32_16x16x32_bf16(Bt[n][k], At[m][k], acc[ai][bj][m][n], 0, 0, 0); __builtin_amdgcn_s_setprio(0); } while (0)
; #define PG8_WAIT_V(n) asm volatile("s_waitcnt vmcnt(" #n ")" ::: "memory")
; template <class Epi, class Sched, bool ALIGN_EPI = false, bool SP2 = false>
; __device__ __forceinline__ void gemm_phase(PG8_LAS unsigned char* lds, const Gemm g, const Sched& S, const Epi& E) {
;     ...
;             PG8_LDB(B0, 0, 0); PG8_LDB(B1, 0, 1); PG8_SCHED; PG8_LDA(At, 0, 0); PG8_STAGE(PG8_SA(1, 1), a1 + hstepA, voffA);
;             PG8_WAIT_V(8); PG8_WAIT_L(0); PG8_BAR; PG8_MMA(0, 0, At, B0); PG8_MMA(0, 1, At, B1); PG8_BAR; PG8_SCHED;
;             PG8_LDA(At, 0, 1); PG8_STAGE(PG8_SB(0, 0), b2, voffB); PG8_STAGE(PG8_SB(0, 1), b2 + hstepB, voffB); PG8_STAGE(PG8_SA(0, 0), a2, voffA);
;             PG8_WAIT_V(8); PG8_WAIT_L(0); PG8_BAR; PG8_MMA(1, 0, At, B0); PG8_MMA(1, 1, At, B1); PG8_BAR; PG8_SCHED;
;             PG8_LDB(B0, 1, 0); PG8_LDB(B1, 1, 1); PG8_SCHED; PG8_LDA(At, 1, 0); PG8_STAGE(PG8_SA(0, 1), a2 + hstepA, voffA);
;             PG8_WAIT_V(8); PG8_WAIT_L(0); PG8_BAR; PG8_MMA(0, 0, At, B0); PG8_MMA(0, 1, At, B1); PG8_BAR; PG8_SCHED;
;             PG8_LDA(At, 1, 1); PG8_STAGE(PG8_SB(1, 0), b3, voffB); PG8_STAGE(PG8_SB(1, 1), b3 + hstepB, voffB); PG8_STAGE(PG8_SA(1, 0), a3, voffA);
;             PG8_WAIT_V(8); PG8_WAIT_L(0); PG8_BAR; PG8_MMA(1, 0, At, B0); PG8_MMA(1, 1, At, B1); PG8_BAR; PG8_SCHED;
.LBB0_727:
	v_add_u32_e32 v160, s66, v157
	ds_read_b128 v[130:133], v160
	ds_read_b128 v[164:167], v160 offset:1024
	ds_read_b128 v[168:171], v160 offset:2048
	ds_read_b128 v[172:175], v160 offset:3072
	v_add_u32_e32 v160, s67, v157
	s_add_u32 s0, s28, s30
	ds_read_b128 v[176:179], v160
	ds_read_b128 v[180:183], v160 offset:1024
	ds_read_b128 v[184:187], v160 offset:2048
	ds_read_b128 v[188:191], v160 offset:3072
	s_addc_u32 s1, s29, s31
	s_add_u32 s0, s0, 0x100
	s_addc_u32 s1, s1, 0
	s_add_u32 s84, s79, s30
	s_addc_u32 s85, s81, s31
	s_cmpk_eq_i32 s30, 0x1f00
	s_cselect_b32 s37, s23, s1
	s_cselect_b32 s36, s72, s0
	s_cselect_b32 s1, s75, s85
	s_cselect_b32 s0, s76, s84
	v_lshl_add_u64 v[160:161], v[150:151], 0, s[30:31]
	s_add_i32 m0, s44, 0xc000
	ds_read_b128 v[192:195], v159
	ds_read_b128 v[196:199], v159 offset:1024
	ds_read_b128 v[200:203], v159 offset:2048
	ds_read_b128 v[204:207], v159 offset:3072
	ds_read_b128 v[208:211], v159 offset:4096
	ds_read_b128 v[212:215], v159 offset:5120
	ds_read_b128 v[216:219], v159 offset:6144
	ds_read_b128 v[220:223], v159 offset:7168
	global_load_lds_dwordx4 v[160:161], off
	v_lshl_add_u64 v[160:161], v[152:153], 0, s[30:31]
	s_add_i32 m0, s44, 0xe000
	s_nop 0
	global_load_lds_dwordx4 v[160:161], off
	s_waitcnt vmcnt(8)
	s_waitcnt lgkmcnt(0)
	s_barrier
	s_setprio 2
	s_waitcnt lgkmcnt(0)
	v_mfma_f32_16x16x32_bf16 v[126:129], v[130:133], v[192:195], v[126:129]
	v_mfma_f32_16x16x32_bf16 v[122:125], v[168:171], v[192:195], v[122:125]
	v_mfma_f32_16x16x32_bf16 v[110:113], v[130:133], v[200:203], v[110:113]
	v_mfma_f32_16x16x32_bf16 v[106:109], v[168:171], v[200:203], v[106:109]
	v_mfma_f32_16x16x32_bf16 v[94:97], v[130:133], v[208:211], v[94:97]
	v_mfma_f32_16x16x32_bf16 v[90:93], v[168:171], v[208:211], v[90:93]
	v_mfma_f32_16x16x32_bf16 v[78:81], v[130:133], v[216:219], v[78:81]
	v_mfma_f32_16x16x32_bf16 v[74:77], v[168:171], v[216:219], v[74:77]
	v_mfma_f32_16x16x32_bf16 v[126:129], v[164:167], v[196:199], v[126:129]
	v_mfma_f32_16x16x32_bf16 v[122:125], v[172:175], v[196:199], v[122:125]
	v_mfma_f32_16x16x32_bf16 v[110:113], v[164:167], v[204:207], v[110:113]
	v_mfma_f32_16x16x32_bf16 v[106:109], v[172:175], v[204:207], v[106:109]
	v_mfma_f32_16x16x32_bf16 v[94:97], v[164:167], v[212:215], v[94:97]
	v_mfma_f32_16x16x32_bf16 v[90:93], v[172:175], v[212:215], v[90:93]
	v_mfma_f32_16x16x32_bf16 v[78:81], v[164:167], v[220:223], v[78:81]
	v_mfma_f32_16x16x32_bf16 v[74:77], v[172:175], v[220:223], v[74:77]
	v_mfma_f32_16x16x32_bf16 v[118:121], v[176:179], v[192:195], v[118:121]
	v_mfma_f32_16x16x32_bf16 v[114:117], v[184:187], v[192:195], v[114:117]
	v_mfma_f32_16x16x32_bf16 v[102:105], v[176:179], v[200:203], v[102:105]
	v_mfma_f32_16x16x32_bf16 v[98:101], v[184:187], v[200:203], v[98:101]
	v_mfma_f32_16x16x32_bf16 v[86:89], v[176:179], v[208:211], v[86:89]
	v_mfma_f32_16x16x32_bf16 v[82:85], v[184:187], v[208:211], v[82:85]
	v_mfma_f32_16x16x32_bf16 v[70:73], v[176:179], v[216:219], v[70:73]
	v_mfma_f32_16x16x32_bf16 v[66:69], v[184:187], v[216:219], v[66:69]
	s_setprio 3
	s_barrier
	v_mfma_f32_16x16x32_bf16 v[118:121], v[180:183], v[196:199], v[118:121]
	v_mfma_f32_16x16x32_bf16 v[114:117], v[188:191], v[196:199], v[114:117]
	v_mfma_f32_16x16x32_bf16 v[102:105], v[180:183], v[204:207], v[102:105]
	v_mfma_f32_16x16x32_bf16 v[98:101], v[188:191], v[204:207], v[98:101]
	v_mfma_f32_16x16x32_bf16 v[86:89], v[180:183], v[212:215], v[86:89]
	v_mfma_f32_16x16x32_bf16 v[82:85], v[188:191], v[212:215], v[82:85]
	v_mfma_f32_16x16x32_bf16 v[70:73], v[180:183], v[220:223], v[70:73]
	v_mfma_f32_16x16x32_bf16 v[66:69], v[188:191], v[220:223], v[66:69]
	s_setprio 0
	s_add_i32 s84, s66, s33
	v_lshl_add_u64 v[160:161], s[0:1], 0, v[136:137]
	s_mov_b32 m0, s84
	ds_read_b128 v[192:195], v159 offset:16384
	ds_read_b128 v[196:199], v159 offset:17408
	ds_read_b128 v[200:203], v159 offset:18432
	ds_read_b128 v[204:207], v159 offset:19456
	ds_read_b128 v[208:211], v159 offset:20480
	ds_read_b128 v[212:215], v159 offset:21504
	ds_read_b128 v[216:219], v159 offset:22528
	ds_read_b128 v[220:223], v159 offset:23552
	global_load_lds_dwordx4 v[160:161], off
	s_add_i32 m0, s84, 0x2000
	s_add_u32 s84, s0, 0x100000
	v_lshl_add_u64 v[224:225], s[0:1], 0, v[140:141]
	s_addc_u32 s85, s1, 0
	s_add_i32 s86, s67, s33
	global_load_lds_dwordx4 v[224:225], off
	v_lshl_add_u64 v[226:227], s[84:85], 0, v[136:137]
	s_mov_b32 m0, s86
	v_lshl_add_u64 v[228:229], s[36:37], 0, v[138:139]
	global_load_lds_dwordx4 v[226:227], off
	v_lshl_add_u64 v[226:227], s[84:85], 0, v[140:141]
	s_add_i32 m0, s86, 0x2000
	s_nop 0
	global_load_lds_dwordx4 v[226:227], off
	v_lshl_add_u64 v[226:227], s[36:37], 0, v[134:135]
	s_mov_b32 m0, s44
	s_nop 0
	global_load_lds_dwordx4 v[226:227], off
	s_mov_b32 m0, s45
	s_nop 0
	global_load_lds_dwordx4 v[228:229], off
	s_waitcnt vmcnt(8)
	s_waitcnt lgkmcnt(0)
	s_barrier
; #define PG8_STAGE(bufoff, gbase, voff) do { _Pragma("unroll") for (int _i = 0; _i < 2; ++_i) \
;         __builtin_amdgcn_global_load_lds((const unsigned*)((const char*)(gbase) + (voff)[_i]), (PG8_LAS unsigned*)(lds + (bufoff) + ldsw + _i * 8192), 16, 0, 0); } while (0)
; #define PG8_LDA(dst, b, h) do { _Pragma("unroll") for (int m = 0; m < 4; ++m) _Pragma("unroll") for (int k = 0; k < 2; ++k) dst[m][k] = *(const PG8_LAS bf16x8*)(lds + PG8_SA(b, h) + aoff + m * 2048 + k * 1024); } while (0)
; #define PG8_LDB(dst, b, h) do { _Pragma("unroll") for (int n = 0; n < 2; ++n) _Pragma("unroll") for (int k = 0; k < 2; ++k) dst[n][k] = *(const PG8_LAS bf16x8*)(lds + PG8_SB(b, h) + boff + n * 2048 + k * 1024); } while (0)
; #define PG8_MMA(ai, bj, At, Bt) do { __builtin_amdgcn_s_setprio(3); _Pragma("unroll") for (int m = 0; m < 4; ++m) _Pragma("unroll") for (int n = 0; n < 2; ++n) _Pragma("unroll") for (int k = 0; k < 2; ++k) \
;         acc[ai][bj][m][n] = __builtin_amdgcn_mfma_f32_16x16x32_bf16(Bt[n][k], At[m][k], acc[ai][bj][m][n], 0, 0, 0); __builtin_amdgcn_s_setprio(0); } while (0)
; #define PG8_WAIT_V(n) asm volatile("s_waitcnt vmcnt(" #n ")" ::: "memory")
; template <class Epi, class Sched, bool ALIGN_EPI = false, bool SP2 = false>
; __device__ __forceinline__ void gemm_phase(PG8_LAS unsigned char* lds, const Gemm g, const Sched& S, const Epi& E) {
;     ...
;             PG8_LDB(B0, 0, 0); PG8_LDB(B1, 0, 1); PG8_SCHED; PG8_LDA(At, 0, 0); PG8_STAGE(PG8_SA(1, 1), a1 + hstepA, voffA);
;             PG8_WAIT_V(8); PG8_WAIT_L(0); PG8_BAR; PG8_MMA(0, 0, At, B0); PG8_MMA(0, 1, At, B1); PG8_BAR; PG8_SCHED;
;             PG8_LDA(At, 0, 1); PG8_STAGE(PG8_SB(0, 0), b2, voffB); PG8_STAGE(PG8_SB(0, 1), b2 + hstepB, voffB); PG8_STAGE(PG8_SA(0, 0), a2, voffA);
;             PG8_WAIT_V(8); PG8_WAIT_L(0); PG8_BAR; PG8_MMA(1, 0, At, B0); PG8_MMA(1, 1, At, B1); PG8_BAR; PG8_SCHED;
;             PG8_LDB(B0, 1, 0); PG8_LDB(B1, 1, 1); PG8_SCHED; PG8_LDA(At, 1, 0); PG8_STAGE(PG8_SA(0, 1), a2 + hstepA, voffA);
;             PG8_WAIT_V(8); PG8_WAIT_L(0); PG8_BAR; PG8_MMA(0, 0, At, B0); PG8_MMA(0, 1, At, B1); PG8_BAR; PG8_SCHED;
;             PG8_LDA(At, 1, 1); PG8_STAGE(PG8_SB(1, 0), b3, voffB); PG8_STAGE(PG8_SB(1, 1), b3 + hstepB, voffB); PG8_STAGE(PG8_SA(1, 0), a3, voffA);
;             PG8_WAIT_V(8); PG8_WAIT_L(0); PG8_BAR; PG8_MMA(1, 0, At, B0); PG8_MMA(1, 1, At, B1); PG8_BAR; PG8_SCHED;
	s_setprio 2
	s_waitcnt lgkmcnt(0)
	v_mfma_f32_16x16x32_bf16 v[62:65], v[130:133], v[192:195], v[62:65]
	v_mfma_f32_16x16x32_bf16 v[58:61], v[168:171], v[192:195], v[58:61]
	v_mfma_f32_16x16x32_bf16 v[46:49], v[130:133], v[200:203], v[46:49]
	v_mfma_f32_16x16x32_bf16 v[42:45], v[168:171], v[200:203], v[42:45]
	v_mfma_f32_16x16x32_bf16 v[30:33], v[130:133], v[208:211], v[30:33]
	v_mfma_f32_16x16x32_bf16 v[26:29], v[168:171], v[208:211], v[26:29]
	v_mfma_f32_16x16x32_bf16 v[14:17], v[130:133], v[216:219], v[14:17]
	v_mfma_f32_16x16x32_bf16 v[10:13], v[168:171], v[216:219], v[10:13]
	v_mfma_f32_16x16x32_bf16 v[62:65], v[164:167], v[196:199], v[62:65]
	v_mfma_f32_16x16x32_bf16 v[58:61], v[172:175], v[196:199], v[58:61]
	v_mfma_f32_16x16x32_bf16 v[46:49], v[164:167], v[204:207], v[46:49]
	v_mfma_f32_16x16x32_bf16 v[42:45], v[172:175], v[204:207], v[42:45]
	v_mfma_f32_16x16x32_bf16 v[30:33], v[164:167], v[212:215], v[30:33]
	v_mfma_f32_16x16x32_bf16 v[26:29], v[172:175], v[212:215], v[26:29]
	v_mfma_f32_16x16x32_bf16 v[14:17], v[164:167], v[220:223], v[14:17]
	v_mfma_f32_16x16x32_bf16 v[10:13], v[172:175], v[220:223], v[10:13]
	v_mfma_f32_16x16x32_bf16 v[54:57], v[176:179], v[192:195], v[54:57]
	v_mfma_f32_16x16x32_bf16 v[50:53], v[184:187], v[192:195], v[50:53]
	v_mfma_f32_16x16x32_bf16 v[38:41], v[176:179], v[200:203], v[38:41]
	v_mfma_f32_16x16x32_bf16 v[34:37], v[184:187], v[200:203], v[34:37]
	v_mfma_f32_16x16x32_bf16 v[22:25], v[176:179], v[208:211], v[22:25]
	v_mfma_f32_16x16x32_bf16 v[18:21], v[184:187], v[208:211], v[18:21]
	v_mfma_f32_16x16x32_bf16 v[6:9], v[176:179], v[216:219], v[6:9]
	v_mfma_f32_16x16x32_bf16 v[2:5], v[184:187], v[216:219], v[2:5]
	s_setprio 3
	s_barrier
	v_mfma_f32_16x16x32_bf16 v[54:57], v[180:183], v[196:199], v[54:57]
	v_mfma_f32_16x16x32_bf16 v[50:53], v[188:191], v[196:199], v[50:53]
	v_mfma_f32_16x16x32_bf16 v[38:41], v[180:183], v[204:207], v[38:41]
	v_mfma_f32_16x16x32_bf16 v[34:37], v[188:191], v[204:207], v[34:37]
	v_mfma_f32_16x16x32_bf16 v[22:25], v[180:183], v[212:215], v[22:25]
	v_mfma_f32_16x16x32_bf16 v[18:21], v[188:191], v[212:215], v[18:21]
	v_mfma_f32_16x16x32_bf16 v[6:9], v[180:183], v[220:223], v[6:9]
	v_mfma_f32_16x16x32_bf16 v[2:5], v[188:191], v[220:223], v[2:5]
	s_setprio 0
	s_add_i32 s84, 0, 0x18000
	v_add_u32_e32 v163, s84, v157
	s_add_i32 s85, 0, 0x1c000
	ds_read_b128 v[130:133], v163
	ds_read_b128 v[164:167], v163 offset:1024
	ds_read_b128 v[168:171], v163 offset:2048
	ds_read_b128 v[172:175], v163 offset:3072
	v_add_u32_e32 v163, s85, v157
	ds_read_b128 v[176:179], v163
	ds_read_b128 v[180:183], v163 offset:1024
	ds_read_b128 v[184:187], v163 offset:2048
	ds_read_b128 v[188:191], v163 offset:3072
	s_add_u32 s36, s36, 0x100000
	s_addc_u32 s37, s37, 0
	s_mov_b32 m0, s54
	v_lshl_add_u64 v[230:231], s[36:37], 0, v[134:135]
	ds_read_b128 v[192:195], v159 offset:32768
	ds_read_b128 v[196:199], v159 offset:33792
	ds_read_b128 v[200:203], v159 offset:34816
	ds_read_b128 v[204:207], v159 offset:35840
	ds_read_b128 v[208:211], v159 offset:36864
	ds_read_b128 v[212:215], v159 offset:37888
	ds_read_b128 v[216:219], v159 offset:38912
	ds_read_b128 v[220:223], v159 offset:39936
	global_load_lds_dwordx4 v[230:231], off
	v_lshl_add_u64 v[230:231], s[36:37], 0, v[138:139]
	s_mov_b32 m0, s55
	s_nop 0
	global_load_lds_dwordx4 v[230:231], off
	s_waitcnt vmcnt(8)
	s_waitcnt lgkmcnt(0)
	s_barrier
	s_setprio 2
	s_waitcnt lgkmcnt(0)
	v_mfma_f32_16x16x32_bf16 v[126:129], v[130:133], v[192:195], v[126:129]
	v_mfma_f32_16x16x32_bf16 v[122:125], v[168:171], v[192:195], v[122:125]
	v_mfma_f32_16x16x32_bf16 v[110:113], v[130:133], v[200:203], v[110:113]
	v_mfma_f32_16x16x32_bf16 v[106:109], v[168:171], v[200:203], v[106:109]
	v_mfma_f32_16x16x32_bf16 v[94:97], v[130:133], v[208:211], v[94:97]
	v_mfma_f32_16x16x32_bf16 v[90:93], v[168:171], v[208:211], v[90:93]
	v_mfma_f32_16x16x32_bf16 v[78:81], v[130:133], v[216:219], v[78:81]
	v_mfma_f32_16x16x32_bf16 v[74:77], v[168:171], v[216:219], v[74:77]
	v_mfma_f32_16x16x32_bf16 v[126:129], v[164:167], v[196:199], v[126:129]
	v_mfma_f32_16x16x32_bf16 v[122:125], v[172:175], v[196:199], v[122:125]
	v_mfma_f32_16x16x32_bf16 v[110:113], v[164:167], v[204:207], v[110:113]
	v_mfma_f32_16x16x32_bf16 v[106:109], v[172:175], v[204:207], v[106:109]
	v_mfma_f32_16x16x32_bf16 v[94:97], v[164:167], v[212:215], v[94:97]
	v_mfma_f32_16x16x32_bf16 v[90:93], v[172:175], v[212:215], v[90:93]
	v_mfma_f32_16x16x32_bf16 v[78:81], v[164:167], v[220:223], v[78:81]
	v_mfma_f32_16x16x32_bf16 v[74:77], v[172:175], v[220:223], v[74:77]
	v_mfma_f32_16x16x32_bf16 v[118:121], v[176:179], v[192:195], v[118:121]
	v_mfma_f32_16x16x32_bf16 v[114:117], v[184:187], v[192:195], v[114:117]
	v_mfma_f32_16x16x32_bf16 v[102:105], v[176:179], v[200:203], v[102:105]
	v_mfma_f32_16x16x32_bf16 v[98:101], v[184:187], v[200:203], v[98:101]
	v_mfma_f32_16x16x32_bf16 v[86:89], v[176:179], v[208:211], v[86:89]
	v_mfma_f32_16x16x32_bf16 v[82:85], v[184:187], v[208:211], v[82:85]
	v_mfma_f32_16x16x32_bf16 v[70:73], v[176:179], v[216:219], v[70:73]
	v_mfma_f32_16x16x32_bf16 v[66:69], v[184:187], v[216:219], v[66:69]
	s_setprio 3
	s_barrier
; #define PG8_STAGE(bufoff, gbase, voff) do { _Pragma("unroll") for (int _i = 0; _i < 2; ++_i) \
;         __builtin_amdgcn_global_load_lds((const unsigned*)((const char*)(gbase) + (voff)[_i]), (PG8_LAS unsigned*)(lds + (bufoff) + ldsw + _i * 8192), 16, 0, 0); } while (0)
; #define PG8_LDA(dst, b, h) do { _Pragma("unroll") for (int m = 0; m < 4; ++m) _Pragma("unroll") for (int k = 0; k < 2; ++k) dst[m][k] = *(const PG8_LAS bf16x8*)(lds + PG8_SA(b, h) + aoff + m * 2048 + k * 1024); } while (0)
; #define PG8_LDB(dst, b, h) do { _Pragma("unroll") for (int n = 0; n < 2; ++n) _Pragma("unroll") for (int k = 0; k < 2; ++k) dst[n][k] = *(const PG8_LAS bf16x8*)(lds + PG8_SB(b, h) + boff + n * 2048 + k * 1024); } while (0)
; #define PG8_MMA(ai, bj, At, Bt) do { __builtin_amdgcn_s_setprio(3); _Pragma("unroll") for (int m = 0; m < 4; ++m) _Pragma("unroll") for (int n = 0; n < 2; ++n) _Pragma("unroll") for (int k = 0; k < 2; ++k) \
;         acc[ai][bj][m][n] = __builtin_amdgcn_mfma_f32_16x16x32_bf16(Bt[n][k], At[m][k], acc[ai][bj][m][n], 0, 0, 0); __builtin_amdgcn_s_setprio(0); } while (0)
; #define PG8_WAIT_V(n) asm volatile("s_waitcnt vmcnt(" #n ")" ::: "memory")
; #define PG8_WAIT_L(n) asm volatile("s_waitcnt lgkmcnt(" #n ")" ::: "memory")
; #define PG8_BAR __builtin_amdgcn_s_barrier()
; #define PG8_SCHED __builtin_amdgcn_sched_barrier(0)
; template <class Epi, class Sched, bool ALIGN_EPI = false, bool SP2 = false>
; __device__ __forceinline__ void gemm_phase(PG8_LAS unsigned char* lds, const Gemm g, const Sched& S, const Epi& E) {
;     ...
;             PG8_LDB(B0, 1, 0); PG8_LDB(B1, 1, 1); PG8_SCHED; PG8_LDA(At, 1, 0); PG8_STAGE(PG8_SA(0, 1), a2 + hstepA, voffA);
;             PG8_WAIT_V(8); PG8_WAIT_L(0); PG8_BAR; PG8_MMA(0, 0, At, B0); PG8_MMA(0, 1, At, B1); PG8_BAR; PG8_SCHED;
;             PG8_LDA(At, 1, 1); PG8_STAGE(PG8_SB(1, 0), b3, voffB); PG8_STAGE(PG8_SB(1, 1), b3 + hstepB, voffB); PG8_STAGE(PG8_SA(1, 0), a3, voffA);
;             PG8_WAIT_V(8); PG8_WAIT_L(0); PG8_BAR; PG8_MMA(1, 0, At, B0); PG8_MMA(1, 1, At, B1); PG8_BAR; PG8_SCHED;
	v_mfma_f32_16x16x32_bf16 v[118:121], v[180:183], v[196:199], v[118:121]
	v_mfma_f32_16x16x32_bf16 v[114:117], v[188:191], v[196:199], v[114:117]
	v_mfma_f32_16x16x32_bf16 v[102:105], v[180:183], v[204:207], v[102:105]
	v_mfma_f32_16x16x32_bf16 v[98:101], v[188:191], v[204:207], v[98:101]
	v_mfma_f32_16x16x32_bf16 v[86:89], v[180:183], v[212:215], v[86:89]
	v_mfma_f32_16x16x32_bf16 v[82:85], v[188:191], v[212:215], v[82:85]
	v_mfma_f32_16x16x32_bf16 v[70:73], v[180:183], v[220:223], v[70:73]
	v_mfma_f32_16x16x32_bf16 v[66:69], v[188:191], v[220:223], v[66:69]
	s_setprio 0
	s_add_i32 s36, s84, s33
	v_lshl_add_u64 v[160:161], v[160:161], 0, s[10:11]
	s_mov_b32 m0, s36
	ds_read_b128 v[192:195], v159 offset:49152
	ds_read_b128 v[196:199], v159 offset:50176
	ds_read_b128 v[200:203], v159 offset:51200
	ds_read_b128 v[204:207], v159 offset:52224
	ds_read_b128 v[208:211], v159 offset:53248
	ds_read_b128 v[212:215], v159 offset:54272
	ds_read_b128 v[216:219], v159 offset:55296
	ds_read_b128 v[220:223], v159 offset:56320
	global_load_lds_dwordx4 v[160:161], off
	s_add_i32 m0, s36, 0x2000
	s_add_u32 s0, s0, 0x100080
	v_lshl_add_u64 v[160:161], v[224:225], 0, s[10:11]
	s_addc_u32 s1, s1, 0
	s_add_i32 s36, s85, s33
	global_load_lds_dwordx4 v[160:161], off
	v_lshl_add_u64 v[160:161], s[0:1], 0, v[136:137]
	s_mov_b32 m0, s36
	s_nop 0
	global_load_lds_dwordx4 v[160:161], off
	v_lshl_add_u64 v[160:161], s[0:1], 0, v[140:141]
	s_add_i32 m0, s36, 0x2000
	s_nop 0
	global_load_lds_dwordx4 v[160:161], off
	v_lshl_add_u64 v[160:161], v[226:227], 0, s[10:11]
	s_mov_b32 m0, s61
	s_nop 0
	global_load_lds_dwordx4 v[160:161], off
	v_lshl_add_u64 v[160:161], v[228:229], 0, s[10:11]
	s_mov_b32 m0, s62
	s_nop 0
	global_load_lds_dwordx4 v[160:161], off
	s_waitcnt vmcnt(8)
	s_waitcnt lgkmcnt(0)
	s_barrier
	s_setprio 2
	s_waitcnt lgkmcnt(0)
	v_mfma_f32_16x16x32_bf16 v[62:65], v[130:133], v[192:195], v[62:65]
	v_mfma_f32_16x16x32_bf16 v[58:61], v[168:171], v[192:195], v[58:61]
	v_mfma_f32_16x16x32_bf16 v[46:49], v[130:133], v[200:203], v[46:49]
	v_mfma_f32_16x16x32_bf16 v[42:45], v[168:171], v[200:203], v[42:45]
	v_mfma_f32_16x16x32_bf16 v[30:33], v[130:133], v[208:211], v[30:33]
	v_mfma_f32_16x16x32_bf16 v[26:29], v[168:171], v[208:211], v[26:29]
	v_mfma_f32_16x16x32_bf16 v[14:17], v[130:133], v[216:219], v[14:17]
	v_mfma_f32_16x16x32_bf16 v[10:13], v[168:171], v[216:219], v[10:13]
	v_mfma_f32_16x16x32_bf16 v[62:65], v[164:167], v[196:199], v[62:65]
	v_mfma_f32_16x16x32_bf16 v[58:61], v[172:175], v[196:199], v[58:61]
	v_mfma_f32_16x16x32_bf16 v[46:49], v[164:167], v[204:207], v[46:49]
	v_mfma_f32_16x16x32_bf16 v[42:45], v[172:175], v[204:207], v[42:45]
	v_mfma_f32_16x16x32_bf16 v[30:33], v[164:167], v[212:215], v[30:33]
	v_mfma_f32_16x16x32_bf16 v[26:29], v[172:175], v[212:215], v[26:29]
	v_mfma_f32_16x16x32_bf16 v[14:17], v[164:167], v[220:223], v[14:17]
	v_mfma_f32_16x16x32_bf16 v[10:13], v[172:175], v[220:223], v[10:13]
	v_mfma_f32_16x16x32_bf16 v[54:57], v[176:179], v[192:195], v[54:57]
	v_mfma_f32_16x16x32_bf16 v[50:53], v[184:187], v[192:195], v[50:53]
	v_mfma_f32_16x16x32_bf16 v[38:41], v[176:179], v[200:203], v[38:41]
	v_mfma_f32_16x16x32_bf16 v[34:37], v[184:187], v[200:203], v[34:37]
	v_mfma_f32_16x16x32_bf16 v[22:25], v[176:179], v[208:211], v[22:25]
	v_mfma_f32_16x16x32_bf16 v[18:21], v[184:187], v[208:211], v[18:21]
	v_mfma_f32_16x16x32_bf16 v[6:9], v[176:179], v[216:219], v[6:9]
	v_mfma_f32_16x16x32_bf16 v[2:5], v[184:187], v[216:219], v[2:5]
	s_setprio 3
	s_barrier
	v_mfma_f32_16x16x32_bf16 v[54:57], v[180:183], v[196:199], v[54:57]
	v_mfma_f32_16x16x32_bf16 v[50:53], v[188:191], v[196:199], v[50:53]
	v_mfma_f32_16x16x32_bf16 v[38:41], v[180:183], v[204:207], v[38:41]
	v_mfma_f32_16x16x32_bf16 v[34:37], v[188:191], v[204:207], v[34:37]
	v_mfma_f32_16x16x32_bf16 v[22:25], v[180:183], v[212:215], v[22:25]
	v_mfma_f32_16x16x32_bf16 v[18:21], v[188:191], v[212:215], v[18:21]
	v_mfma_f32_16x16x32_bf16 v[6:9], v[180:183], v[220:223], v[6:9]
	v_mfma_f32_16x16x32_bf16 v[2:5], v[188:191], v[220:223], v[2:5]
	s_setprio 0
	s_add_i32 s83, s83, 2
	s_add_u32 s30, s30, 0x100
	s_addc_u32 s31, s31, 0
	s_cmp_gt_u32 s83, 61
	s_cbranch_scc1 .LBB0_730

; #define PG8_STAGE(bufoff, gbase, voff) do { _Pragma("unroll") for (int _i = 0; _i < 2; ++_i) \
;         __builtin_amdgcn_global_load_lds((const unsigned*)((const char*)(gbase) + (voff)[_i]), (PG8_LAS unsigned*)(lds + (bufoff) + ldsw + _i * 8192), 16, 0, 0); } while (0)
; #define PG8_LDA(dst, b, h) do { _Pragma("unroll") for (int m = 0; m < 4; ++m) _Pragma("unroll") for (int k = 0; k < 2; ++k) dst[m][k] = *(const PG8_LAS bf16x8*)(lds + PG8_SA(b, h) + aoff + m * 2048 + k * 1024); } while (0)
; #define PG8_LDB(dst, b, h) do { _Pragma("unroll") for (int n = 0; n < 2; ++n) _Pragma("unroll") for (int k = 0; k < 2; ++k) dst[n][k] = *(const PG8_LAS bf16x8*)(lds + PG8_SB(b, h) + boff + n * 2048 + k * 1024); } while (0)
; #define PG8_MMA(ai, bj, At, Bt) do { __builtin_amdgcn_s_setprio(3); _Pragma("unroll") for (int m = 0; m < 4; ++m) _Pragma("unroll") for (int n = 0; n < 2; ++n) _Pragma("unroll") for (int k = 0; k < 2; ++k) \
;         acc[ai][bj][m][n] = __builtin_amdgcn_mfma_f32_16x16x32_bf16(Bt[n][k], At[m][k], acc[ai][bj][m][n], 0, 0, 0); __builtin_amdgcn_s_setprio(0); } while (0)
; #define PG8_WAIT_V(n) asm volatile("s_waitcnt vmcnt(" #n ")" ::: "memory")
; template <class Epi, class Sched, bool ALIGN_EPI = false, bool SP2 = false>
; __device__ __forceinline__ void gemm_phase(PG8_LAS unsigned char* lds, const Gemm g, const Sched& S, const Epi& E) {
;     ...
;             PG8_LDB(B0, 0, 0); PG8_LDB(B1, 0, 1); PG8_SCHED; PG8_LDA(At, 0, 0); PG8_STAGE(PG8_SA(1, 1), a1 + hstepA, voffA);
;             PG8_WAIT_V(8); PG8_WAIT_L(0); PG8_BAR; PG8_MMA(0, 0, At, B0); PG8_MMA(0, 1, At, B1); PG8_BAR; PG8_SCHED;
;             PG8_LDA(At, 0, 1); PG8_STAGE(PG8_SB(0, 0), b2, voffB); PG8_STAGE(PG8_SB(0, 1), b2 + hstepB, voffB); PG8_STAGE(PG8_SA(0, 0), a2, voffA);
;             PG8_WAIT_V(8); PG8_WAIT_L(0); PG8_BAR; PG8_MMA(1, 0, At, B0); PG8_MMA(1, 1, At, B1); PG8_BAR; PG8_SCHED;
;             PG8_LDB(B0, 1, 0); PG8_LDB(B1, 1, 1); PG8_SCHED; PG8_LDA(At, 1, 0); PG8_STAGE(PG8_SA(0, 1), a2 + hstepA, voffA);
;             PG8_WAIT_V(8); PG8_WAIT_L(0); PG8_BAR; PG8_MMA(0, 0, At, B0); PG8_MMA(0, 1, At, B1); PG8_BAR; PG8_SCHED;
;             PG8_LDA(At, 1, 1); PG8_STAGE(PG8_SB(1, 0), b3, voffB); PG8_STAGE(PG8_SB(1, 1), b3 + hstepB, voffB); PG8_STAGE(PG8_SA(1, 0), a3, voffA);
;             PG8_WAIT_V(8); PG8_WAIT_L(0); PG8_BAR; PG8_MMA(1, 0, At, B0); PG8_MMA(1, 1, At, B1); PG8_BAR; PG8_SCHED;
.LBB0_808:
	v_add_u32_e32 v3, s65, v186
	ds_read_b128 v[134:137], v3
	ds_read_b128 v[138:141], v3 offset:1024
	ds_read_b128 v[142:145], v3 offset:2048
	ds_read_b128 v[146:149], v3 offset:3072
	v_add_u32_e32 v3, s66, v186
	s_add_u32 s36, s28, s30
	ds_read_b128 v[150:153], v3
	ds_read_b128 v[154:157], v3 offset:1024
	ds_read_b128 v[158:161], v3 offset:2048
	ds_read_b128 v[190:193], v3 offset:3072
	s_addc_u32 s37, s29, s31
	s_add_u32 s36, s36, 0x100
	s_addc_u32 s37, s37, 0
	s_add_u32 s86, s83, s30
	s_addc_u32 s87, s84, s31
	s_cmpk_eq_i32 s30, 0x1f00
	s_cselect_b32 s41, s23, s37
	s_cselect_b32 s40, s75, s36
	s_cselect_b32 s37, s77, s87
	s_cselect_b32 s36, s78, s86
	v_lshl_add_u64 v[4:5], v[180:181], 0, s[30:31]
	s_add_i32 m0, s42, 0xc000
	ds_read_b128 v[194:197], v188
	ds_read_b128 v[198:201], v188 offset:1024
	ds_read_b128 v[202:205], v188 offset:2048
	ds_read_b128 v[206:209], v188 offset:3072
	ds_read_b128 v[210:213], v188 offset:4096
	ds_read_b128 v[214:217], v188 offset:5120
	ds_read_b128 v[218:221], v188 offset:6144
	ds_read_b128 v[222:225], v188 offset:7168
	global_load_lds_dwordx4 v[4:5], off
	v_lshl_add_u64 v[4:5], v[182:183], 0, s[30:31]
	s_add_i32 m0, s42, 0xe000
	s_nop 0
	global_load_lds_dwordx4 v[4:5], off
	s_waitcnt vmcnt(8)
	s_waitcnt lgkmcnt(0)
	s_barrier
	s_setprio 2
	s_waitcnt lgkmcnt(0)
	v_mfma_f32_16x16x32_bf16 v[130:133], v[134:137], v[194:197], v[130:133]
	v_mfma_f32_16x16x32_bf16 v[126:129], v[142:145], v[194:197], v[126:129]
	v_mfma_f32_16x16x32_bf16 v[114:117], v[134:137], v[202:205], v[114:117]
	v_mfma_f32_16x16x32_bf16 v[110:113], v[142:145], v[202:205], v[110:113]
	v_mfma_f32_16x16x32_bf16 v[98:101], v[134:137], v[210:213], v[98:101]
	v_mfma_f32_16x16x32_bf16 v[94:97], v[142:145], v[210:213], v[94:97]
	v_mfma_f32_16x16x32_bf16 v[82:85], v[134:137], v[218:221], v[82:85]
	v_mfma_f32_16x16x32_bf16 v[78:81], v[142:145], v[218:221], v[78:81]
	v_mfma_f32_16x16x32_bf16 v[130:133], v[138:141], v[198:201], v[130:133]
	v_mfma_f32_16x16x32_bf16 v[126:129], v[146:149], v[198:201], v[126:129]
	v_mfma_f32_16x16x32_bf16 v[114:117], v[138:141], v[206:209], v[114:117]
	v_mfma_f32_16x16x32_bf16 v[110:113], v[146:149], v[206:209], v[110:113]
	v_mfma_f32_16x16x32_bf16 v[98:101], v[138:141], v[214:217], v[98:101]
	v_mfma_f32_16x16x32_bf16 v[94:97], v[146:149], v[214:217], v[94:97]
	v_mfma_f32_16x16x32_bf16 v[82:85], v[138:141], v[222:225], v[82:85]
	v_mfma_f32_16x16x32_bf16 v[78:81], v[146:149], v[222:225], v[78:81]
	v_mfma_f32_16x16x32_bf16 v[122:125], v[150:153], v[194:197], v[122:125]
	v_mfma_f32_16x16x32_bf16 v[118:121], v[158:161], v[194:197], v[118:121]
	v_mfma_f32_16x16x32_bf16 v[106:109], v[150:153], v[202:205], v[106:109]
	v_mfma_f32_16x16x32_bf16 v[102:105], v[158:161], v[202:205], v[102:105]
	v_mfma_f32_16x16x32_bf16 v[90:93], v[150:153], v[210:213], v[90:93]
	v_mfma_f32_16x16x32_bf16 v[86:89], v[158:161], v[210:213], v[86:89]
	v_mfma_f32_16x16x32_bf16 v[74:77], v[150:153], v[218:221], v[74:77]
	v_mfma_f32_16x16x32_bf16 v[70:73], v[158:161], v[218:221], v[70:73]
	s_setprio 3
	s_barrier
	v_mfma_f32_16x16x32_bf16 v[122:125], v[154:157], v[198:201], v[122:125]
	v_mfma_f32_16x16x32_bf16 v[118:121], v[190:193], v[198:201], v[118:121]
	v_mfma_f32_16x16x32_bf16 v[106:109], v[154:157], v[206:209], v[106:109]
	v_mfma_f32_16x16x32_bf16 v[102:105], v[190:193], v[206:209], v[102:105]
	v_mfma_f32_16x16x32_bf16 v[90:93], v[154:157], v[214:217], v[90:93]
	v_mfma_f32_16x16x32_bf16 v[86:89], v[190:193], v[214:217], v[86:89]
	v_mfma_f32_16x16x32_bf16 v[74:77], v[154:157], v[222:225], v[74:77]
	v_mfma_f32_16x16x32_bf16 v[70:73], v[190:193], v[222:225], v[70:73]
	s_setprio 0
	s_add_i32 s86, s65, s33
	v_lshl_add_u64 v[226:227], s[36:37], 0, v[166:167]
	s_mov_b32 m0, s86
	ds_read_b128 v[194:197], v188 offset:16384
	ds_read_b128 v[198:201], v188 offset:17408
	ds_read_b128 v[202:205], v188 offset:18432
	ds_read_b128 v[206:209], v188 offset:19456
	ds_read_b128 v[210:213], v188 offset:20480
	ds_read_b128 v[214:217], v188 offset:21504
	ds_read_b128 v[218:221], v188 offset:22528
	ds_read_b128 v[222:225], v188 offset:23552
	global_load_lds_dwordx4 v[226:227], off
	s_add_i32 m0, s86, 0x2000
	s_add_u32 s86, s36, 0x100000
	v_lshl_add_u64 v[228:229], s[36:37], 0, v[170:171]
	s_addc_u32 s87, s37, 0
	s_add_i32 s88, s66, s33
	global_load_lds_dwordx4 v[228:229], off
	v_lshl_add_u64 v[4:5], s[86:87], 0, v[166:167]
	s_mov_b32 m0, s88
	v_lshl_add_u64 v[230:231], s[40:41], 0, v[164:165]
	global_load_lds_dwordx4 v[4:5], off
	v_lshl_add_u64 v[4:5], s[86:87], 0, v[170:171]
	s_add_i32 m0, s88, 0x2000
	v_lshl_add_u64 v[232:233], s[40:41], 0, v[168:169]
	global_load_lds_dwordx4 v[4:5], off
	s_mov_b32 m0, s42
	s_nop 0
	global_load_lds_dwordx4 v[230:231], off
	s_mov_b32 m0, s43
	s_nop 0
	global_load_lds_dwordx4 v[232:233], off
	s_waitcnt vmcnt(8)
	s_waitcnt lgkmcnt(0)
	s_barrier
; #define PG8_STAGE(bufoff, gbase, voff) do { _Pragma("unroll") for (int _i = 0; _i < 2; ++_i) \
;         __builtin_amdgcn_global_load_lds((const unsigned*)((const char*)(gbase) + (voff)[_i]), (PG8_LAS unsigned*)(lds + (bufoff) + ldsw + _i * 8192), 16, 0, 0); } while (0)
; #define PG8_LDA(dst, b, h) do { _Pragma("unroll") for (int m = 0; m < 4; ++m) _Pragma("unroll") for (int k = 0; k < 2; ++k) dst[m][k] = *(const PG8_LAS bf16x8*)(lds + PG8_SA(b, h) + aoff + m * 2048 + k * 1024); } while (0)
; #define PG8_LDB(dst, b, h) do { _Pragma("unroll") for (int n = 0; n < 2; ++n) _Pragma("unroll") for (int k = 0; k < 2; ++k) dst[n][k] = *(const PG8_LAS bf16x8*)(lds + PG8_SB(b, h) + boff + n * 2048 + k * 1024); } while (0)
; #define PG8_MMA(ai, bj, At, Bt) do { __builtin_amdgcn_s_setprio(3); _Pragma("unroll") for (int m = 0; m < 4; ++m) _Pragma("unroll") for (int n = 0; n < 2; ++n) _Pragma("unroll") for (int k = 0; k < 2; ++k) \
;         acc[ai][bj][m][n] = __builtin_amdgcn_mfma_f32_16x16x32_bf16(Bt[n][k], At[m][k], acc[ai][bj][m][n], 0, 0, 0); __builtin_amdgcn_s_setprio(0); } while (0)
; #define PG8_WAIT_V(n) asm volatile("s_waitcnt vmcnt(" #n ")" ::: "memory")
; template <class Epi, class Sched, bool ALIGN_EPI = false, bool SP2 = false>
; __device__ __forceinline__ void gemm_phase(PG8_LAS unsigned char* lds, const Gemm g, const Sched& S, const Epi& E) {
;     ...
;             PG8_LDB(B0, 0, 0); PG8_LDB(B1, 0, 1); PG8_SCHED; PG8_LDA(At, 0, 0); PG8_STAGE(PG8_SA(1, 1), a1 + hstepA, voffA);
;             PG8_WAIT_V(8); PG8_WAIT_L(0); PG8_BAR; PG8_MMA(0, 0, At, B0); PG8_MMA(0, 1, At, B1); PG8_BAR; PG8_SCHED;
;             PG8_LDA(At, 0, 1); PG8_STAGE(PG8_SB(0, 0), b2, voffB); PG8_STAGE(PG8_SB(0, 1), b2 + hstepB, voffB); PG8_STAGE(PG8_SA(0, 0), a2, voffA);
;             PG8_WAIT_V(8); PG8_WAIT_L(0); PG8_BAR; PG8_MMA(1, 0, At, B0); PG8_MMA(1, 1, At, B1); PG8_BAR; PG8_SCHED;
;             PG8_LDB(B0, 1, 0); PG8_LDB(B1, 1, 1); PG8_SCHED; PG8_LDA(At, 1, 0); PG8_STAGE(PG8_SA(0, 1), a2 + hstepA, voffA);
;             PG8_WAIT_V(8); PG8_WAIT_L(0); PG8_BAR; PG8_MMA(0, 0, At, B0); PG8_MMA(0, 1, At, B1); PG8_BAR; PG8_SCHED;
;             PG8_LDA(At, 1, 1); PG8_STAGE(PG8_SB(1, 0), b3, voffB); PG8_STAGE(PG8_SB(1, 1), b3 + hstepB, voffB); PG8_STAGE(PG8_SA(1, 0), a3, voffA);
;             PG8_WAIT_V(8); PG8_WAIT_L(0); PG8_BAR; PG8_MMA(1, 0, At, B0); PG8_MMA(1, 1, At, B1); PG8_BAR; PG8_SCHED;
	s_setprio 2
	s_waitcnt lgkmcnt(0)
	v_mfma_f32_16x16x32_bf16 v[66:69], v[134:137], v[194:197], v[66:69]
	v_mfma_f32_16x16x32_bf16 v[62:65], v[142:145], v[194:197], v[62:65]
	v_mfma_f32_16x16x32_bf16 v[50:53], v[134:137], v[202:205], v[50:53]
	v_mfma_f32_16x16x32_bf16 v[46:49], v[142:145], v[202:205], v[46:49]
	v_mfma_f32_16x16x32_bf16 v[34:37], v[134:137], v[210:213], v[34:37]
	v_mfma_f32_16x16x32_bf16 v[30:33], v[142:145], v[210:213], v[30:33]
	v_mfma_f32_16x16x32_bf16 v[18:21], v[134:137], v[218:221], v[18:21]
	v_mfma_f32_16x16x32_bf16 v[14:17], v[142:145], v[218:221], v[14:17]
	v_mfma_f32_16x16x32_bf16 v[66:69], v[138:141], v[198:201], v[66:69]
	v_mfma_f32_16x16x32_bf16 v[62:65], v[146:149], v[198:201], v[62:65]
	v_mfma_f32_16x16x32_bf16 v[50:53], v[138:141], v[206:209], v[50:53]
	v_mfma_f32_16x16x32_bf16 v[46:49], v[146:149], v[206:209], v[46:49]
	v_mfma_f32_16x16x32_bf16 v[34:37], v[138:141], v[214:217], v[34:37]
	v_mfma_f32_16x16x32_bf16 v[30:33], v[146:149], v[214:217], v[30:33]
	v_mfma_f32_16x16x32_bf16 v[18:21], v[138:141], v[222:225], v[18:21]
	v_mfma_f32_16x16x32_bf16 v[14:17], v[146:149], v[222:225], v[14:17]
	v_mfma_f32_16x16x32_bf16 v[58:61], v[150:153], v[194:197], v[58:61]
	v_mfma_f32_16x16x32_bf16 v[54:57], v[158:161], v[194:197], v[54:57]
	v_mfma_f32_16x16x32_bf16 v[42:45], v[150:153], v[202:205], v[42:45]
	v_mfma_f32_16x16x32_bf16 v[38:41], v[158:161], v[202:205], v[38:41]
	v_mfma_f32_16x16x32_bf16 v[26:29], v[150:153], v[210:213], v[26:29]
	v_mfma_f32_16x16x32_bf16 v[22:25], v[158:161], v[210:213], v[22:25]
	v_mfma_f32_16x16x32_bf16 v[10:13], v[150:153], v[218:221], v[10:13]
	v_mfma_f32_16x16x32_bf16 v[4:7], v[158:161], v[218:221], v[6:9]
	s_setprio 3
	s_barrier
	v_mfma_f32_16x16x32_bf16 v[58:61], v[154:157], v[198:201], v[58:61]
	v_mfma_f32_16x16x32_bf16 v[54:57], v[190:193], v[198:201], v[54:57]
	v_mfma_f32_16x16x32_bf16 v[42:45], v[154:157], v[206:209], v[42:45]
	v_mfma_f32_16x16x32_bf16 v[38:41], v[190:193], v[206:209], v[38:41]
	v_mfma_f32_16x16x32_bf16 v[26:29], v[154:157], v[214:217], v[26:29]
	v_mfma_f32_16x16x32_bf16 v[22:25], v[190:193], v[214:217], v[22:25]
	v_mfma_f32_16x16x32_bf16 v[10:13], v[154:157], v[222:225], v[10:13]
	v_mfma_f32_16x16x32_bf16 v[4:7], v[190:193], v[222:225], v[4:7]
	s_setprio 0
	s_add_i32 s86, 0, 0x18000
	v_add_u32_e32 v3, s86, v186
	s_add_i32 s87, 0, 0x1c000
	ds_read_b128 v[134:137], v3
	ds_read_b128 v[138:141], v3 offset:1024
	ds_read_b128 v[142:145], v3 offset:2048
	ds_read_b128 v[146:149], v3 offset:3072
	v_add_u32_e32 v3, s87, v186
	ds_read_b128 v[150:153], v3
	ds_read_b128 v[154:157], v3 offset:1024
	ds_read_b128 v[158:161], v3 offset:2048
	ds_read_b128 v[190:193], v3 offset:3072
	s_add_u32 s40, s40, 0x100000
	s_addc_u32 s41, s41, 0
	s_mov_b32 m0, s44
	v_lshl_add_u64 v[8:9], s[40:41], 0, v[164:165]
	ds_read_b128 v[194:197], v188 offset:32768
	ds_read_b128 v[198:201], v188 offset:33792
	ds_read_b128 v[202:205], v188 offset:34816
	ds_read_b128 v[206:209], v188 offset:35840
	ds_read_b128 v[210:213], v188 offset:36864
	ds_read_b128 v[214:217], v188 offset:37888
	ds_read_b128 v[218:221], v188 offset:38912
	ds_read_b128 v[222:225], v188 offset:39936
	global_load_lds_dwordx4 v[8:9], off
	v_lshl_add_u64 v[8:9], s[40:41], 0, v[168:169]
	s_mov_b32 m0, s45
	s_nop 0
	global_load_lds_dwordx4 v[8:9], off
	s_waitcnt vmcnt(8)
	s_waitcnt lgkmcnt(0)
	s_barrier
	s_setprio 2
	s_waitcnt lgkmcnt(0)
	v_mfma_f32_16x16x32_bf16 v[130:133], v[134:137], v[194:197], v[130:133]
	v_mfma_f32_16x16x32_bf16 v[126:129], v[142:145], v[194:197], v[126:129]
	v_mfma_f32_16x16x32_bf16 v[114:117], v[134:137], v[202:205], v[114:117]
	v_mfma_f32_16x16x32_bf16 v[110:113], v[142:145], v[202:205], v[110:113]
	v_mfma_f32_16x16x32_bf16 v[98:101], v[134:137], v[210:213], v[98:101]
	v_mfma_f32_16x16x32_bf16 v[94:97], v[142:145], v[210:213], v[94:97]
	v_mfma_f32_16x16x32_bf16 v[82:85], v[134:137], v[218:221], v[82:85]
	v_mfma_f32_16x16x32_bf16 v[78:81], v[142:145], v[218:221], v[78:81]
	v_mfma_f32_16x16x32_bf16 v[130:133], v[138:141], v[198:201], v[130:133]
	v_mfma_f32_16x16x32_bf16 v[126:129], v[146:149], v[198:201], v[126:129]
	v_mfma_f32_16x16x32_bf16 v[114:117], v[138:141], v[206:209], v[114:117]
	v_mfma_f32_16x16x32_bf16 v[110:113], v[146:149], v[206:209], v[110:113]
	v_mfma_f32_16x16x32_bf16 v[98:101], v[138:141], v[214:217], v[98:101]
	v_mfma_f32_16x16x32_bf16 v[94:97], v[146:149], v[214:217], v[94:97]
	v_mfma_f32_16x16x32_bf16 v[82:85], v[138:141], v[222:225], v[82:85]
	v_mfma_f32_16x16x32_bf16 v[78:81], v[146:149], v[222:225], v[78:81]
	v_mfma_f32_16x16x32_bf16 v[122:125], v[150:153], v[194:197], v[122:125]
	v_mfma_f32_16x16x32_bf16 v[118:121], v[158:161], v[194:197], v[118:121]
	v_mfma_f32_16x16x32_bf16 v[106:109], v[150:153], v[202:205], v[106:109]
	v_mfma_f32_16x16x32_bf16 v[102:105], v[158:161], v[202:205], v[102:105]
	v_mfma_f32_16x16x32_bf16 v[90:93], v[150:153], v[210:213], v[90:93]
	v_mfma_f32_16x16x32_bf16 v[86:89], v[158:161], v[210:213], v[86:89]
	v_mfma_f32_16x16x32_bf16 v[74:77], v[150:153], v[218:221], v[74:77]
	v_mfma_f32_16x16x32_bf16 v[70:73], v[158:161], v[218:221], v[70:73]
	s_setprio 3
	s_barrier
; #define PG8_STAGE(bufoff, gbase, voff) do { _Pragma("unroll") for (int _i = 0; _i < 2; ++_i) \
;         __builtin_amdgcn_global_load_lds((const unsigned*)((const char*)(gbase) + (voff)[_i]), (PG8_LAS unsigned*)(lds + (bufoff) + ldsw + _i * 8192), 16, 0, 0); } while (0)
; #define PG8_LDA(dst, b, h) do { _Pragma("unroll") for (int m = 0; m < 4; ++m) _Pragma("unroll") for (int k = 0; k < 2; ++k) dst[m][k] = *(const PG8_LAS bf16x8*)(lds + PG8_SA(b, h) + aoff + m * 2048 + k * 1024); } while (0)
; #define PG8_LDB(dst, b, h) do { _Pragma("unroll") for (int n = 0; n < 2; ++n) _Pragma("unroll") for (int k = 0; k < 2; ++k) dst[n][k] = *(const PG8_LAS bf16x8*)(lds + PG8_SB(b, h) + boff + n * 2048 + k * 1024); } while (0)
; #define PG8_MMA(ai, bj, At, Bt) do { __builtin_amdgcn_s_setprio(3); _Pragma("unroll") for (int m = 0; m < 4; ++m) _Pragma("unroll") for (int n = 0; n < 2; ++n) _Pragma("unroll") for (int k = 0; k < 2; ++k) \
;         acc[ai][bj][m][n] = __builtin_amdgcn_mfma_f32_16x16x32_bf16(Bt[n][k], At[m][k], acc[ai][bj][m][n], 0, 0, 0); __builtin_amdgcn_s_setprio(0); } while (0)
; #define PG8_WAIT_V(n) asm volatile("s_waitcnt vmcnt(" #n ")" ::: "memory")
; #define PG8_WAIT_L(n) asm volatile("s_waitcnt lgkmcnt(" #n ")" ::: "memory")
; #define PG8_BAR __builtin_amdgcn_s_barrier()
; #define PG8_SCHED __builtin_amdgcn_sched_barrier(0)
; template <class Epi, class Sched, bool ALIGN_EPI = false, bool SP2 = false>
; __device__ __forceinline__ void gemm_phase(PG8_LAS unsigned char* lds, const Gemm g, const Sched& S, const Epi& E) {
;     ...
;             PG8_LDB(B0, 1, 0); PG8_LDB(B1, 1, 1); PG8_SCHED; PG8_LDA(At, 1, 0); PG8_STAGE(PG8_SA(0, 1), a2 + hstepA, voffA);
;             PG8_WAIT_V(8); PG8_WAIT_L(0); PG8_BAR; PG8_MMA(0, 0, At, B0); PG8_MMA(0, 1, At, B1); PG8_BAR; PG8_SCHED;
;             PG8_LDA(At, 1, 1); PG8_STAGE(PG8_SB(1, 0), b3, voffB); PG8_STAGE(PG8_SB(1, 1), b3 + hstepB, voffB); PG8_STAGE(PG8_SA(1, 0), a3, voffA);
;             PG8_WAIT_V(8); PG8_WAIT_L(0); PG8_BAR; PG8_MMA(1, 0, At, B0); PG8_MMA(1, 1, At, B1); PG8_BAR; PG8_SCHED;
	v_mfma_f32_16x16x32_bf16 v[122:125], v[154:157], v[198:201], v[122:125]
	v_mfma_f32_16x16x32_bf16 v[118:121], v[190:193], v[198:201], v[118:121]
	v_mfma_f32_16x16x32_bf16 v[106:109], v[154:157], v[206:209], v[106:109]
	v_mfma_f32_16x16x32_bf16 v[102:105], v[190:193], v[206:209], v[102:105]
	v_mfma_f32_16x16x32_bf16 v[90:93], v[154:157], v[214:217], v[90:93]
	v_mfma_f32_16x16x32_bf16 v[86:89], v[190:193], v[214:217], v[86:89]
	v_mfma_f32_16x16x32_bf16 v[74:77], v[154:157], v[222:225], v[74:77]
	v_mfma_f32_16x16x32_bf16 v[70:73], v[190:193], v[222:225], v[70:73]
	s_setprio 0
	s_add_i32 s40, s86, s33
	v_lshl_add_u64 v[8:9], v[226:227], 0, s[10:11]
	s_mov_b32 m0, s40
	ds_read_b128 v[194:197], v188 offset:49152
	ds_read_b128 v[198:201], v188 offset:50176
	ds_read_b128 v[202:205], v188 offset:51200
	ds_read_b128 v[206:209], v188 offset:52224
	ds_read_b128 v[210:213], v188 offset:53248
	ds_read_b128 v[214:217], v188 offset:54272
	ds_read_b128 v[218:221], v188 offset:55296
	ds_read_b128 v[222:225], v188 offset:56320
	global_load_lds_dwordx4 v[8:9], off
	s_add_i32 m0, s40, 0x2000
	s_add_u32 s36, s36, 0x100080
	v_lshl_add_u64 v[8:9], v[228:229], 0, s[10:11]
	s_addc_u32 s37, s37, 0
	s_add_i32 s40, s87, s33
	global_load_lds_dwordx4 v[8:9], off
	v_lshl_add_u64 v[8:9], s[36:37], 0, v[166:167]
	s_mov_b32 m0, s40
	s_nop 0
	global_load_lds_dwordx4 v[8:9], off
	v_lshl_add_u64 v[8:9], s[36:37], 0, v[170:171]
	s_add_i32 m0, s40, 0x2000
	s_nop 0
	global_load_lds_dwordx4 v[8:9], off
	v_lshl_add_u64 v[8:9], v[230:231], 0, s[10:11]
	s_mov_b32 m0, s60
	s_nop 0
	global_load_lds_dwordx4 v[8:9], off
	v_lshl_add_u64 v[8:9], v[232:233], 0, s[10:11]
	s_mov_b32 m0, s61
	s_nop 0
	global_load_lds_dwordx4 v[8:9], off
	s_waitcnt vmcnt(8)
	s_waitcnt lgkmcnt(0)
	s_barrier
	s_setprio 2
	s_waitcnt lgkmcnt(0)
	v_mfma_f32_16x16x32_bf16 v[66:69], v[134:137], v[194:197], v[66:69]
	v_mfma_f32_16x16x32_bf16 v[62:65], v[142:145], v[194:197], v[62:65]
	v_mfma_f32_16x16x32_bf16 v[50:53], v[134:137], v[202:205], v[50:53]
	v_mfma_f32_16x16x32_bf16 v[46:49], v[142:145], v[202:205], v[46:49]
	v_mfma_f32_16x16x32_bf16 v[34:37], v[134:137], v[210:213], v[34:37]
	v_mfma_f32_16x16x32_bf16 v[30:33], v[142:145], v[210:213], v[30:33]
	v_mfma_f32_16x16x32_bf16 v[18:21], v[134:137], v[218:221], v[18:21]
	v_mfma_f32_16x16x32_bf16 v[14:17], v[142:145], v[218:221], v[14:17]
	v_mfma_f32_16x16x32_bf16 v[66:69], v[138:141], v[198:201], v[66:69]
	v_mfma_f32_16x16x32_bf16 v[62:65], v[146:149], v[198:201], v[62:65]
	v_mfma_f32_16x16x32_bf16 v[50:53], v[138:141], v[206:209], v[50:53]
	v_mfma_f32_16x16x32_bf16 v[46:49], v[146:149], v[206:209], v[46:49]
	v_mfma_f32_16x16x32_bf16 v[34:37], v[138:141], v[214:217], v[34:37]
	v_mfma_f32_16x16x32_bf16 v[30:33], v[146:149], v[214:217], v[30:33]
	v_mfma_f32_16x16x32_bf16 v[18:21], v[138:141], v[222:225], v[18:21]
	v_mfma_f32_16x16x32_bf16 v[14:17], v[146:149], v[222:225], v[14:17]
	v_mfma_f32_16x16x32_bf16 v[58:61], v[150:153], v[194:197], v[58:61]
	v_mfma_f32_16x16x32_bf16 v[54:57], v[158:161], v[194:197], v[54:57]
	v_mfma_f32_16x16x32_bf16 v[42:45], v[150:153], v[202:205], v[42:45]
	v_mfma_f32_16x16x32_bf16 v[38:41], v[158:161], v[202:205], v[38:41]
	v_mfma_f32_16x16x32_bf16 v[26:29], v[150:153], v[210:213], v[26:29]
	v_mfma_f32_16x16x32_bf16 v[22:25], v[158:161], v[210:213], v[22:25]
	v_mfma_f32_16x16x32_bf16 v[8:11], v[150:153], v[218:221], v[10:13]
	v_mfma_f32_16x16x32_bf16 v[4:7], v[158:161], v[218:221], v[4:7]
	s_setprio 3
	s_barrier
	v_mfma_f32_16x16x32_bf16 v[58:61], v[154:157], v[198:201], v[58:61]
	v_mfma_f32_16x16x32_bf16 v[54:57], v[190:193], v[198:201], v[54:57]
	v_mfma_f32_16x16x32_bf16 v[42:45], v[154:157], v[206:209], v[42:45]
	v_mfma_f32_16x16x32_bf16 v[38:41], v[190:193], v[206:209], v[38:41]
	v_mfma_f32_16x16x32_bf16 v[26:29], v[154:157], v[214:217], v[26:29]
	v_mfma_f32_16x16x32_bf16 v[22:25], v[190:193], v[214:217], v[22:25]
	v_mfma_f32_16x16x32_bf16 v[10:13], v[154:157], v[222:225], v[8:11]
	v_mfma_f32_16x16x32_bf16 v[6:9], v[190:193], v[222:225], v[4:7]
	s_setprio 0
	s_add_i32 s85, s85, 2
	s_add_u32 s30, s30, 0x100
	s_addc_u32 s31, s31, 0
	s_cmp_gt_u32 s85, 61
	s_cbranch_scc1 .LBB0_811

; #define PG8_STAGE(bufoff, gbase, voff) do { _Pragma("unroll") for (int _i = 0; _i < 2; ++_i) \
;         __builtin_amdgcn_global_load_lds((const unsigned*)((const char*)(gbase) + (voff)[_i]), (PG8_LAS unsigned*)(lds + (bufoff) + ldsw + _i * 8192), 16, 0, 0); } while (0)
; #define PG8_LDA(dst, b, h) do { _Pragma("unroll") for (int m = 0; m < 4; ++m) _Pragma("unroll") for (int k = 0; k < 2; ++k) dst[m][k] = *(const PG8_LAS bf16x8*)(lds + PG8_SA(b, h) + aoff + m * 2048 + k * 1024); } while (0)
; #define PG8_LDB(dst, b, h) do { _Pragma("unroll") for (int n = 0; n < 2; ++n) _Pragma("unroll") for (int k = 0; k < 2; ++k) dst[n][k] = *(const PG8_LAS bf16x8*)(lds + PG8_SB(b, h) + boff + n * 2048 + k * 1024); } while (0)
; #define PG8_MMA(ai, bj, At, Bt) do { __builtin_amdgcn_s_setprio(3); _Pragma("unroll") for (int m = 0; m < 4; ++m) _Pragma("unroll") for (int n = 0; n < 2; ++n) _Pragma("unroll") for (int k = 0; k < 2; ++k) \
;         acc[ai][bj][m][n] = __builtin_amdgcn_mfma_f32_16x16x32_bf16(Bt[n][k], At[m][k], acc[ai][bj][m][n], 0, 0, 0); __builtin_amdgcn_s_setprio(0); } while (0)
; #define PG8_WAIT_V(n) asm volatile("s_waitcnt vmcnt(" #n ")" ::: "memory")
; template <class Epi, class Sched, bool ALIGN_EPI = false, bool SP2 = false>
; __device__ __forceinline__ void gemm_phase(PG8_LAS unsigned char* lds, const Gemm g, const Sched& S, const Epi& E) {
;     ...
;             PG8_LDB(B0, 0, 0); PG8_LDB(B1, 0, 1); PG8_SCHED; PG8_LDA(At, 0, 0); PG8_STAGE(PG8_SA(1, 1), a1 + hstepA, voffA);
;             PG8_WAIT_V(8); PG8_WAIT_L(0); PG8_BAR; PG8_MMA(0, 0, At, B0); PG8_MMA(0, 1, At, B1); PG8_BAR; PG8_SCHED;
;             PG8_LDA(At, 0, 1); PG8_STAGE(PG8_SB(0, 0), b2, voffB); PG8_STAGE(PG8_SB(0, 1), b2 + hstepB, voffB); PG8_STAGE(PG8_SA(0, 0), a2, voffA);
;             PG8_WAIT_V(8); PG8_WAIT_L(0); PG8_BAR; PG8_MMA(1, 0, At, B0); PG8_MMA(1, 1, At, B1); PG8_BAR; PG8_SCHED;
;             PG8_LDB(B0, 1, 0); PG8_LDB(B1, 1, 1); PG8_SCHED; PG8_LDA(At, 1, 0); PG8_STAGE(PG8_SA(0, 1), a2 + hstepA, voffA);
;             PG8_WAIT_V(8); PG8_WAIT_L(0); PG8_BAR; PG8_MMA(0, 0, At, B0); PG8_MMA(0, 1, At, B1); PG8_BAR; PG8_SCHED;
;             PG8_LDA(At, 1, 1); PG8_STAGE(PG8_SB(1, 0), b3, voffB); PG8_STAGE(PG8_SB(1, 1), b3 + hstepB, voffB); PG8_STAGE(PG8_SA(1, 0), a3, voffA);
;             PG8_WAIT_V(8); PG8_WAIT_L(0); PG8_BAR; PG8_MMA(1, 0, At, B0); PG8_MMA(1, 1, At, B1); PG8_BAR; PG8_SCHED;
.LBB0_908:
	ds_read_b128 v[158:161], v155
	ds_read_b128 v[164:167], v155 offset:1024
	ds_read_b128 v[168:171], v155 offset:2048
	ds_read_b128 v[172:175], v155 offset:3072
	ds_read_b128 v[176:179], v156
	ds_read_b128 v[180:183], v156 offset:1024
	ds_read_b128 v[184:187], v156 offset:2048
	ds_read_b128 v[188:191], v156 offset:3072
	s_add_u32 s26, s24, 0xfff00080
	s_addc_u32 s27, s25, -1
	s_cmp_eq_u32 s55, 60
	s_cselect_b32 s29, s17, s27
	s_cselect_b32 s28, s47, s26
	s_cselect_b32 s27, s15, s54
	s_cselect_b32 s26, s52, s53
	v_lshl_add_u64 v[146:147], s[24:25], 0, v[138:139]
	s_add_i32 m0, s23, 0xc000
	ds_read_b128 v[192:195], v157
	ds_read_b128 v[196:199], v157 offset:1024
	ds_read_b128 v[200:203], v157 offset:2048
	ds_read_b128 v[204:207], v157 offset:3072
	ds_read_b128 v[208:211], v157 offset:4096
	ds_read_b128 v[212:215], v157 offset:5120
	ds_read_b128 v[216:219], v157 offset:6144
	ds_read_b128 v[220:223], v157 offset:7168
	global_load_lds_dwordx4 v[146:147], off
	v_lshl_add_u64 v[146:147], s[24:25], 0, v[140:141]
	s_add_i32 m0, s23, 0xe000
	s_nop 0
	global_load_lds_dwordx4 v[146:147], off
	s_waitcnt vmcnt(8)
	s_waitcnt lgkmcnt(0)
	s_barrier
	s_setprio 2
	s_waitcnt lgkmcnt(0)
	v_mfma_f32_16x16x32_bf16 v[126:129], v[158:161], v[192:195], v[126:129]
	v_mfma_f32_16x16x32_bf16 v[122:125], v[168:171], v[192:195], v[122:125]
	v_mfma_f32_16x16x32_bf16 v[114:117], v[158:161], v[200:203], v[114:117]
	v_mfma_f32_16x16x32_bf16 v[106:109], v[168:171], v[200:203], v[106:109]
	v_mfma_f32_16x16x32_bf16 v[98:101], v[158:161], v[208:211], v[98:101]
	v_mfma_f32_16x16x32_bf16 v[90:93], v[168:171], v[208:211], v[90:93]
	v_mfma_f32_16x16x32_bf16 v[82:85], v[158:161], v[216:219], v[82:85]
	v_mfma_f32_16x16x32_bf16 v[74:77], v[168:171], v[216:219], v[74:77]
	v_mfma_f32_16x16x32_bf16 v[126:129], v[164:167], v[196:199], v[126:129]
	v_mfma_f32_16x16x32_bf16 v[122:125], v[172:175], v[196:199], v[122:125]
	v_mfma_f32_16x16x32_bf16 v[114:117], v[164:167], v[204:207], v[114:117]
	v_mfma_f32_16x16x32_bf16 v[106:109], v[172:175], v[204:207], v[106:109]
	v_mfma_f32_16x16x32_bf16 v[98:101], v[164:167], v[212:215], v[98:101]
	v_mfma_f32_16x16x32_bf16 v[90:93], v[172:175], v[212:215], v[90:93]
	v_mfma_f32_16x16x32_bf16 v[82:85], v[164:167], v[220:223], v[82:85]
	v_mfma_f32_16x16x32_bf16 v[74:77], v[172:175], v[220:223], v[74:77]
	v_mfma_f32_16x16x32_bf16 v[118:121], v[176:179], v[192:195], v[118:121]
	v_mfma_f32_16x16x32_bf16 v[110:113], v[184:187], v[192:195], v[110:113]
	v_mfma_f32_16x16x32_bf16 v[102:105], v[176:179], v[200:203], v[102:105]
	v_mfma_f32_16x16x32_bf16 v[94:97], v[184:187], v[200:203], v[94:97]
	v_mfma_f32_16x16x32_bf16 v[86:89], v[176:179], v[208:211], v[86:89]
	v_mfma_f32_16x16x32_bf16 v[78:81], v[184:187], v[208:211], v[78:81]
	v_mfma_f32_16x16x32_bf16 v[70:73], v[176:179], v[216:219], v[70:73]
	v_mfma_f32_16x16x32_bf16 v[66:69], v[184:187], v[216:219], v[66:69]
	s_setprio 3
	s_barrier
	v_mfma_f32_16x16x32_bf16 v[118:121], v[180:183], v[196:199], v[118:121]
	v_mfma_f32_16x16x32_bf16 v[110:113], v[188:191], v[196:199], v[110:113]
	v_mfma_f32_16x16x32_bf16 v[102:105], v[180:183], v[204:207], v[102:105]
	v_mfma_f32_16x16x32_bf16 v[94:97], v[188:191], v[204:207], v[94:97]
	v_mfma_f32_16x16x32_bf16 v[86:89], v[180:183], v[212:215], v[86:89]
	v_mfma_f32_16x16x32_bf16 v[78:81], v[188:191], v[212:215], v[78:81]
	v_mfma_f32_16x16x32_bf16 v[70:73], v[180:183], v[220:223], v[70:73]
	v_mfma_f32_16x16x32_bf16 v[66:69], v[188:191], v[220:223], v[66:69]
	s_setprio 0
	s_add_i32 s56, s42, s30
	v_lshl_add_u64 v[146:147], s[26:27], 0, v[134:135]
	s_mov_b32 m0, s56
	ds_read_b128 v[192:195], v157 offset:16384
	ds_read_b128 v[196:199], v157 offset:17408
	ds_read_b128 v[200:203], v157 offset:18432
	ds_read_b128 v[204:207], v157 offset:19456
	ds_read_b128 v[208:211], v157 offset:20480
	ds_read_b128 v[212:215], v157 offset:21504
	ds_read_b128 v[216:219], v157 offset:22528
	ds_read_b128 v[220:223], v157 offset:23552
	global_load_lds_dwordx4 v[146:147], off
	s_add_i32 m0, s56, 0x2000
	s_add_u32 s56, s26, 0x100000
	v_lshl_add_u64 v[224:225], s[26:27], 0, v[130:131]
	s_addc_u32 s57, s27, 0
	s_add_i32 s58, s43, s30
	global_load_lds_dwordx4 v[224:225], off
	v_lshl_add_u64 v[226:227], s[56:57], 0, v[134:135]
	s_mov_b32 m0, s58
	v_lshl_add_u64 v[228:229], s[28:29], 0, v[132:133]
	global_load_lds_dwordx4 v[226:227], off
	v_lshl_add_u64 v[226:227], s[56:57], 0, v[130:131]
	s_add_i32 m0, s58, 0x2000
	s_nop 0
	global_load_lds_dwordx4 v[226:227], off
	v_lshl_add_u64 v[226:227], s[28:29], 0, v[136:137]
	s_mov_b32 m0, s23
	s_nop 0
	global_load_lds_dwordx4 v[226:227], off
	s_mov_b32 m0, s33
	s_nop 0
	global_load_lds_dwordx4 v[228:229], off
	s_waitcnt vmcnt(8)
	s_waitcnt lgkmcnt(0)
	s_barrier
	s_setprio 2
	s_waitcnt lgkmcnt(0)
	v_mfma_f32_16x16x32_bf16 v[62:65], v[158:161], v[192:195], v[62:65]
	v_mfma_f32_16x16x32_bf16 v[58:61], v[168:171], v[192:195], v[58:61]
	v_mfma_f32_16x16x32_bf16 v[50:53], v[158:161], v[200:203], v[50:53]
	v_mfma_f32_16x16x32_bf16 v[42:45], v[168:171], v[200:203], v[42:45]
	v_mfma_f32_16x16x32_bf16 v[34:37], v[158:161], v[208:211], v[34:37]
	v_mfma_f32_16x16x32_bf16 v[26:29], v[168:171], v[208:211], v[26:29]
	v_mfma_f32_16x16x32_bf16 v[14:17], v[158:161], v[216:219], v[14:17]
	v_mfma_f32_16x16x32_bf16 v[10:13], v[168:171], v[216:219], v[10:13]
	v_mfma_f32_16x16x32_bf16 v[62:65], v[164:167], v[196:199], v[62:65]
	v_mfma_f32_16x16x32_bf16 v[58:61], v[172:175], v[196:199], v[58:61]
	v_mfma_f32_16x16x32_bf16 v[50:53], v[164:167], v[204:207], v[50:53]
	v_mfma_f32_16x16x32_bf16 v[42:45], v[172:175], v[204:207], v[42:45]
	v_mfma_f32_16x16x32_bf16 v[34:37], v[164:167], v[212:215], v[34:37]
	v_mfma_f32_16x16x32_bf16 v[26:29], v[172:175], v[212:215], v[26:29]
	v_mfma_f32_16x16x32_bf16 v[14:17], v[164:167], v[220:223], v[14:17]
	v_mfma_f32_16x16x32_bf16 v[10:13], v[172:175], v[220:223], v[10:13]
	v_mfma_f32_16x16x32_bf16 v[54:57], v[176:179], v[192:195], v[54:57]
	v_mfma_f32_16x16x32_bf16 v[46:49], v[184:187], v[192:195], v[46:49]
	v_mfma_f32_16x16x32_bf16 v[38:41], v[176:179], v[200:203], v[38:41]
	v_mfma_f32_16x16x32_bf16 v[30:33], v[184:187], v[200:203], v[30:33]
	v_mfma_f32_16x16x32_bf16 v[22:25], v[176:179], v[208:211], v[22:25]
	v_mfma_f32_16x16x32_bf16 v[18:21], v[184:187], v[208:211], v[18:21]
	v_mfma_f32_16x16x32_bf16 v[6:9], v[176:179], v[216:219], v[6:9]
	v_mfma_f32_16x16x32_bf16 v[2:5], v[184:187], v[216:219], v[2:5]
	s_setprio 3
	s_barrier
; #define PG8_STAGE(bufoff, gbase, voff) do { _Pragma("unroll") for (int _i = 0; _i < 2; ++_i) \
;         __builtin_amdgcn_global_load_lds((const unsigned*)((const char*)(gbase) + (voff)[_i]), (PG8_LAS unsigned*)(lds + (bufoff) + ldsw + _i * 8192), 16, 0, 0); } while (0)
; #define PG8_LDA(dst, b, h) do { _Pragma("unroll") for (int m = 0; m < 4; ++m) _Pragma("unroll") for (int k = 0; k < 2; ++k) dst[m][k] = *(const PG8_LAS bf16x8*)(lds + PG8_SA(b, h) + aoff + m * 2048 + k * 1024); } while (0)
; #define PG8_LDB(dst, b, h) do { _Pragma("unroll") for (int n = 0; n < 2; ++n) _Pragma("unroll") for (int k = 0; k < 2; ++k) dst[n][k] = *(const PG8_LAS bf16x8*)(lds + PG8_SB(b, h) + boff + n * 2048 + k * 1024); } while (0)
; #define PG8_MMA(ai, bj, At, Bt) do { __builtin_amdgcn_s_setprio(3); _Pragma("unroll") for (int m = 0; m < 4; ++m) _Pragma("unroll") for (int n = 0; n < 2; ++n) _Pragma("unroll") for (int k = 0; k < 2; ++k) \
;         acc[ai][bj][m][n] = __builtin_amdgcn_mfma_f32_16x16x32_bf16(Bt[n][k], At[m][k], acc[ai][bj][m][n], 0, 0, 0); __builtin_amdgcn_s_setprio(0); } while (0)
; #define PG8_WAIT_V(n) asm volatile("s_waitcnt vmcnt(" #n ")" ::: "memory")
; template <class Epi, class Sched, bool ALIGN_EPI = false, bool SP2 = false>
; __device__ __forceinline__ void gemm_phase(PG8_LAS unsigned char* lds, const Gemm g, const Sched& S, const Epi& E) {
;     ...
;             PG8_LDB(B0, 0, 0); PG8_LDB(B1, 0, 1); PG8_SCHED; PG8_LDA(At, 0, 0); PG8_STAGE(PG8_SA(1, 1), a1 + hstepA, voffA);
;             PG8_WAIT_V(8); PG8_WAIT_L(0); PG8_BAR; PG8_MMA(0, 0, At, B0); PG8_MMA(0, 1, At, B1); PG8_BAR; PG8_SCHED;
;             PG8_LDA(At, 0, 1); PG8_STAGE(PG8_SB(0, 0), b2, voffB); PG8_STAGE(PG8_SB(0, 1), b2 + hstepB, voffB); PG8_STAGE(PG8_SA(0, 0), a2, voffA);
;             PG8_WAIT_V(8); PG8_WAIT_L(0); PG8_BAR; PG8_MMA(1, 0, At, B0); PG8_MMA(1, 1, At, B1); PG8_BAR; PG8_SCHED;
;             PG8_LDB(B0, 1, 0); PG8_LDB(B1, 1, 1); PG8_SCHED; PG8_LDA(At, 1, 0); PG8_STAGE(PG8_SA(0, 1), a2 + hstepA, voffA);
;             PG8_WAIT_V(8); PG8_WAIT_L(0); PG8_BAR; PG8_MMA(0, 0, At, B0); PG8_MMA(0, 1, At, B1); PG8_BAR; PG8_SCHED;
;             PG8_LDA(At, 1, 1); PG8_STAGE(PG8_SB(1, 0), b3, voffB); PG8_STAGE(PG8_SB(1, 1), b3 + hstepB, voffB); PG8_STAGE(PG8_SA(1, 0), a3, voffA);
;             PG8_WAIT_V(8); PG8_WAIT_L(0); PG8_BAR; PG8_MMA(1, 0, At, B0); PG8_MMA(1, 1, At, B1); PG8_BAR; PG8_SCHED;
	v_mfma_f32_16x16x32_bf16 v[54:57], v[180:183], v[196:199], v[54:57]
	v_mfma_f32_16x16x32_bf16 v[46:49], v[188:191], v[196:199], v[46:49]
	v_mfma_f32_16x16x32_bf16 v[38:41], v[180:183], v[204:207], v[38:41]
	v_mfma_f32_16x16x32_bf16 v[30:33], v[188:191], v[204:207], v[30:33]
	v_mfma_f32_16x16x32_bf16 v[22:25], v[180:183], v[212:215], v[22:25]
	v_mfma_f32_16x16x32_bf16 v[18:21], v[188:191], v[212:215], v[18:21]
	v_mfma_f32_16x16x32_bf16 v[6:9], v[180:183], v[220:223], v[6:9]
	v_mfma_f32_16x16x32_bf16 v[2:5], v[188:191], v[220:223], v[2:5]
	s_setprio 0
	s_add_i32 s56, 0, 0x18000
	v_add_u32_e32 v148, s56, v151
	s_add_i32 s57, 0, 0x1c000
	ds_read_b128 v[158:161], v148
	ds_read_b128 v[164:167], v148 offset:1024
	ds_read_b128 v[168:171], v148 offset:2048
	ds_read_b128 v[172:175], v148 offset:3072
	v_add_u32_e32 v148, s57, v151
	ds_read_b128 v[176:179], v148
	ds_read_b128 v[180:183], v148 offset:1024
	ds_read_b128 v[184:187], v148 offset:2048
	ds_read_b128 v[188:191], v148 offset:3072
	s_add_u32 s28, s28, 0x100000
	s_addc_u32 s29, s29, 0
	s_mov_b32 m0, s36
	v_lshl_add_u64 v[230:231], s[28:29], 0, v[136:137]
	ds_read_b128 v[192:195], v157 offset:32768
	ds_read_b128 v[196:199], v157 offset:33792
	ds_read_b128 v[200:203], v157 offset:34816
	ds_read_b128 v[204:207], v157 offset:35840
	ds_read_b128 v[208:211], v157 offset:36864
	ds_read_b128 v[212:215], v157 offset:37888
	ds_read_b128 v[216:219], v157 offset:38912
	ds_read_b128 v[220:223], v157 offset:39936
	global_load_lds_dwordx4 v[230:231], off
	v_lshl_add_u64 v[230:231], s[28:29], 0, v[132:133]
	s_mov_b32 m0, s37
	s_nop 0
	global_load_lds_dwordx4 v[230:231], off
	s_waitcnt vmcnt(8)
	s_waitcnt lgkmcnt(0)
	s_barrier
	s_setprio 2
	s_waitcnt lgkmcnt(0)
	v_mfma_f32_16x16x32_bf16 v[126:129], v[158:161], v[192:195], v[126:129]
	v_mfma_f32_16x16x32_bf16 v[122:125], v[168:171], v[192:195], v[122:125]
	v_mfma_f32_16x16x32_bf16 v[114:117], v[158:161], v[200:203], v[114:117]
	v_mfma_f32_16x16x32_bf16 v[106:109], v[168:171], v[200:203], v[106:109]
	v_mfma_f32_16x16x32_bf16 v[98:101], v[158:161], v[208:211], v[98:101]
	v_mfma_f32_16x16x32_bf16 v[90:93], v[168:171], v[208:211], v[90:93]
	v_mfma_f32_16x16x32_bf16 v[82:85], v[158:161], v[216:219], v[82:85]
	v_mfma_f32_16x16x32_bf16 v[74:77], v[168:171], v[216:219], v[74:77]
	v_mfma_f32_16x16x32_bf16 v[126:129], v[164:167], v[196:199], v[126:129]
	v_mfma_f32_16x16x32_bf16 v[122:125], v[172:175], v[196:199], v[122:125]
	v_mfma_f32_16x16x32_bf16 v[114:117], v[164:167], v[204:207], v[114:117]
	v_mfma_f32_16x16x32_bf16 v[106:109], v[172:175], v[204:207], v[106:109]
	v_mfma_f32_16x16x32_bf16 v[98:101], v[164:167], v[212:215], v[98:101]
	v_mfma_f32_16x16x32_bf16 v[90:93], v[172:175], v[212:215], v[90:93]
	v_mfma_f32_16x16x32_bf16 v[82:85], v[164:167], v[220:223], v[82:85]
	v_mfma_f32_16x16x32_bf16 v[74:77], v[172:175], v[220:223], v[74:77]
	v_mfma_f32_16x16x32_bf16 v[118:121], v[176:179], v[192:195], v[118:121]
	v_mfma_f32_16x16x32_bf16 v[110:113], v[184:187], v[192:195], v[110:113]
	v_mfma_f32_16x16x32_bf16 v[102:105], v[176:179], v[200:203], v[102:105]
	v_mfma_f32_16x16x32_bf16 v[94:97], v[184:187], v[200:203], v[94:97]
	v_mfma_f32_16x16x32_bf16 v[86:89], v[176:179], v[208:211], v[86:89]
	v_mfma_f32_16x16x32_bf16 v[78:81], v[184:187], v[208:211], v[78:81]
	v_mfma_f32_16x16x32_bf16 v[70:73], v[176:179], v[216:219], v[70:73]
	v_mfma_f32_16x16x32_bf16 v[66:69], v[184:187], v[216:219], v[66:69]
	s_setprio 3
	s_barrier
; #define PG8_STAGE(bufoff, gbase, voff) do { _Pragma("unroll") for (int _i = 0; _i < 2; ++_i) \
;         __builtin_amdgcn_global_load_lds((const unsigned*)((const char*)(gbase) + (voff)[_i]), (PG8_LAS unsigned*)(lds + (bufoff) + ldsw + _i * 8192), 16, 0, 0); } while (0)
; #define PG8_LDA(dst, b, h) do { _Pragma("unroll") for (int m = 0; m < 4; ++m) _Pragma("unroll") for (int k = 0; k < 2; ++k) dst[m][k] = *(const PG8_LAS bf16x8*)(lds + PG8_SA(b, h) + aoff + m * 2048 + k * 1024); } while (0)
; #define PG8_LDB(dst, b, h) do { _Pragma("unroll") for (int n = 0; n < 2; ++n) _Pragma("unroll") for (int k = 0; k < 2; ++k) dst[n][k] = *(const PG8_LAS bf16x8*)(lds + PG8_SB(b, h) + boff + n * 2048 + k * 1024); } while (0)
; #define PG8_MMA(ai, bj, At, Bt) do { __builtin_amdgcn_s_setprio(3); _Pragma("unroll") for (int m = 0; m < 4; ++m) _Pragma("unroll") for (int n = 0; n < 2; ++n) _Pragma("unroll") for (int k = 0; k < 2; ++k) \
;         acc[ai][bj][m][n] = __builtin_amdgcn_mfma_f32_16x16x32_bf16(Bt[n][k], At[m][k], acc[ai][bj][m][n], 0, 0, 0); __builtin_amdgcn_s_setprio(0); } while (0)
; #define PG8_WAIT_V(n) asm volatile("s_waitcnt vmcnt(" #n ")" ::: "memory")
; #define PG8_WAIT_L(n) asm volatile("s_waitcnt lgkmcnt(" #n ")" ::: "memory")
; #define PG8_BAR __builtin_amdgcn_s_barrier()
; #define PG8_SCHED __builtin_amdgcn_sched_barrier(0)
; template <class Epi, class Sched, bool ALIGN_EPI = false, bool SP2 = false>
; __device__ __forceinline__ void gemm_phase(PG8_LAS unsigned char* lds, const Gemm g, const Sched& S, const Epi& E) {
;     ...
;             PG8_LDB(B0, 1, 0); PG8_LDB(B1, 1, 1); PG8_SCHED; PG8_LDA(At, 1, 0); PG8_STAGE(PG8_SA(0, 1), a2 + hstepA, voffA);
;             PG8_WAIT_V(8); PG8_WAIT_L(0); PG8_BAR; PG8_MMA(0, 0, At, B0); PG8_MMA(0, 1, At, B1); PG8_BAR; PG8_SCHED;
;             PG8_LDA(At, 1, 1); PG8_STAGE(PG8_SB(1, 0), b3, voffB); PG8_STAGE(PG8_SB(1, 1), b3 + hstepB, voffB); PG8_STAGE(PG8_SA(1, 0), a3, voffA);
;             PG8_WAIT_V(8); PG8_WAIT_L(0); PG8_BAR; PG8_MMA(1, 0, At, B0); PG8_MMA(1, 1, At, B1); PG8_BAR; PG8_SCHED;
;     ...
;         if constexpr (ALIGN_EPI) { if (wr == 0) PG8_BAR; }
	v_mfma_f32_16x16x32_bf16 v[118:121], v[180:183], v[196:199], v[118:121]
	v_mfma_f32_16x16x32_bf16 v[110:113], v[188:191], v[196:199], v[110:113]
	v_mfma_f32_16x16x32_bf16 v[102:105], v[180:183], v[204:207], v[102:105]
	v_mfma_f32_16x16x32_bf16 v[94:97], v[188:191], v[204:207], v[94:97]
	v_mfma_f32_16x16x32_bf16 v[86:89], v[180:183], v[212:215], v[86:89]
	v_mfma_f32_16x16x32_bf16 v[78:81], v[188:191], v[212:215], v[78:81]
	v_mfma_f32_16x16x32_bf16 v[70:73], v[180:183], v[220:223], v[70:73]
	v_mfma_f32_16x16x32_bf16 v[66:69], v[188:191], v[220:223], v[66:69]
	s_setprio 0
	s_add_i32 s28, s56, s30
	v_lshl_add_u64 v[146:147], v[146:147], 0, s[12:13]
	s_mov_b32 m0, s28
	ds_read_b128 v[192:195], v157 offset:49152
	ds_read_b128 v[196:199], v157 offset:50176
	ds_read_b128 v[200:203], v157 offset:51200
	ds_read_b128 v[204:207], v157 offset:52224
	ds_read_b128 v[208:211], v157 offset:53248
	ds_read_b128 v[212:215], v157 offset:54272
	ds_read_b128 v[216:219], v157 offset:55296
	ds_read_b128 v[220:223], v157 offset:56320
	global_load_lds_dwordx4 v[146:147], off
	s_add_i32 m0, s28, 0x2000
	s_add_u32 s26, s26, 0x100080
	v_lshl_add_u64 v[146:147], v[224:225], 0, s[12:13]
	s_addc_u32 s27, s27, 0
	s_add_i32 s28, s57, s30
	global_load_lds_dwordx4 v[146:147], off
	v_lshl_add_u64 v[146:147], s[26:27], 0, v[134:135]
	s_mov_b32 m0, s28
	s_nop 0
	global_load_lds_dwordx4 v[146:147], off
	v_lshl_add_u64 v[146:147], s[26:27], 0, v[130:131]
	s_add_i32 m0, s28, 0x2000
	s_nop 0
	global_load_lds_dwordx4 v[146:147], off
	v_lshl_add_u64 v[146:147], v[226:227], 0, s[12:13]
	s_mov_b32 m0, s39
	s_nop 0
	global_load_lds_dwordx4 v[146:147], off
	v_lshl_add_u64 v[146:147], v[228:229], 0, s[12:13]
	s_mov_b32 m0, s40
	s_nop 0
	global_load_lds_dwordx4 v[146:147], off
	s_waitcnt vmcnt(8)
	s_waitcnt lgkmcnt(0)
	s_barrier
	s_setprio 2
	s_waitcnt lgkmcnt(0)
	v_mfma_f32_16x16x32_bf16 v[62:65], v[158:161], v[192:195], v[62:65]
	v_mfma_f32_16x16x32_bf16 v[58:61], v[168:171], v[192:195], v[58:61]
	v_mfma_f32_16x16x32_bf16 v[50:53], v[158:161], v[200:203], v[50:53]
	v_mfma_f32_16x16x32_bf16 v[42:45], v[168:171], v[200:203], v[42:45]
	v_mfma_f32_16x16x32_bf16 v[34:37], v[158:161], v[208:211], v[34:37]
	v_mfma_f32_16x16x32_bf16 v[26:29], v[168:171], v[208:211], v[26:29]
	v_mfma_f32_16x16x32_bf16 v[14:17], v[158:161], v[216:219], v[14:17]
	v_mfma_f32_16x16x32_bf16 v[10:13], v[168:171], v[216:219], v[10:13]
	v_mfma_f32_16x16x32_bf16 v[62:65], v[164:167], v[196:199], v[62:65]
	v_mfma_f32_16x16x32_bf16 v[58:61], v[172:175], v[196:199], v[58:61]
	v_mfma_f32_16x16x32_bf16 v[50:53], v[164:167], v[204:207], v[50:53]
	v_mfma_f32_16x16x32_bf16 v[42:45], v[172:175], v[204:207], v[42:45]
	v_mfma_f32_16x16x32_bf16 v[34:37], v[164:167], v[212:215], v[34:37]
	v_mfma_f32_16x16x32_bf16 v[26:29], v[172:175], v[212:215], v[26:29]
	v_mfma_f32_16x16x32_bf16 v[14:17], v[164:167], v[220:223], v[14:17]
	v_mfma_f32_16x16x32_bf16 v[10:13], v[172:175], v[220:223], v[10:13]
	v_mfma_f32_16x16x32_bf16 v[54:57], v[176:179], v[192:195], v[54:57]
	v_mfma_f32_16x16x32_bf16 v[46:49], v[184:187], v[192:195], v[46:49]
	v_mfma_f32_16x16x32_bf16 v[38:41], v[176:179], v[200:203], v[38:41]
	v_mfma_f32_16x16x32_bf16 v[30:33], v[184:187], v[200:203], v[30:33]
	v_mfma_f32_16x16x32_bf16 v[22:25], v[176:179], v[208:211], v[22:25]
	v_mfma_f32_16x16x32_bf16 v[18:21], v[184:187], v[208:211], v[18:21]
	v_mfma_f32_16x16x32_bf16 v[6:9], v[176:179], v[216:219], v[6:9]
	v_mfma_f32_16x16x32_bf16 v[2:5], v[184:187], v[216:219], v[2:5]
	s_setprio 3
	s_barrier
	v_mfma_f32_16x16x32_bf16 v[54:57], v[180:183], v[196:199], v[54:57]
	v_mfma_f32_16x16x32_bf16 v[46:49], v[188:191], v[196:199], v[46:49]
	v_mfma_f32_16x16x32_bf16 v[38:41], v[180:183], v[204:207], v[38:41]
	v_mfma_f32_16x16x32_bf16 v[30:33], v[188:191], v[204:207], v[30:33]
	v_mfma_f32_16x16x32_bf16 v[22:25], v[180:183], v[212:215], v[22:25]
	v_mfma_f32_16x16x32_bf16 v[18:21], v[188:191], v[212:215], v[18:21]
	v_mfma_f32_16x16x32_bf16 v[6:9], v[180:183], v[220:223], v[6:9]
	v_mfma_f32_16x16x32_bf16 v[2:5], v[188:191], v[220:223], v[2:5]
	s_setprio 0
	s_add_i32 s55, s55, 2
	s_add_u32 s24, s24, 0x100
	s_addc_u32 s25, s25, 0
	s_add_u32 s53, s53, 0x100
	s_addc_u32 s54, s54, 0
	s_cmp_gt_u32 s55, 61
	s_cbranch_scc0 .LBB0_908
	s_and_b64 vcc, exec, s[0:1]
	s_cbranch_vccz .LBB0_911
	s_barrier

; #define PG8_STAGE(bufoff, gbase, voff) do { _Pragma("unroll") for (int _i = 0; _i < 2; ++_i) \
;         __builtin_amdgcn_global_load_lds((const unsigned*)((const char*)(gbase) + (voff)[_i]), (PG8_LAS unsigned*)(lds + (bufoff) + ldsw + _i * 8192), 16, 0, 0); } while (0)
; #define PG8_LDA(dst, b, h) do { _Pragma("unroll") for (int m = 0; m < 4; ++m) _Pragma("unroll") for (int k = 0; k < 2; ++k) dst[m][k] = *(const PG8_LAS bf16x8*)(lds + PG8_SA(b, h) + aoff + m * 2048 + k * 1024); } while (0)
; #define PG8_LDB(dst, b, h) do { _Pragma("unroll") for (int n = 0; n < 2; ++n) _Pragma("unroll") for (int k = 0; k < 2; ++k) dst[n][k] = *(const PG8_LAS bf16x8*)(lds + PG8_SB(b, h) + boff + n * 2048 + k * 1024); } while (0)
; #define PG8_MMA(ai, bj, At, Bt) do { __builtin_amdgcn_s_setprio(3); _Pragma("unroll") for (int m = 0; m < 4; ++m) _Pragma("unroll") for (int n = 0; n < 2; ++n) _Pragma("unroll") for (int k = 0; k < 2; ++k) \
;         acc[ai][bj][m][n] = __builtin_amdgcn_mfma_f32_16x16x32_bf16(Bt[n][k], At[m][k], acc[ai][bj][m][n], 0, 0, 0); __builtin_amdgcn_s_setprio(0); } while (0)
; #define PG8_WAIT_V(n) asm volatile("s_waitcnt vmcnt(" #n ")" ::: "memory")
; template <class Epi, class Sched, bool ALIGN_EPI = false, bool SP2 = false>
; __device__ __forceinline__ void gemm_phase(PG8_LAS unsigned char* lds, const Gemm g, const Sched& S, const Epi& E) {
;     ...
;             PG8_LDB(B0, 0, 0); PG8_LDB(B1, 0, 1); PG8_SCHED; PG8_LDA(At, 0, 0); PG8_STAGE(PG8_SA(1, 1), a1 + hstepA, voffA);
;             PG8_WAIT_V(8); PG8_WAIT_L(0); PG8_BAR; PG8_MMA(0, 0, At, B0); PG8_MMA(0, 1, At, B1); PG8_BAR; PG8_SCHED;
;             PG8_LDA(At, 0, 1); PG8_STAGE(PG8_SB(0, 0), b2, voffB); PG8_STAGE(PG8_SB(0, 1), b2 + hstepB, voffB); PG8_STAGE(PG8_SA(0, 0), a2, voffA);
;             PG8_WAIT_V(8); PG8_WAIT_L(0); PG8_BAR; PG8_MMA(1, 0, At, B0); PG8_MMA(1, 1, At, B1); PG8_BAR; PG8_SCHED;
;             PG8_LDB(B0, 1, 0); PG8_LDB(B1, 1, 1); PG8_SCHED; PG8_LDA(At, 1, 0); PG8_STAGE(PG8_SA(0, 1), a2 + hstepA, voffA);
;             PG8_WAIT_V(8); PG8_WAIT_L(0); PG8_BAR; PG8_MMA(0, 0, At, B0); PG8_MMA(0, 1, At, B1); PG8_BAR; PG8_SCHED;
;             PG8_LDA(At, 1, 1); PG8_STAGE(PG8_SB(1, 0), b3, voffB); PG8_STAGE(PG8_SB(1, 1), b3 + hstepB, voffB); PG8_STAGE(PG8_SA(1, 0), a3, voffA);
;             PG8_WAIT_V(8); PG8_WAIT_L(0); PG8_BAR; PG8_MMA(1, 0, At, B0); PG8_MMA(1, 1, At, B1); PG8_BAR; PG8_SCHED;
.LBB0_975:
	v_add_u32_e32 v144, s46, v206
	v_add_u32_e32 v160, s47, v206
	s_add_u32 s28, s2, s12
	ds_read_b128 v[132:135], v144
	ds_read_b128 v[136:139], v144 offset:1024
	ds_read_b128 v[140:143], v144 offset:2048
	ds_read_b128 v[144:147], v144 offset:3072
	ds_read_b128 v[148:151], v160
	ds_read_b128 v[152:155], v160 offset:1024
	ds_read_b128 v[156:159], v160 offset:2048
	ds_read_b128 v[160:163], v160 offset:3072
	s_addc_u32 s29, s3, s13
	s_add_u32 s28, s28, 0x21500100
	s_addc_u32 s29, s29, 0
	s_add_u32 s81, s44, s12
	s_addc_u32 s82, s45, s13
	s_cmpk_eq_i32 s12, 0x5500
	s_cselect_b32 s31, s1, s29
	s_cselect_b32 s30, s0, s28
	s_cselect_b32 s29, s11, s82
	s_cselect_b32 s28, s10, s81
	s_mov_b32 m0, s71
	v_lshl_add_u64 v[234:235], v[2:3], 0, s[12:13]
	ds_read_b128 v[164:167], v207
	ds_read_b128 v[168:171], v207 offset:1024
	ds_read_b128 v[210:213], v207 offset:2048
	ds_read_b128 v[214:217], v207 offset:3072
	ds_read_b128 v[218:221], v207 offset:4096
	ds_read_b128 v[222:225], v207 offset:5120
	ds_read_b128 v[226:229], v207 offset:6144
	ds_read_b128 v[230:233], v207 offset:7168
	global_load_lds_dwordx4 v[234:235], off
	v_lshl_add_u64 v[234:235], v[200:201], 0, s[12:13]
	s_mov_b32 m0, s72
	s_nop 0
	global_load_lds_dwordx4 v[234:235], off
	s_waitcnt vmcnt(8)
	s_waitcnt lgkmcnt(0)
	s_barrier
	s_setprio 2
	s_waitcnt lgkmcnt(0)
	v_mfma_f32_16x16x32_bf16 v[128:131], v[132:135], v[164:167], v[128:131]
	v_mfma_f32_16x16x32_bf16 v[124:127], v[140:143], v[164:167], v[124:127]
	v_mfma_f32_16x16x32_bf16 v[100:103], v[132:135], v[210:213], v[100:103]
	v_mfma_f32_16x16x32_bf16 v[96:99], v[140:143], v[210:213], v[96:99]
	v_mfma_f32_16x16x32_bf16 v[112:115], v[132:135], v[218:221], v[112:115]
	v_mfma_f32_16x16x32_bf16 v[108:111], v[140:143], v[218:221], v[108:111]
	v_mfma_f32_16x16x32_bf16 v[80:83], v[132:135], v[226:229], v[80:83]
	v_mfma_f32_16x16x32_bf16 v[76:79], v[140:143], v[226:229], v[76:79]
	v_mfma_f32_16x16x32_bf16 v[128:131], v[136:139], v[168:171], v[128:131]
	v_mfma_f32_16x16x32_bf16 v[124:127], v[144:147], v[168:171], v[124:127]
	v_mfma_f32_16x16x32_bf16 v[100:103], v[136:139], v[214:217], v[100:103]
	v_mfma_f32_16x16x32_bf16 v[96:99], v[144:147], v[214:217], v[96:99]
	v_mfma_f32_16x16x32_bf16 v[112:115], v[136:139], v[222:225], v[112:115]
	v_mfma_f32_16x16x32_bf16 v[108:111], v[144:147], v[222:225], v[108:111]
	v_mfma_f32_16x16x32_bf16 v[80:83], v[136:139], v[230:233], v[80:83]
	v_mfma_f32_16x16x32_bf16 v[76:79], v[144:147], v[230:233], v[76:79]
	v_mfma_f32_16x16x32_bf16 v[120:123], v[148:151], v[164:167], v[120:123]
	v_mfma_f32_16x16x32_bf16 v[116:119], v[156:159], v[164:167], v[116:119]
	v_mfma_f32_16x16x32_bf16 v[92:95], v[148:151], v[210:213], v[92:95]
	v_mfma_f32_16x16x32_bf16 v[88:91], v[156:159], v[210:213], v[88:91]
	v_mfma_f32_16x16x32_bf16 v[104:107], v[148:151], v[218:221], v[104:107]
	v_mfma_f32_16x16x32_bf16 v[84:87], v[156:159], v[218:221], v[84:87]
	v_mfma_f32_16x16x32_bf16 v[72:75], v[148:151], v[226:229], v[72:75]
	v_mfma_f32_16x16x32_bf16 v[68:71], v[156:159], v[226:229], v[68:71]
	s_setprio 3
	s_barrier
	v_mfma_f32_16x16x32_bf16 v[120:123], v[152:155], v[168:171], v[120:123]
	v_mfma_f32_16x16x32_bf16 v[116:119], v[160:163], v[168:171], v[116:119]
	v_mfma_f32_16x16x32_bf16 v[92:95], v[152:155], v[214:217], v[92:95]
	v_mfma_f32_16x16x32_bf16 v[88:91], v[160:163], v[214:217], v[88:91]
	v_mfma_f32_16x16x32_bf16 v[104:107], v[152:155], v[222:225], v[104:107]
	v_mfma_f32_16x16x32_bf16 v[84:87], v[160:163], v[222:225], v[84:87]
	v_mfma_f32_16x16x32_bf16 v[72:75], v[152:155], v[230:233], v[72:75]
	v_mfma_f32_16x16x32_bf16 v[68:71], v[160:163], v[230:233], v[68:71]
	s_setprio 0
	s_mov_b32 m0, s73
	v_lshl_add_u64 v[234:235], s[28:29], 0, v[174:175]
	s_add_u32 s82, s28, 0x2b0000
	ds_read_b128 v[164:167], v207 offset:16384
	ds_read_b128 v[168:171], v207 offset:17408
	ds_read_b128 v[210:213], v207 offset:18432
	ds_read_b128 v[214:217], v207 offset:19456
	ds_read_b128 v[218:221], v207 offset:20480
	ds_read_b128 v[222:225], v207 offset:21504
	ds_read_b128 v[226:229], v207 offset:22528
	ds_read_b128 v[230:233], v207 offset:23552
	global_load_lds_dwordx4 v[234:235], off
	v_lshl_add_u64 v[236:237], s[28:29], 0, v[178:179]
	s_mov_b32 m0, s74
	s_addc_u32 s83, s29, 0
	global_load_lds_dwordx4 v[236:237], off
	v_lshl_add_u64 v[238:239], s[82:83], 0, v[174:175]
	s_mov_b32 m0, s75
	v_lshl_add_u64 v[240:241], s[30:31], 0, v[176:177]
	global_load_lds_dwordx4 v[238:239], off
	v_lshl_add_u64 v[238:239], s[82:83], 0, v[178:179]
	s_mov_b32 m0, s76
	s_nop 0
	global_load_lds_dwordx4 v[238:239], off
	v_lshl_add_u64 v[238:239], s[30:31], 0, v[172:173]
	s_mov_b32 m0, s42
	s_nop 0
	global_load_lds_dwordx4 v[238:239], off
	s_mov_b32 m0, s54
	s_nop 0
	global_load_lds_dwordx4 v[240:241], off
	s_waitcnt vmcnt(8)
	s_waitcnt lgkmcnt(0)
	s_barrier
; #define PG8_STAGE(bufoff, gbase, voff) do { _Pragma("unroll") for (int _i = 0; _i < 2; ++_i) \
;         __builtin_amdgcn_global_load_lds((const unsigned*)((const char*)(gbase) + (voff)[_i]), (PG8_LAS unsigned*)(lds + (bufoff) + ldsw + _i * 8192), 16, 0, 0); } while (0)
; #define PG8_LDA(dst, b, h) do { _Pragma("unroll") for (int m = 0; m < 4; ++m) _Pragma("unroll") for (int k = 0; k < 2; ++k) dst[m][k] = *(const PG8_LAS bf16x8*)(lds + PG8_SA(b, h) + aoff + m * 2048 + k * 1024); } while (0)
; #define PG8_LDB(dst, b, h) do { _Pragma("unroll") for (int n = 0; n < 2; ++n) _Pragma("unroll") for (int k = 0; k < 2; ++k) dst[n][k] = *(const PG8_LAS bf16x8*)(lds + PG8_SB(b, h) + boff + n * 2048 + k * 1024); } while (0)
; #define PG8_MMA(ai, bj, At, Bt) do { __builtin_amdgcn_s_setprio(3); _Pragma("unroll") for (int m = 0; m < 4; ++m) _Pragma("unroll") for (int n = 0; n < 2; ++n) _Pragma("unroll") for (int k = 0; k < 2; ++k) \
;         acc[ai][bj][m][n] = __builtin_amdgcn_mfma_f32_16x16x32_bf16(Bt[n][k], At[m][k], acc[ai][bj][m][n], 0, 0, 0); __builtin_amdgcn_s_setprio(0); } while (0)
; #define PG8_WAIT_V(n) asm volatile("s_waitcnt vmcnt(" #n ")" ::: "memory")
; template <class Epi, class Sched, bool ALIGN_EPI = false, bool SP2 = false>
; __device__ __forceinline__ void gemm_phase(PG8_LAS unsigned char* lds, const Gemm g, const Sched& S, const Epi& E) {
;     ...
;             PG8_LDB(B0, 0, 0); PG8_LDB(B1, 0, 1); PG8_SCHED; PG8_LDA(At, 0, 0); PG8_STAGE(PG8_SA(1, 1), a1 + hstepA, voffA);
;             PG8_WAIT_V(8); PG8_WAIT_L(0); PG8_BAR; PG8_MMA(0, 0, At, B0); PG8_MMA(0, 1, At, B1); PG8_BAR; PG8_SCHED;
;             PG8_LDA(At, 0, 1); PG8_STAGE(PG8_SB(0, 0), b2, voffB); PG8_STAGE(PG8_SB(0, 1), b2 + hstepB, voffB); PG8_STAGE(PG8_SA(0, 0), a2, voffA);
;             PG8_WAIT_V(8); PG8_WAIT_L(0); PG8_BAR; PG8_MMA(1, 0, At, B0); PG8_MMA(1, 1, At, B1); PG8_BAR; PG8_SCHED;
;             PG8_LDB(B0, 1, 0); PG8_LDB(B1, 1, 1); PG8_SCHED; PG8_LDA(At, 1, 0); PG8_STAGE(PG8_SA(0, 1), a2 + hstepA, voffA);
;             PG8_WAIT_V(8); PG8_WAIT_L(0); PG8_BAR; PG8_MMA(0, 0, At, B0); PG8_MMA(0, 1, At, B1); PG8_BAR; PG8_SCHED;
;             PG8_LDA(At, 1, 1); PG8_STAGE(PG8_SB(1, 0), b3, voffB); PG8_STAGE(PG8_SB(1, 1), b3 + hstepB, voffB); PG8_STAGE(PG8_SA(1, 0), a3, voffA);
;             PG8_WAIT_V(8); PG8_WAIT_L(0); PG8_BAR; PG8_MMA(1, 0, At, B0); PG8_MMA(1, 1, At, B1); PG8_BAR; PG8_SCHED;
	s_setprio 2
	s_waitcnt lgkmcnt(0)
	v_mfma_f32_16x16x32_bf16 v[64:67], v[132:135], v[164:167], v[64:67]
	v_mfma_f32_16x16x32_bf16 v[60:63], v[140:143], v[164:167], v[60:63]
	v_mfma_f32_16x16x32_bf16 v[48:51], v[132:135], v[210:213], v[48:51]
	v_mfma_f32_16x16x32_bf16 v[44:47], v[140:143], v[210:213], v[44:47]
	v_mfma_f32_16x16x32_bf16 v[32:35], v[132:135], v[218:221], v[32:35]
	v_mfma_f32_16x16x32_bf16 v[28:31], v[140:143], v[218:221], v[28:31]
	v_mfma_f32_16x16x32_bf16 v[16:19], v[132:135], v[226:229], v[16:19]
	v_mfma_f32_16x16x32_bf16 v[12:15], v[140:143], v[226:229], v[12:15]
	v_mfma_f32_16x16x32_bf16 v[64:67], v[136:139], v[168:171], v[64:67]
	v_mfma_f32_16x16x32_bf16 v[60:63], v[144:147], v[168:171], v[60:63]
	v_mfma_f32_16x16x32_bf16 v[48:51], v[136:139], v[214:217], v[48:51]
	v_mfma_f32_16x16x32_bf16 v[44:47], v[144:147], v[214:217], v[44:47]
	v_mfma_f32_16x16x32_bf16 v[32:35], v[136:139], v[222:225], v[32:35]
	v_mfma_f32_16x16x32_bf16 v[28:31], v[144:147], v[222:225], v[28:31]
	v_mfma_f32_16x16x32_bf16 v[16:19], v[136:139], v[230:233], v[16:19]
	v_mfma_f32_16x16x32_bf16 v[12:15], v[144:147], v[230:233], v[12:15]
	v_mfma_f32_16x16x32_bf16 v[56:59], v[148:151], v[164:167], v[56:59]
	v_mfma_f32_16x16x32_bf16 v[52:55], v[156:159], v[164:167], v[52:55]
	v_mfma_f32_16x16x32_bf16 v[40:43], v[148:151], v[210:213], v[40:43]
	v_mfma_f32_16x16x32_bf16 v[36:39], v[156:159], v[210:213], v[36:39]
	v_mfma_f32_16x16x32_bf16 v[24:27], v[148:151], v[218:221], v[24:27]
	v_mfma_f32_16x16x32_bf16 v[20:23], v[156:159], v[218:221], v[20:23]
	v_mfma_f32_16x16x32_bf16 v[8:11], v[148:151], v[226:229], v[8:11]
	v_mfma_f32_16x16x32_bf16 v[4:7], v[156:159], v[226:229], v[4:7]
	s_setprio 3
	s_barrier
	v_mfma_f32_16x16x32_bf16 v[56:59], v[152:155], v[168:171], v[56:59]
	v_mfma_f32_16x16x32_bf16 v[52:55], v[160:163], v[168:171], v[52:55]
	v_mfma_f32_16x16x32_bf16 v[40:43], v[152:155], v[214:217], v[40:43]
	v_mfma_f32_16x16x32_bf16 v[36:39], v[160:163], v[214:217], v[36:39]
	v_mfma_f32_16x16x32_bf16 v[24:27], v[152:155], v[222:225], v[24:27]
	v_mfma_f32_16x16x32_bf16 v[20:23], v[160:163], v[222:225], v[20:23]
	v_mfma_f32_16x16x32_bf16 v[8:11], v[152:155], v[230:233], v[8:11]
	v_mfma_f32_16x16x32_bf16 v[4:7], v[160:163], v[230:233], v[4:7]
	s_setprio 0
	v_add_u32_e32 v144, s52, v206
	v_add_u32_e32 v160, s53, v206
	ds_read_b128 v[132:135], v144
	ds_read_b128 v[136:139], v144 offset:1024
	ds_read_b128 v[140:143], v144 offset:2048
	ds_read_b128 v[144:147], v144 offset:3072
	ds_read_b128 v[148:151], v160
	ds_read_b128 v[152:155], v160 offset:1024
	ds_read_b128 v[156:159], v160 offset:2048
	ds_read_b128 v[160:163], v160 offset:3072
	s_add_u32 s30, s30, 0x2b0000
	s_addc_u32 s31, s31, 0
	s_mov_b32 m0, s55
	v_lshl_add_u64 v[242:243], s[30:31], 0, v[172:173]
	ds_read_b128 v[164:167], v207 offset:32768
	ds_read_b128 v[168:171], v207 offset:33792
	ds_read_b128 v[210:213], v207 offset:34816
	ds_read_b128 v[214:217], v207 offset:35840
	ds_read_b128 v[218:221], v207 offset:36864
	ds_read_b128 v[222:225], v207 offset:37888
	ds_read_b128 v[226:229], v207 offset:38912
	ds_read_b128 v[230:233], v207 offset:39936
	global_load_lds_dwordx4 v[242:243], off
	v_lshl_add_u64 v[242:243], s[30:31], 0, v[176:177]
	s_mov_b32 m0, s56
	s_nop 0
	global_load_lds_dwordx4 v[242:243], off
	s_waitcnt vmcnt(8)
	s_waitcnt lgkmcnt(0)
	s_barrier
	s_setprio 2
	s_waitcnt lgkmcnt(0)
	v_mfma_f32_16x16x32_bf16 v[128:131], v[132:135], v[164:167], v[128:131]
	v_mfma_f32_16x16x32_bf16 v[124:127], v[140:143], v[164:167], v[124:127]
	v_mfma_f32_16x16x32_bf16 v[100:103], v[132:135], v[210:213], v[100:103]
	v_mfma_f32_16x16x32_bf16 v[96:99], v[140:143], v[210:213], v[96:99]
	v_mfma_f32_16x16x32_bf16 v[112:115], v[132:135], v[218:221], v[112:115]
	v_mfma_f32_16x16x32_bf16 v[108:111], v[140:143], v[218:221], v[108:111]
	v_mfma_f32_16x16x32_bf16 v[80:83], v[132:135], v[226:229], v[80:83]
	v_mfma_f32_16x16x32_bf16 v[76:79], v[140:143], v[226:229], v[76:79]
	v_mfma_f32_16x16x32_bf16 v[128:131], v[136:139], v[168:171], v[128:131]
	v_mfma_f32_16x16x32_bf16 v[124:127], v[144:147], v[168:171], v[124:127]
	v_mfma_f32_16x16x32_bf16 v[100:103], v[136:139], v[214:217], v[100:103]
	v_mfma_f32_16x16x32_bf16 v[96:99], v[144:147], v[214:217], v[96:99]
	v_mfma_f32_16x16x32_bf16 v[112:115], v[136:139], v[222:225], v[112:115]
	v_mfma_f32_16x16x32_bf16 v[108:111], v[144:147], v[222:225], v[108:111]
	v_mfma_f32_16x16x32_bf16 v[80:83], v[136:139], v[230:233], v[80:83]
	v_mfma_f32_16x16x32_bf16 v[76:79], v[144:147], v[230:233], v[76:79]
	v_mfma_f32_16x16x32_bf16 v[120:123], v[148:151], v[164:167], v[120:123]
	v_mfma_f32_16x16x32_bf16 v[116:119], v[156:159], v[164:167], v[116:119]
	v_mfma_f32_16x16x32_bf16 v[92:95], v[148:151], v[210:213], v[92:95]
	v_mfma_f32_16x16x32_bf16 v[88:91], v[156:159], v[210:213], v[88:91]
	v_mfma_f32_16x16x32_bf16 v[104:107], v[148:151], v[218:221], v[104:107]
	v_mfma_f32_16x16x32_bf16 v[84:87], v[156:159], v[218:221], v[84:87]
	v_mfma_f32_16x16x32_bf16 v[72:75], v[148:151], v[226:229], v[72:75]
	v_mfma_f32_16x16x32_bf16 v[68:71], v[156:159], v[226:229], v[68:71]
	s_setprio 3
	s_barrier
; #define PG8_STAGE(bufoff, gbase, voff) do { _Pragma("unroll") for (int _i = 0; _i < 2; ++_i) \
;         __builtin_amdgcn_global_load_lds((const unsigned*)((const char*)(gbase) + (voff)[_i]), (PG8_LAS unsigned*)(lds + (bufoff) + ldsw + _i * 8192), 16, 0, 0); } while (0)
; #define PG8_LDA(dst, b, h) do { _Pragma("unroll") for (int m = 0; m < 4; ++m) _Pragma("unroll") for (int k = 0; k < 2; ++k) dst[m][k] = *(const PG8_LAS bf16x8*)(lds + PG8_SA(b, h) + aoff + m * 2048 + k * 1024); } while (0)
; #define PG8_LDB(dst, b, h) do { _Pragma("unroll") for (int n = 0; n < 2; ++n) _Pragma("unroll") for (int k = 0; k < 2; ++k) dst[n][k] = *(const PG8_LAS bf16x8*)(lds + PG8_SB(b, h) + boff + n * 2048 + k * 1024); } while (0)
; #define PG8_MMA(ai, bj, At, Bt) do { __builtin_amdgcn_s_setprio(3); _Pragma("unroll") for (int m = 0; m < 4; ++m) _Pragma("unroll") for (int n = 0; n < 2; ++n) _Pragma("unroll") for (int k = 0; k < 2; ++k) \
;         acc[ai][bj][m][n] = __builtin_amdgcn_mfma_f32_16x16x32_bf16(Bt[n][k], At[m][k], acc[ai][bj][m][n], 0, 0, 0); __builtin_amdgcn_s_setprio(0); } while (0)
; #define PG8_WAIT_V(n) asm volatile("s_waitcnt vmcnt(" #n ")" ::: "memory")
; #define PG8_WAIT_L(n) asm volatile("s_waitcnt lgkmcnt(" #n ")" ::: "memory")
; #define PG8_BAR __builtin_amdgcn_s_barrier()
; #define PG8_SCHED __builtin_amdgcn_sched_barrier(0)
; template <class Epi, class Sched, bool ALIGN_EPI = false, bool SP2 = false>
; __device__ __forceinline__ void gemm_phase(PG8_LAS unsigned char* lds, const Gemm g, const Sched& S, const Epi& E) {
;     ...
;             PG8_LDB(B0, 1, 0); PG8_LDB(B1, 1, 1); PG8_SCHED; PG8_LDA(At, 1, 0); PG8_STAGE(PG8_SA(0, 1), a2 + hstepA, voffA);
;             PG8_WAIT_V(8); PG8_WAIT_L(0); PG8_BAR; PG8_MMA(0, 0, At, B0); PG8_MMA(0, 1, At, B1); PG8_BAR; PG8_SCHED;
;             PG8_LDA(At, 1, 1); PG8_STAGE(PG8_SB(1, 0), b3, voffB); PG8_STAGE(PG8_SB(1, 1), b3 + hstepB, voffB); PG8_STAGE(PG8_SA(1, 0), a3, voffA);
;             PG8_WAIT_V(8); PG8_WAIT_L(0); PG8_BAR; PG8_MMA(1, 0, At, B0); PG8_MMA(1, 1, At, B1); PG8_BAR; PG8_SCHED;
	v_mfma_f32_16x16x32_bf16 v[120:123], v[152:155], v[168:171], v[120:123]
	v_mfma_f32_16x16x32_bf16 v[116:119], v[160:163], v[168:171], v[116:119]
	v_mfma_f32_16x16x32_bf16 v[92:95], v[152:155], v[214:217], v[92:95]
	v_mfma_f32_16x16x32_bf16 v[88:91], v[160:163], v[214:217], v[88:91]
	v_mfma_f32_16x16x32_bf16 v[104:107], v[152:155], v[222:225], v[104:107]
	v_mfma_f32_16x16x32_bf16 v[84:87], v[160:163], v[222:225], v[84:87]
	v_mfma_f32_16x16x32_bf16 v[72:75], v[152:155], v[230:233], v[72:75]
	v_mfma_f32_16x16x32_bf16 v[68:71], v[160:163], v[230:233], v[68:71]
	s_setprio 0
	s_mov_b32 m0, s77
	v_lshl_add_u64 v[234:235], v[234:235], 0, s[4:5]
	s_add_u32 s28, s28, 0x2b0080
	ds_read_b128 v[164:167], v207 offset:49152
	ds_read_b128 v[168:171], v207 offset:50176
	ds_read_b128 v[210:213], v207 offset:51200
	ds_read_b128 v[214:217], v207 offset:52224
	ds_read_b128 v[218:221], v207 offset:53248
	ds_read_b128 v[222:225], v207 offset:54272
	ds_read_b128 v[226:229], v207 offset:55296
	ds_read_b128 v[230:233], v207 offset:56320
	global_load_lds_dwordx4 v[234:235], off
	v_lshl_add_u64 v[234:235], v[236:237], 0, s[4:5]
	s_mov_b32 m0, s78
	s_addc_u32 s29, s29, 0
	global_load_lds_dwordx4 v[234:235], off
	v_lshl_add_u64 v[234:235], s[28:29], 0, v[174:175]
	s_mov_b32 m0, s79
	s_nop 0
	global_load_lds_dwordx4 v[234:235], off
	v_lshl_add_u64 v[234:235], s[28:29], 0, v[178:179]
	s_mov_b32 m0, s80
	s_nop 0
	global_load_lds_dwordx4 v[234:235], off
	v_lshl_add_u64 v[234:235], v[238:239], 0, s[4:5]
	s_mov_b32 m0, s57
	s_nop 0
	global_load_lds_dwordx4 v[234:235], off
	v_lshl_add_u64 v[234:235], v[240:241], 0, s[4:5]
	s_mov_b32 m0, s58
	s_nop 0
	global_load_lds_dwordx4 v[234:235], off
	s_waitcnt vmcnt(8)
	s_waitcnt lgkmcnt(0)
	s_barrier
	s_setprio 2
	s_waitcnt lgkmcnt(0)
	v_mfma_f32_16x16x32_bf16 v[64:67], v[132:135], v[164:167], v[64:67]
	v_mfma_f32_16x16x32_bf16 v[60:63], v[140:143], v[164:167], v[60:63]
	v_mfma_f32_16x16x32_bf16 v[48:51], v[132:135], v[210:213], v[48:51]
	v_mfma_f32_16x16x32_bf16 v[44:47], v[140:143], v[210:213], v[44:47]
	v_mfma_f32_16x16x32_bf16 v[32:35], v[132:135], v[218:221], v[32:35]
	v_mfma_f32_16x16x32_bf16 v[28:31], v[140:143], v[218:221], v[28:31]
	v_mfma_f32_16x16x32_bf16 v[16:19], v[132:135], v[226:229], v[16:19]
	v_mfma_f32_16x16x32_bf16 v[12:15], v[140:143], v[226:229], v[12:15]
	v_mfma_f32_16x16x32_bf16 v[64:67], v[136:139], v[168:171], v[64:67]
	v_mfma_f32_16x16x32_bf16 v[60:63], v[144:147], v[168:171], v[60:63]
	v_mfma_f32_16x16x32_bf16 v[48:51], v[136:139], v[214:217], v[48:51]
	v_mfma_f32_16x16x32_bf16 v[44:47], v[144:147], v[214:217], v[44:47]
	v_mfma_f32_16x16x32_bf16 v[32:35], v[136:139], v[222:225], v[32:35]
	v_mfma_f32_16x16x32_bf16 v[28:31], v[144:147], v[222:225], v[28:31]
	v_mfma_f32_16x16x32_bf16 v[16:19], v[136:139], v[230:233], v[16:19]
	v_mfma_f32_16x16x32_bf16 v[12:15], v[144:147], v[230:233], v[12:15]
	v_mfma_f32_16x16x32_bf16 v[56:59], v[148:151], v[164:167], v[56:59]
	v_mfma_f32_16x16x32_bf16 v[52:55], v[156:159], v[164:167], v[52:55]
	v_mfma_f32_16x16x32_bf16 v[40:43], v[148:151], v[210:213], v[40:43]
	v_mfma_f32_16x16x32_bf16 v[36:39], v[156:159], v[210:213], v[36:39]
	v_mfma_f32_16x16x32_bf16 v[24:27], v[148:151], v[218:221], v[24:27]
	v_mfma_f32_16x16x32_bf16 v[20:23], v[156:159], v[218:221], v[20:23]
	v_mfma_f32_16x16x32_bf16 v[8:11], v[148:151], v[226:229], v[8:11]
	v_mfma_f32_16x16x32_bf16 v[4:7], v[156:159], v[226:229], v[4:7]
	s_setprio 3
	s_barrier
	v_mfma_f32_16x16x32_bf16 v[56:59], v[152:155], v[168:171], v[56:59]
	v_mfma_f32_16x16x32_bf16 v[52:55], v[160:163], v[168:171], v[52:55]
	v_mfma_f32_16x16x32_bf16 v[40:43], v[152:155], v[214:217], v[40:43]
	v_mfma_f32_16x16x32_bf16 v[36:39], v[160:163], v[214:217], v[36:39]
	v_mfma_f32_16x16x32_bf16 v[24:27], v[152:155], v[222:225], v[24:27]
	v_mfma_f32_16x16x32_bf16 v[20:23], v[160:163], v[222:225], v[20:23]
	v_mfma_f32_16x16x32_bf16 v[8:11], v[152:155], v[230:233], v[8:11]
	v_mfma_f32_16x16x32_bf16 v[4:7], v[160:163], v[230:233], v[4:7]
	s_setprio 0
	s_add_i32 s61, s61, 2
	s_add_u32 s12, s12, 0x100
	s_addc_u32 s13, s13, 0
	s_cmpk_gt_u32 s61, 0xa9
	s_cbranch_scc1 .LBB0_978

; #define PG8_STAGE(bufoff, gbase, voff) do { _Pragma("unroll") for (int _i = 0; _i < 2; ++_i) \
;         __builtin_amdgcn_global_load_lds((const unsigned*)((const char*)(gbase) + (voff)[_i]), (PG8_LAS unsigned*)(lds + (bufoff) + ldsw + _i * 8192), 16, 0, 0); } while (0)
; #define PG8_LDA(dst, b, h) do { _Pragma("unroll") for (int m = 0; m < 4; ++m) _Pragma("unroll") for (int k = 0; k < 2; ++k) dst[m][k] = *(const PG8_LAS bf16x8*)(lds + PG8_SA(b, h) + aoff + m * 2048 + k * 1024); } while (0)
; #define PG8_LDB(dst, b, h) do { _Pragma("unroll") for (int n = 0; n < 2; ++n) _Pragma("unroll") for (int k = 0; k < 2; ++k) dst[n][k] = *(const PG8_LAS bf16x8*)(lds + PG8_SB(b, h) + boff + n * 2048 + k * 1024); } while (0)
; #define PG8_MMA(ai, bj, At, Bt) do { __builtin_amdgcn_s_setprio(3); _Pragma("unroll") for (int m = 0; m < 4; ++m) _Pragma("unroll") for (int n = 0; n < 2; ++n) _Pragma("unroll") for (int k = 0; k < 2; ++k) \
;         acc[ai][bj][m][n] = __builtin_amdgcn_mfma_f32_16x16x32_bf16(Bt[n][k], At[m][k], acc[ai][bj][m][n], 0, 0, 0); __builtin_amdgcn_s_setprio(0); } while (0)
; #define PG8_WAIT_V(n) asm volatile("s_waitcnt vmcnt(" #n ")" ::: "memory")
; template <class Epi, class Sched, bool ALIGN_EPI = false, bool SP2 = false>
; __device__ __forceinline__ void gemm_phase(PG8_LAS unsigned char* lds, const Gemm g, const Sched& S, const Epi& E) {
;     ...
;             PG8_LDB(B0, 0, 0); PG8_LDB(B1, 0, 1); PG8_SCHED; PG8_LDA(At, 0, 0); PG8_STAGE(PG8_SA(1, 1), a1 + hstepA, voffA);
;             PG8_WAIT_V(8); PG8_WAIT_L(0); PG8_BAR; PG8_MMA(0, 0, At, B0); PG8_MMA(0, 1, At, B1); PG8_BAR; PG8_SCHED;
;             PG8_LDA(At, 0, 1); PG8_STAGE(PG8_SB(0, 0), b2, voffB); PG8_STAGE(PG8_SB(0, 1), b2 + hstepB, voffB); PG8_STAGE(PG8_SA(0, 0), a2, voffA);
;             PG8_WAIT_V(8); PG8_WAIT_L(0); PG8_BAR; PG8_MMA(1, 0, At, B0); PG8_MMA(1, 1, At, B1); PG8_BAR; PG8_SCHED;
;             PG8_LDB(B0, 1, 0); PG8_LDB(B1, 1, 1); PG8_SCHED; PG8_LDA(At, 1, 0); PG8_STAGE(PG8_SA(0, 1), a2 + hstepA, voffA);
;             PG8_WAIT_V(8); PG8_WAIT_L(0); PG8_BAR; PG8_MMA(0, 0, At, B0); PG8_MMA(0, 1, At, B1); PG8_BAR; PG8_SCHED;
;             PG8_LDA(At, 1, 1); PG8_STAGE(PG8_SB(1, 0), b3, voffB); PG8_STAGE(PG8_SB(1, 1), b3 + hstepB, voffB); PG8_STAGE(PG8_SA(1, 0), a3, voffA);
;             PG8_WAIT_V(8); PG8_WAIT_L(0); PG8_BAR; PG8_MMA(1, 0, At, B0); PG8_MMA(1, 1, At, B1); PG8_BAR; PG8_SCHED;
.LBB0_1018:
	v_add_u32_e32 v142, s46, v189
	v_add_u32_e32 v158, s47, v189
	s_add_u32 s40, s20, s22
	ds_read_b128 v[130:133], v142
	ds_read_b128 v[134:137], v142 offset:1024
	ds_read_b128 v[138:141], v142 offset:2048
	ds_read_b128 v[142:145], v142 offset:3072
	ds_read_b128 v[146:149], v158
	ds_read_b128 v[150:153], v158 offset:1024
	ds_read_b128 v[154:157], v158 offset:2048
	ds_read_b128 v[158:161], v158 offset:3072
	s_addc_u32 s41, s21, s23
	s_add_u32 s40, s40, 0x21500100
	s_addc_u32 s41, s41, 0
	s_add_u32 s87, s44, s22
	s_addc_u32 s88, s45, s23
	s_cmpk_eq_i32 s22, 0x5500
	s_cselect_b32 s43, s17, s41
	s_cselect_b32 s42, s16, s40
	s_cselect_b32 s41, s11, s88
	s_cselect_b32 s40, s10, s87
	s_mov_b32 m0, s77
	v_lshl_add_u64 v[186:187], v[0:1], 0, s[22:23]
	ds_read_b128 v[162:165], v180
	ds_read_b128 v[166:169], v180 offset:1024
	ds_read_b128 v[182:185], v180 offset:2048
	ds_read_b128 v[190:193], v180 offset:3072
	ds_read_b128 v[194:197], v180 offset:4096
	ds_read_b128 v[208:211], v180 offset:5120
	ds_read_b128 v[212:215], v180 offset:6144
	ds_read_b128 v[216:219], v180 offset:7168
	global_load_lds_dwordx4 v[186:187], off
	v_lshl_add_u64 v[186:187], v[170:171], 0, s[22:23]
	s_mov_b32 m0, s78
	s_nop 0
	global_load_lds_dwordx4 v[186:187], off
	s_waitcnt vmcnt(8)
	s_waitcnt lgkmcnt(0)
	s_barrier
	s_setprio 2
	s_waitcnt lgkmcnt(0)
	v_mfma_f32_16x16x32_bf16 v[126:129], v[130:133], v[162:165], v[126:129]
	v_mfma_f32_16x16x32_bf16 v[122:125], v[138:141], v[162:165], v[122:125]
	v_mfma_f32_16x16x32_bf16 v[98:101], v[130:133], v[182:185], v[98:101]
	v_mfma_f32_16x16x32_bf16 v[94:97], v[138:141], v[182:185], v[94:97]
	v_mfma_f32_16x16x32_bf16 v[110:113], v[130:133], v[194:197], v[110:113]
	v_mfma_f32_16x16x32_bf16 v[106:109], v[138:141], v[194:197], v[106:109]
	v_mfma_f32_16x16x32_bf16 v[78:81], v[130:133], v[212:215], v[78:81]
	v_mfma_f32_16x16x32_bf16 v[74:77], v[138:141], v[212:215], v[74:77]
	v_mfma_f32_16x16x32_bf16 v[126:129], v[134:137], v[166:169], v[126:129]
	v_mfma_f32_16x16x32_bf16 v[122:125], v[142:145], v[166:169], v[122:125]
	v_mfma_f32_16x16x32_bf16 v[98:101], v[134:137], v[190:193], v[98:101]
	v_mfma_f32_16x16x32_bf16 v[94:97], v[142:145], v[190:193], v[94:97]
	v_mfma_f32_16x16x32_bf16 v[110:113], v[134:137], v[208:211], v[110:113]
	v_mfma_f32_16x16x32_bf16 v[106:109], v[142:145], v[208:211], v[106:109]
	v_mfma_f32_16x16x32_bf16 v[78:81], v[134:137], v[216:219], v[78:81]
	v_mfma_f32_16x16x32_bf16 v[74:77], v[142:145], v[216:219], v[74:77]
	v_mfma_f32_16x16x32_bf16 v[118:121], v[146:149], v[162:165], v[118:121]
	v_mfma_f32_16x16x32_bf16 v[114:117], v[154:157], v[162:165], v[114:117]
	v_mfma_f32_16x16x32_bf16 v[90:93], v[146:149], v[182:185], v[90:93]
	v_mfma_f32_16x16x32_bf16 v[86:89], v[154:157], v[182:185], v[86:89]
	v_mfma_f32_16x16x32_bf16 v[102:105], v[146:149], v[194:197], v[102:105]
	v_mfma_f32_16x16x32_bf16 v[82:85], v[154:157], v[194:197], v[82:85]
	v_mfma_f32_16x16x32_bf16 v[70:73], v[146:149], v[212:215], v[70:73]
	v_mfma_f32_16x16x32_bf16 v[66:69], v[154:157], v[212:215], v[66:69]
	s_setprio 3
	s_barrier
	v_mfma_f32_16x16x32_bf16 v[118:121], v[150:153], v[166:169], v[118:121]
	v_mfma_f32_16x16x32_bf16 v[114:117], v[158:161], v[166:169], v[114:117]
	v_mfma_f32_16x16x32_bf16 v[90:93], v[150:153], v[190:193], v[90:93]
	v_mfma_f32_16x16x32_bf16 v[86:89], v[158:161], v[190:193], v[86:89]
	v_mfma_f32_16x16x32_bf16 v[102:105], v[150:153], v[208:211], v[102:105]
	v_mfma_f32_16x16x32_bf16 v[82:85], v[158:161], v[208:211], v[82:85]
	v_mfma_f32_16x16x32_bf16 v[70:73], v[150:153], v[216:219], v[70:73]
	v_mfma_f32_16x16x32_bf16 v[66:69], v[158:161], v[216:219], v[66:69]
	s_setprio 0
	s_mov_b32 m0, s79
	v_lshl_add_u64 v[186:187], s[40:41], 0, v[174:175]
	s_add_u32 s88, s40, 0x2b0000
	ds_read_b128 v[162:165], v180 offset:16384
	ds_read_b128 v[166:169], v180 offset:17408
	ds_read_b128 v[182:185], v180 offset:18432
	ds_read_b128 v[190:193], v180 offset:19456
	ds_read_b128 v[194:197], v180 offset:20480
	ds_read_b128 v[208:211], v180 offset:21504
	ds_read_b128 v[212:215], v180 offset:22528
	ds_read_b128 v[216:219], v180 offset:23552
	global_load_lds_dwordx4 v[186:187], off
	v_lshl_add_u64 v[198:199], s[40:41], 0, v[178:179]
	s_mov_b32 m0, s80
	s_addc_u32 s89, s41, 0
	global_load_lds_dwordx4 v[198:199], off
	v_lshl_add_u64 v[204:205], s[88:89], 0, v[174:175]
	s_mov_b32 m0, s81
	v_lshl_add_u64 v[220:221], s[42:43], 0, v[176:177]
	global_load_lds_dwordx4 v[204:205], off
	v_lshl_add_u64 v[204:205], s[88:89], 0, v[178:179]
	s_mov_b32 m0, s82
	s_nop 0
	global_load_lds_dwordx4 v[204:205], off
	v_lshl_add_u64 v[204:205], s[42:43], 0, v[172:173]
	s_mov_b32 m0, s58
	s_nop 0
	global_load_lds_dwordx4 v[204:205], off
	s_mov_b32 m0, s60
	s_nop 0
	global_load_lds_dwordx4 v[220:221], off
	s_waitcnt vmcnt(8)
	s_waitcnt lgkmcnt(0)
	s_barrier
; #define PG8_STAGE(bufoff, gbase, voff) do { _Pragma("unroll") for (int _i = 0; _i < 2; ++_i) \
;         __builtin_amdgcn_global_load_lds((const unsigned*)((const char*)(gbase) + (voff)[_i]), (PG8_LAS unsigned*)(lds + (bufoff) + ldsw + _i * 8192), 16, 0, 0); } while (0)
; #define PG8_LDA(dst, b, h) do { _Pragma("unroll") for (int m = 0; m < 4; ++m) _Pragma("unroll") for (int k = 0; k < 2; ++k) dst[m][k] = *(const PG8_LAS bf16x8*)(lds + PG8_SA(b, h) + aoff + m * 2048 + k * 1024); } while (0)
; #define PG8_LDB(dst, b, h) do { _Pragma("unroll") for (int n = 0; n < 2; ++n) _Pragma("unroll") for (int k = 0; k < 2; ++k) dst[n][k] = *(const PG8_LAS bf16x8*)(lds + PG8_SB(b, h) + boff + n * 2048 + k * 1024); } while (0)
; #define PG8_MMA(ai, bj, At, Bt) do { __builtin_amdgcn_s_setprio(3); _Pragma("unroll") for (int m = 0; m < 4; ++m) _Pragma("unroll") for (int n = 0; n < 2; ++n) _Pragma("unroll") for (int k = 0; k < 2; ++k) \
;         acc[ai][bj][m][n] = __builtin_amdgcn_mfma_f32_16x16x32_bf16(Bt[n][k], At[m][k], acc[ai][bj][m][n], 0, 0, 0); __builtin_amdgcn_s_setprio(0); } while (0)
; #define PG8_WAIT_V(n) asm volatile("s_waitcnt vmcnt(" #n ")" ::: "memory")
; template <class Epi, class Sched, bool ALIGN_EPI = false, bool SP2 = false>
; __device__ __forceinline__ void gemm_phase(PG8_LAS unsigned char* lds, const Gemm g, const Sched& S, const Epi& E) {
;     ...
;             PG8_LDB(B0, 0, 0); PG8_LDB(B1, 0, 1); PG8_SCHED; PG8_LDA(At, 0, 0); PG8_STAGE(PG8_SA(1, 1), a1 + hstepA, voffA);
;             PG8_WAIT_V(8); PG8_WAIT_L(0); PG8_BAR; PG8_MMA(0, 0, At, B0); PG8_MMA(0, 1, At, B1); PG8_BAR; PG8_SCHED;
;             PG8_LDA(At, 0, 1); PG8_STAGE(PG8_SB(0, 0), b2, voffB); PG8_STAGE(PG8_SB(0, 1), b2 + hstepB, voffB); PG8_STAGE(PG8_SA(0, 0), a2, voffA);
;             PG8_WAIT_V(8); PG8_WAIT_L(0); PG8_BAR; PG8_MMA(1, 0, At, B0); PG8_MMA(1, 1, At, B1); PG8_BAR; PG8_SCHED;
;             PG8_LDB(B0, 1, 0); PG8_LDB(B1, 1, 1); PG8_SCHED; PG8_LDA(At, 1, 0); PG8_STAGE(PG8_SA(0, 1), a2 + hstepA, voffA);
;             PG8_WAIT_V(8); PG8_WAIT_L(0); PG8_BAR; PG8_MMA(0, 0, At, B0); PG8_MMA(0, 1, At, B1); PG8_BAR; PG8_SCHED;
;             PG8_LDA(At, 1, 1); PG8_STAGE(PG8_SB(1, 0), b3, voffB); PG8_STAGE(PG8_SB(1, 1), b3 + hstepB, voffB); PG8_STAGE(PG8_SA(1, 0), a3, voffA);
;             PG8_WAIT_V(8); PG8_WAIT_L(0); PG8_BAR; PG8_MMA(1, 0, At, B0); PG8_MMA(1, 1, At, B1); PG8_BAR; PG8_SCHED;
	s_setprio 2
	s_waitcnt lgkmcnt(0)
	v_mfma_f32_16x16x32_bf16 v[62:65], v[130:133], v[162:165], v[62:65]
	v_mfma_f32_16x16x32_bf16 v[58:61], v[138:141], v[162:165], v[58:61]
	v_mfma_f32_16x16x32_bf16 v[46:49], v[130:133], v[182:185], v[46:49]
	v_mfma_f32_16x16x32_bf16 v[42:45], v[138:141], v[182:185], v[42:45]
	v_mfma_f32_16x16x32_bf16 v[30:33], v[130:133], v[194:197], v[30:33]
	v_mfma_f32_16x16x32_bf16 v[26:29], v[138:141], v[194:197], v[26:29]
	v_mfma_f32_16x16x32_bf16 v[14:17], v[130:133], v[212:215], v[14:17]
	v_mfma_f32_16x16x32_bf16 v[10:13], v[138:141], v[212:215], v[10:13]
	v_mfma_f32_16x16x32_bf16 v[62:65], v[134:137], v[166:169], v[62:65]
	v_mfma_f32_16x16x32_bf16 v[58:61], v[142:145], v[166:169], v[58:61]
	v_mfma_f32_16x16x32_bf16 v[46:49], v[134:137], v[190:193], v[46:49]
	v_mfma_f32_16x16x32_bf16 v[42:45], v[142:145], v[190:193], v[42:45]
	v_mfma_f32_16x16x32_bf16 v[30:33], v[134:137], v[208:211], v[30:33]
	v_mfma_f32_16x16x32_bf16 v[26:29], v[142:145], v[208:211], v[26:29]
	v_mfma_f32_16x16x32_bf16 v[14:17], v[134:137], v[216:219], v[14:17]
	v_mfma_f32_16x16x32_bf16 v[10:13], v[142:145], v[216:219], v[10:13]
	v_mfma_f32_16x16x32_bf16 v[54:57], v[146:149], v[162:165], v[54:57]
	v_mfma_f32_16x16x32_bf16 v[50:53], v[154:157], v[162:165], v[50:53]
	v_mfma_f32_16x16x32_bf16 v[38:41], v[146:149], v[182:185], v[38:41]
	v_mfma_f32_16x16x32_bf16 v[34:37], v[154:157], v[182:185], v[34:37]
	v_mfma_f32_16x16x32_bf16 v[22:25], v[146:149], v[194:197], v[22:25]
	v_mfma_f32_16x16x32_bf16 v[18:21], v[154:157], v[194:197], v[18:21]
	v_mfma_f32_16x16x32_bf16 v[6:9], v[146:149], v[212:215], v[6:9]
	v_mfma_f32_16x16x32_bf16 v[2:5], v[154:157], v[212:215], v[2:5]
	s_setprio 3
	s_barrier
	v_mfma_f32_16x16x32_bf16 v[54:57], v[150:153], v[166:169], v[54:57]
	v_mfma_f32_16x16x32_bf16 v[50:53], v[158:161], v[166:169], v[50:53]
	v_mfma_f32_16x16x32_bf16 v[38:41], v[150:153], v[190:193], v[38:41]
	v_mfma_f32_16x16x32_bf16 v[34:37], v[158:161], v[190:193], v[34:37]
	v_mfma_f32_16x16x32_bf16 v[22:25], v[150:153], v[208:211], v[22:25]
	v_mfma_f32_16x16x32_bf16 v[18:21], v[158:161], v[208:211], v[18:21]
	v_mfma_f32_16x16x32_bf16 v[6:9], v[150:153], v[216:219], v[6:9]
	v_mfma_f32_16x16x32_bf16 v[2:5], v[158:161], v[216:219], v[2:5]
	s_setprio 0
	v_add_u32_e32 v142, s52, v189
	v_add_u32_e32 v158, s53, v189
	ds_read_b128 v[130:133], v142
	ds_read_b128 v[134:137], v142 offset:1024
	ds_read_b128 v[138:141], v142 offset:2048
	ds_read_b128 v[142:145], v142 offset:3072
	ds_read_b128 v[146:149], v158
	ds_read_b128 v[150:153], v158 offset:1024
	ds_read_b128 v[154:157], v158 offset:2048
	ds_read_b128 v[158:161], v158 offset:3072
	s_add_u32 s42, s42, 0x2b0000
	s_addc_u32 s43, s43, 0
	s_mov_b32 m0, s61
	v_lshl_add_u64 v[222:223], s[42:43], 0, v[172:173]
	ds_read_b128 v[162:165], v180 offset:32768
	ds_read_b128 v[166:169], v180 offset:33792
	ds_read_b128 v[182:185], v180 offset:34816
	ds_read_b128 v[190:193], v180 offset:35840
	ds_read_b128 v[194:197], v180 offset:36864
	ds_read_b128 v[208:211], v180 offset:37888
	ds_read_b128 v[212:215], v180 offset:38912
	ds_read_b128 v[216:219], v180 offset:39936
	global_load_lds_dwordx4 v[222:223], off
	v_lshl_add_u64 v[222:223], s[42:43], 0, v[176:177]
	s_mov_b32 m0, s62
	s_nop 0
	global_load_lds_dwordx4 v[222:223], off
	s_waitcnt vmcnt(8)
	s_waitcnt lgkmcnt(0)
	s_barrier
	s_setprio 2
	s_waitcnt lgkmcnt(0)
	v_mfma_f32_16x16x32_bf16 v[126:129], v[130:133], v[162:165], v[126:129]
	v_mfma_f32_16x16x32_bf16 v[122:125], v[138:141], v[162:165], v[122:125]
	v_mfma_f32_16x16x32_bf16 v[98:101], v[130:133], v[182:185], v[98:101]
	v_mfma_f32_16x16x32_bf16 v[94:97], v[138:141], v[182:185], v[94:97]
	v_mfma_f32_16x16x32_bf16 v[110:113], v[130:133], v[194:197], v[110:113]
	v_mfma_f32_16x16x32_bf16 v[106:109], v[138:141], v[194:197], v[106:109]
	v_mfma_f32_16x16x32_bf16 v[78:81], v[130:133], v[212:215], v[78:81]
	v_mfma_f32_16x16x32_bf16 v[74:77], v[138:141], v[212:215], v[74:77]
	v_mfma_f32_16x16x32_bf16 v[126:129], v[134:137], v[166:169], v[126:129]
	v_mfma_f32_16x16x32_bf16 v[122:125], v[142:145], v[166:169], v[122:125]
	v_mfma_f32_16x16x32_bf16 v[98:101], v[134:137], v[190:193], v[98:101]
	v_mfma_f32_16x16x32_bf16 v[94:97], v[142:145], v[190:193], v[94:97]
	v_mfma_f32_16x16x32_bf16 v[110:113], v[134:137], v[208:211], v[110:113]
	v_mfma_f32_16x16x32_bf16 v[106:109], v[142:145], v[208:211], v[106:109]
	v_mfma_f32_16x16x32_bf16 v[78:81], v[134:137], v[216:219], v[78:81]
	v_mfma_f32_16x16x32_bf16 v[74:77], v[142:145], v[216:219], v[74:77]
	v_mfma_f32_16x16x32_bf16 v[118:121], v[146:149], v[162:165], v[118:121]
	v_mfma_f32_16x16x32_bf16 v[114:117], v[154:157], v[162:165], v[114:117]
	v_mfma_f32_16x16x32_bf16 v[90:93], v[146:149], v[182:185], v[90:93]
	v_mfma_f32_16x16x32_bf16 v[86:89], v[154:157], v[182:185], v[86:89]
	v_mfma_f32_16x16x32_bf16 v[102:105], v[146:149], v[194:197], v[102:105]
	v_mfma_f32_16x16x32_bf16 v[82:85], v[154:157], v[194:197], v[82:85]
	v_mfma_f32_16x16x32_bf16 v[70:73], v[146:149], v[212:215], v[70:73]
	v_mfma_f32_16x16x32_bf16 v[66:69], v[154:157], v[212:215], v[66:69]
	s_setprio 3
	s_barrier
; #define PG8_STAGE(bufoff, gbase, voff) do { _Pragma("unroll") for (int _i = 0; _i < 2; ++_i) \
;         __builtin_amdgcn_global_load_lds((const unsigned*)((const char*)(gbase) + (voff)[_i]), (PG8_LAS unsigned*)(lds + (bufoff) + ldsw + _i * 8192), 16, 0, 0); } while (0)
; #define PG8_LDA(dst, b, h) do { _Pragma("unroll") for (int m = 0; m < 4; ++m) _Pragma("unroll") for (int k = 0; k < 2; ++k) dst[m][k] = *(const PG8_LAS bf16x8*)(lds + PG8_SA(b, h) + aoff + m * 2048 + k * 1024); } while (0)
; #define PG8_LDB(dst, b, h) do { _Pragma("unroll") for (int n = 0; n < 2; ++n) _Pragma("unroll") for (int k = 0; k < 2; ++k) dst[n][k] = *(const PG8_LAS bf16x8*)(lds + PG8_SB(b, h) + boff + n * 2048 + k * 1024); } while (0)
; #define PG8_MMA(ai, bj, At, Bt) do { __builtin_amdgcn_s_setprio(3); _Pragma("unroll") for (int m = 0; m < 4; ++m) _Pragma("unroll") for (int n = 0; n < 2; ++n) _Pragma("unroll") for (int k = 0; k < 2; ++k) \
;         acc[ai][bj][m][n] = __builtin_amdgcn_mfma_f32_16x16x32_bf16(Bt[n][k], At[m][k], acc[ai][bj][m][n], 0, 0, 0); __builtin_amdgcn_s_setprio(0); } while (0)
; #define PG8_WAIT_V(n) asm volatile("s_waitcnt vmcnt(" #n ")" ::: "memory")
; #define PG8_WAIT_L(n) asm volatile("s_waitcnt lgkmcnt(" #n ")" ::: "memory")
; #define PG8_BAR __builtin_amdgcn_s_barrier()
; #define PG8_SCHED __builtin_amdgcn_sched_barrier(0)
; template <class Epi, class Sched, bool ALIGN_EPI = false, bool SP2 = false>
; __device__ __forceinline__ void gemm_phase(PG8_LAS unsigned char* lds, const Gemm g, const Sched& S, const Epi& E) {
;     ...
;             PG8_LDB(B0, 1, 0); PG8_LDB(B1, 1, 1); PG8_SCHED; PG8_LDA(At, 1, 0); PG8_STAGE(PG8_SA(0, 1), a2 + hstepA, voffA);
;             PG8_WAIT_V(8); PG8_WAIT_L(0); PG8_BAR; PG8_MMA(0, 0, At, B0); PG8_MMA(0, 1, At, B1); PG8_BAR; PG8_SCHED;
;             PG8_LDA(At, 1, 1); PG8_STAGE(PG8_SB(1, 0), b3, voffB); PG8_STAGE(PG8_SB(1, 1), b3 + hstepB, voffB); PG8_STAGE(PG8_SA(1, 0), a3, voffA);
;             PG8_WAIT_V(8); PG8_WAIT_L(0); PG8_BAR; PG8_MMA(1, 0, At, B0); PG8_MMA(1, 1, At, B1); PG8_BAR; PG8_SCHED;
	v_mfma_f32_16x16x32_bf16 v[118:121], v[150:153], v[166:169], v[118:121]
	v_mfma_f32_16x16x32_bf16 v[114:117], v[158:161], v[166:169], v[114:117]
	v_mfma_f32_16x16x32_bf16 v[90:93], v[150:153], v[190:193], v[90:93]
	v_mfma_f32_16x16x32_bf16 v[86:89], v[158:161], v[190:193], v[86:89]
	v_mfma_f32_16x16x32_bf16 v[102:105], v[150:153], v[208:211], v[102:105]
	v_mfma_f32_16x16x32_bf16 v[82:85], v[158:161], v[208:211], v[82:85]
	v_mfma_f32_16x16x32_bf16 v[70:73], v[150:153], v[216:219], v[70:73]
	v_mfma_f32_16x16x32_bf16 v[66:69], v[158:161], v[216:219], v[66:69]
	s_setprio 0
	s_mov_b32 m0, s83
	v_lshl_add_u64 v[186:187], v[186:187], 0, s[18:19]
	s_add_u32 s40, s40, 0x2b0080
	ds_read_b128 v[162:165], v180 offset:49152
	ds_read_b128 v[166:169], v180 offset:50176
	ds_read_b128 v[182:185], v180 offset:51200
	ds_read_b128 v[190:193], v180 offset:52224
	ds_read_b128 v[194:197], v180 offset:53248
	ds_read_b128 v[208:211], v180 offset:54272
	ds_read_b128 v[212:215], v180 offset:55296
	ds_read_b128 v[216:219], v180 offset:56320
	global_load_lds_dwordx4 v[186:187], off
	v_lshl_add_u64 v[186:187], v[198:199], 0, s[18:19]
	s_mov_b32 m0, s84
	s_addc_u32 s41, s41, 0
	global_load_lds_dwordx4 v[186:187], off
	v_lshl_add_u64 v[186:187], s[40:41], 0, v[174:175]
	s_mov_b32 m0, s85
	s_nop 0
	global_load_lds_dwordx4 v[186:187], off
	v_lshl_add_u64 v[186:187], s[40:41], 0, v[178:179]
	s_mov_b32 m0, s86
	s_nop 0
	global_load_lds_dwordx4 v[186:187], off
	v_lshl_add_u64 v[186:187], v[204:205], 0, s[18:19]
	s_mov_b32 m0, s63
	s_nop 0
	global_load_lds_dwordx4 v[186:187], off
	v_lshl_add_u64 v[186:187], v[220:221], 0, s[18:19]
	s_mov_b32 m0, s64
	s_nop 0
	global_load_lds_dwordx4 v[186:187], off
	s_waitcnt vmcnt(8)
	s_waitcnt lgkmcnt(0)
	s_barrier
	s_setprio 2
	s_waitcnt lgkmcnt(0)
	v_mfma_f32_16x16x32_bf16 v[62:65], v[130:133], v[162:165], v[62:65]
	v_mfma_f32_16x16x32_bf16 v[58:61], v[138:141], v[162:165], v[58:61]
	v_mfma_f32_16x16x32_bf16 v[46:49], v[130:133], v[182:185], v[46:49]
	v_mfma_f32_16x16x32_bf16 v[42:45], v[138:141], v[182:185], v[42:45]
	v_mfma_f32_16x16x32_bf16 v[30:33], v[130:133], v[194:197], v[30:33]
	v_mfma_f32_16x16x32_bf16 v[26:29], v[138:141], v[194:197], v[26:29]
	v_mfma_f32_16x16x32_bf16 v[14:17], v[130:133], v[212:215], v[14:17]
	v_mfma_f32_16x16x32_bf16 v[10:13], v[138:141], v[212:215], v[10:13]
	v_mfma_f32_16x16x32_bf16 v[62:65], v[134:137], v[166:169], v[62:65]
	v_mfma_f32_16x16x32_bf16 v[58:61], v[142:145], v[166:169], v[58:61]
	v_mfma_f32_16x16x32_bf16 v[46:49], v[134:137], v[190:193], v[46:49]
	v_mfma_f32_16x16x32_bf16 v[42:45], v[142:145], v[190:193], v[42:45]
	v_mfma_f32_16x16x32_bf16 v[30:33], v[134:137], v[208:211], v[30:33]
	v_mfma_f32_16x16x32_bf16 v[26:29], v[142:145], v[208:211], v[26:29]
	v_mfma_f32_16x16x32_bf16 v[14:17], v[134:137], v[216:219], v[14:17]
	v_mfma_f32_16x16x32_bf16 v[10:13], v[142:145], v[216:219], v[10:13]
	v_mfma_f32_16x16x32_bf16 v[54:57], v[146:149], v[162:165], v[54:57]
	v_mfma_f32_16x16x32_bf16 v[50:53], v[154:157], v[162:165], v[50:53]
	v_mfma_f32_16x16x32_bf16 v[38:41], v[146:149], v[182:185], v[38:41]
	v_mfma_f32_16x16x32_bf16 v[34:37], v[154:157], v[182:185], v[34:37]
	v_mfma_f32_16x16x32_bf16 v[22:25], v[146:149], v[194:197], v[22:25]
	v_mfma_f32_16x16x32_bf16 v[18:21], v[154:157], v[194:197], v[18:21]
	v_mfma_f32_16x16x32_bf16 v[6:9], v[146:149], v[212:215], v[6:9]
	v_mfma_f32_16x16x32_bf16 v[2:5], v[154:157], v[212:215], v[2:5]
	s_setprio 3
	s_barrier
	v_mfma_f32_16x16x32_bf16 v[54:57], v[150:153], v[166:169], v[54:57]
	v_mfma_f32_16x16x32_bf16 v[50:53], v[158:161], v[166:169], v[50:53]
	v_mfma_f32_16x16x32_bf16 v[38:41], v[150:153], v[190:193], v[38:41]
	v_mfma_f32_16x16x32_bf16 v[34:37], v[158:161], v[190:193], v[34:37]
	v_mfma_f32_16x16x32_bf16 v[22:25], v[150:153], v[208:211], v[22:25]
	v_mfma_f32_16x16x32_bf16 v[18:21], v[158:161], v[208:211], v[18:21]
	v_mfma_f32_16x16x32_bf16 v[6:9], v[150:153], v[216:219], v[6:9]
	v_mfma_f32_16x16x32_bf16 v[2:5], v[158:161], v[216:219], v[2:5]
	s_setprio 0
	s_add_i32 s67, s67, 2
	s_add_u32 s22, s22, 0x100
	s_addc_u32 s23, s23, 0
	s_cmpk_gt_u32 s67, 0xa9
	s_cbranch_scc1 .LBB0_1021
